# gemm_kloop MB=2 (merge, out): waves 4-7 run the K-loop half a tile behind (last 8 MFMAs of each tile issued after the next barrier), so SIMD partners no longer read LDS in lockstep
# speedup vs baseline: 1.0105x; 1.0105x over previous
; DI void wait_vm0() { asm volatile("s_waitcnt vmcnt(0)" ::: "memory"); }
; DI int otid() { int t = threadIdx.x; asm volatile("" : "+v"(t)); return t; }
; template <int MB, bool SWAP>
; DI void gemm_kloop(f32x16 (&acc)[MB][2], const h16* __restrict__ A, int lda, const h16* __restrict__ B, int ldb, int K, char* lds) {
;     ...
;   const int tid = otid(), w = tid >> 6, lane = tid & 63;
;   const int wr = w >> 2, wc = w & 3;
;   const int lrow = w * 8 + (lane >> 3), pch = lane & 7;
;   const int gch = pch ^ ((lrow >> 1) & 7);
;   const unsigned voa = (unsigned)(lrow * lda + gch * 8) * 2u, vob = (unsigned)(lrow * ldb + gch * 8) * 2u;
;   const int lofs = lrow * 128 + pch * 16;
;   const int r32 = lane & 31, hh = lane >> 5, sw = (r32 >> 1) & 7;
;   const int a_rd = (wr * 32 * MB + r32) * 128;
;   const int b_rd = A_BYTES + (wc * 64 + r32) * 128;
;   const int nk = K >> 6;
;   constexpr int NP = MB + 4;
;   auto piece = [&](int p, int kt, int buf) {
;     char* s = lds + buf * STAGE;
;     if (p < MB) __builtin_amdgcn_global_load_lds((const unsigned*)((const char*)(A + (size_t)p * 64 * lda + kt * 64) + voa), (unsigned*)(s + p * 8192 + lofs), 16, 0, 0);
;     else __builtin_amdgcn_global_load_lds((const unsigned*)((const char*)(B + (size_t)(p - MB) * 64 * ldb + kt * 64) + vob), (unsigned*)(s + A_BYTES + (p - MB) * 8192 + lofs), 16, 0, 0);
;   };
;   wait_vm0();
; #pragma unroll
;   for (int p = 0; p < NP; ++p) piece(p, 0, 0);
; #pragma unroll
;   for (int p = 0; p < NP; ++p) piece(p, 1, 1);
;   int cur = 0;
.LBB0_39:
	v_mov_b32_e32 v5, v208
	s_lshl_b32 vcc_lo, s45, 10
	v_ashrrev_i32_e32 v11, 3, v5
	v_bfe_u32 v12, v5, 3, 3
	v_and_or_b32 v0, v11, -8, v12
	v_lshrrev_b32_e32 v1, 1, v0
	v_xor_b32_e32 v1, v1, v5
	v_lshlrev_b32_e32 v1, 3, v1
	v_mul_lo_u32 v2, v0, s6
	v_and_b32_e32 v13, 56, v1
	v_or_b32_e32 v1, v13, v2
	v_lshlrev_b32_e32 v128, 1, v1
	v_lshlrev_b32_e32 v1, 4, v5
	v_and_b32_e32 v1, 0x70, v1
	v_lshl_or_b32 v8, v0, 7, v1
	v_add_u32_e32 v10, 0, v8
	v_add_u32_e32 v15, 0x2000, v10
	v_readfirstlane_b32 s33, v10
	s_add_i32 s24, s74, vcc_lo
	s_waitcnt vmcnt(0)
	v_lshl_add_u64 v[2:3], s[50:51], 0, v[128:129]
	s_mov_b32 m0, s33
	s_mov_b64 s[52:53], 0x22000
	v_readfirstlane_b32 s33, v15
	s_mul_i32 s84, s24, 0x440
	global_load_lds_dwordx4 v128, s[50:51]
	v_lshl_add_u64 v[6:7], v[2:3], 0, s[52:53]
	s_mov_b32 m0, s33
	s_lshl_b64 s[24:25], s[84:85], 1
	global_load_lds_dwordx4 v[6:7], off
	v_add_u32_e32 v6, 0x4000, v10
	s_add_u32 s24, s96, s24
	v_and_b32_e32 v0, 31, v5
	v_lshrrev_b32_e32 v1, 2, v5
	v_readfirstlane_b32 s33, v6
	s_addc_u32 s25, s97, s25
	v_and_or_b32 v14, v1, s7, v0
	v_lshlrev_b32_e32 v0, 7, v5
	s_mov_b32 m0, s33
	v_add_u32_e32 v15, 0x6000, v10
	v_and_b32_e32 v4, 0x6f80, v0
	v_lshl_add_u64 v[0:1], s[24:25], 0, v[128:129]
	global_load_lds_dwordx4 v128, s[24:25]
	v_readfirstlane_b32 s24, v15
	v_lshl_add_u64 v[6:7], v[0:1], 0, s[52:53]
	s_mov_b32 m0, s24
	s_mov_b64 s[24:25], 0x44000
	v_add_u32_e32 v15, 0x8000, v10
	global_load_lds_dwordx4 v[6:7], off
	v_lshl_add_u64 v[6:7], v[0:1], 0, s[24:25]
	v_readfirstlane_b32 s24, v15
	s_mov_b32 m0, s24
	s_mov_b64 s[24:25], 0x66000
	v_add_u32_e32 v15, 0xa000, v10
	global_load_lds_dwordx4 v[6:7], off
	v_lshl_add_u64 v[6:7], v[0:1], 0, s[24:25]
	v_readfirstlane_b32 s24, v15
	s_mov_b32 m0, s24
	v_lshl_add_u64 v[2:3], v[2:3], 0, s[22:23]
	global_load_lds_dwordx4 v[6:7], off
	v_add_u32_e32 v7, 0xc000, v10
	v_lshrrev_b32_e32 v9, 1, v5
	v_readfirstlane_b32 s24, v7
	s_mov_b32 m0, s24
	v_add_u32_e32 v7, s8, v8
	global_load_lds_dwordx4 v[2:3], off
	v_add_u32_e32 v2, 0xe000, v10
	v_bfe_u32 v15, v5, 5, 1
	v_readfirstlane_b32 s24, v2
	s_mov_b32 m0, s24
	v_readfirstlane_b32 s24, v7
	global_load_lds_dwordx4 v128, s[86:87]
	v_lshl_add_u64 v[2:3], v[0:1], 0, s[22:23]
	s_mov_b32 m0, s24
	s_mov_b64 s[24:25], 0x22080
	v_add_u32_e32 v7, s9, v8
	global_load_lds_dwordx4 v[2:3], off
	v_lshl_add_u64 v[2:3], v[0:1], 0, s[24:25]
	v_readfirstlane_b32 s24, v7
	s_mov_b32 m0, s24
	s_mov_b64 s[24:25], 0x44080
	v_add_u32_e32 v7, s79, v8
	global_load_lds_dwordx4 v[2:3], off
	v_lshl_add_u64 v[2:3], v[0:1], 0, s[24:25]
	v_readfirstlane_b32 s24, v7
	s_mov_b32 m0, s24
	s_mov_b64 s[24:25], 0x66080
	global_load_lds_dwordx4 v[2:3], off
	v_add_u32_e32 v2, s10, v8
	v_lshl_add_u64 v[0:1], v[0:1], 0, s[24:25]
	v_readfirstlane_b32 s24, v2
	s_mov_b32 m0, s24
	v_lshlrev_b32_e32 v6, 7, v14
	global_load_lds_dwordx4 v[0:1], off
	v_bfe_u32 v0, v5, 1, 3
	v_bitop3_b32 v1, v15, v9, 7 bitop3:0x78
	v_lshlrev_b32_e32 v9, 4, v1
	v_bitop3_b32 v1, v15, v0, 2 bitop3:0x36
	v_lshlrev_b32_e32 v8, 4, v1
	v_bitop3_b32 v1, v15, v0, 4 bitop3:0x36
	v_bitop3_b32 v0, v15, v0, 6 bitop3:0x36
	v_lshlrev_b32_e32 v5, 4, v0
	v_lshrrev_b32_e32 v0, 3, v11
	v_mul_lo_u32 v0, v0, s11
	v_mad_u32_u24 v0, v12, s6, v0
	v_or_b32_e32 v0, v0, v13
	v_lshlrev_b32_e32 v128, 1, v0
	v_lshlrev_b32_e32 v7, 4, v1
	v_lshl_add_u64 v[0:1], s[38:39], 0, v[128:129]
	v_lshl_add_u64 v[2:3], s[42:43], 0, v[128:129]
	s_mov_b64 s[80:81], 0
	s_mov_b32 s24, 0
	v_mov_b32_e32 v64, 0
	v_mov_b32_e32 v65, v197
	v_mov_b32_e32 v66, v197
	v_mov_b32_e32 v67, v197
	v_mov_b32_e32 v68, v197
	v_mov_b32_e32 v69, v197
	v_mov_b32_e32 v70, v197
	v_mov_b32_e32 v71, v197
	v_mov_b32_e32 v72, v197
	v_mov_b32_e32 v73, v197
	v_mov_b32_e32 v74, v197
	v_mov_b32_e32 v75, v197
	v_mov_b32_e32 v76, v197
	v_mov_b32_e32 v77, v197
	v_mov_b32_e32 v78, v197
	v_mov_b32_e32 v79, v197
	v_mov_b32_e32 v80, 0
	v_mov_b32_e32 v81, v197
	v_mov_b32_e32 v82, v197
	v_mov_b32_e32 v83, v197
	v_mov_b32_e32 v84, v197
	v_mov_b32_e32 v85, v197
	v_mov_b32_e32 v86, v197
	v_mov_b32_e32 v87, v197
	v_mov_b32_e32 v88, v197
	v_mov_b32_e32 v89, v197
	v_mov_b32_e32 v90, v197
	v_mov_b32_e32 v91, v197
	v_mov_b32_e32 v92, v197
	v_mov_b32_e32 v93, v197
	v_mov_b32_e32 v94, v197
	v_mov_b32_e32 v95, v197
	v_mov_b32_e32 v96, 0
	v_mov_b32_e32 v97, v197
	v_mov_b32_e32 v98, v197
	v_mov_b32_e32 v99, v197
	v_mov_b32_e32 v100, v197
	v_mov_b32_e32 v101, v197
	v_mov_b32_e32 v102, v197
	v_mov_b32_e32 v103, v197
	v_mov_b32_e32 v104, v197
	v_mov_b32_e32 v105, v197
	v_mov_b32_e32 v106, v197
	v_mov_b32_e32 v107, v197
	v_mov_b32_e32 v108, v197
	v_mov_b32_e32 v109, v197
	v_mov_b32_e32 v110, v197
	v_mov_b32_e32 v111, v197
	v_mov_b32_e32 v112, 0
	v_mov_b32_e32 v113, v197
	v_mov_b32_e32 v114, v197
	v_mov_b32_e32 v115, v197
	v_mov_b32_e32 v116, v197
	v_mov_b32_e32 v117, v197
	v_mov_b32_e32 v118, v197
	v_mov_b32_e32 v119, v197
	v_mov_b32_e32 v120, v197
	v_mov_b32_e32 v121, v197
	v_mov_b32_e32 v122, v197
	v_mov_b32_e32 v123, v197
	v_mov_b32_e32 v124, v197
	v_mov_b32_e32 v125, v197
	v_mov_b32_e32 v126, v197
	v_mov_b32_e32 v127, v197
	s_mov_b64 s[52:53], 0x3308100
	v_readfirstlane_b32 s25, v208
	s_nop 0
	s_lshr_b32 s25, s25, 8
	s_cmp_lg_u32 s25, 0
	s_cbranch_scc1 .Lstg40_top
; DI void wait_vm0() { asm volatile("s_waitcnt vmcnt(0)" ::: "memory"); }
; template <int MB, bool SWAP>
; DI void gemm_kloop(f32x16 (&acc)[MB][2], const h16* __restrict__ A, int lda, const h16* __restrict__ B, int ldb, int K, char* lds) {
;     ...
;   for (int kt = 0; kt < nk; ++kt) {
;     if (kt + 1 < nk) { if (MB == 2) asm volatile("s_waitcnt vmcnt(6)" ::: "memory"); else asm volatile("s_waitcnt vmcnt(5)" ::: "memory"); }
;     else wait_vm0();
;     __syncthreads();
;     const char* s = lds + cur * STAGE;
;     const int nbuf = cur == 0 ? 2 : cur - 1;
;     const bool more = kt + 2 < nk;
;     half8 af[2][MB], bf[2][2];
; #pragma unroll
;     for (int mb = 0; mb < MB; ++mb) af[0][mb] = *(const half8*)(s + a_rd + mb * 4096 + (((0 + hh) ^ sw) * 16));
; #pragma unroll
;     for (int nb = 0; nb < 2; ++nb) bf[0][nb] = *(const half8*)(s + b_rd + nb * 4096 + (((0 + hh) ^ sw) * 16));
; #pragma unroll
;     for (int ks = 0; ks < 4; ++ks) {
;       if (ks < 3) {
; #pragma unroll
;         for (int mb = 0; mb < MB; ++mb) af[(ks + 1) & 1][mb] = *(const half8*)(s + a_rd + mb * 4096 + (((2 * (ks + 1) + hh) ^ sw) * 16));
; #pragma unroll
;         for (int nb = 0; nb < 2; ++nb) bf[(ks + 1) & 1][nb] = *(const half8*)(s + b_rd + nb * 4096 + (((2 * (ks + 1) + hh) ^ sw) * 16));
;       }
;       if (more) {
;         if (2 * ks < NP) piece(2 * ks, kt + 2, nbuf);
;         if (2 * ks + 1 < NP) piece(2 * ks + 1, kt + 2, nbuf);
;       }
;       __builtin_amdgcn_sched_barrier(0);
;       __builtin_amdgcn_s_setprio(1);
; #pragma unroll
;       for (int mb = 0; mb < MB; ++mb)
; #pragma unroll
;         for (int nb = 0; nb < 2; ++nb)
;           acc[mb][nb] = SWAP ? __builtin_amdgcn_mfma_f32_32x32x16_f16(bf[ks & 1][nb], af[ks & 1][mb], acc[mb][nb], 0, 0, 0)
;                              : __builtin_amdgcn_mfma_f32_32x32x16_f16(af[ks & 1][mb], bf[ks & 1][nb], acc[mb][nb], 0, 0, 0);
;       __builtin_amdgcn_s_setprio(0);
;       __builtin_amdgcn_sched_barrier(0);
;     }
.LBB0_40:
	s_mul_i32 s25, s24, 0xc000
	s_add_i32 s33, s25, 0
	s_add_i32 s25, s25, 0xffff4000
	s_cmp_lg_u32 s24, 0
	s_cselect_b32 s25, s25, 0x18000
	v_add_u32_e32 v51, s25, v10
	v_add_u32_e32 v11, s33, v6
	v_add_u32_e32 v50, s33, v4
	v_add_u32_e32 v48, 0x2000, v51
	v_lshl_add_u64 v[44:45], v[0:1], 0, s[80:81]
	v_readfirstlane_b32 s25, v51
	v_add_u32_e32 v16, v11, v9
	v_add_u32_e32 v24, v50, v9
	v_add_u32_e32 v32, v11, v8
	v_add_u32_e32 v40, v50, v8
	v_lshl_add_u64 v[46:47], v[44:45], 0, s[52:53]
	v_lshl_add_u64 v[44:45], v[44:45], 0, s[90:91]
	s_mov_b32 m0, s25
	v_readfirstlane_b32 s25, v48
	s_waitcnt vmcnt(6)
	s_waitcnt lgkmcnt(0)
	s_barrier
	ds_read_b128 v[12:15], v16
	ds_read_b128 v[16:19], v16 offset:4096
	ds_read_b128 v[20:23], v24 offset:16384
	ds_read_b128 v[24:27], v24 offset:20480
	ds_read_b128 v[28:31], v32
	ds_read_b128 v[32:35], v32 offset:4096
	ds_read_b128 v[36:39], v40 offset:16384
	ds_read_b128 v[40:43], v40 offset:20480
	global_load_lds_dwordx4 v[44:45], off
	s_mov_b32 m0, s25
	v_lshl_add_u64 v[44:45], v[2:3], 0, s[80:81]
	global_load_lds_dwordx4 v[46:47], off
	v_lshl_add_u64 v[46:47], v[44:45], 0, s[72:73]
	s_setprio 1
	s_waitcnt lgkmcnt(0)
	v_mfma_f32_32x32x16_f16 v[112:127], v[20:23], v[12:15], v[112:127]
	v_mfma_f32_32x32x16_f16 v[96:111], v[24:27], v[12:15], v[96:111]
	v_mfma_f32_32x32x16_f16 v[80:95], v[20:23], v[16:19], v[80:95]
	v_mfma_f32_32x32x16_f16 v[64:79], v[24:27], v[16:19], v[64:79]
	s_setprio 0
	v_add_u32_e32 v53, 0x4000, v51
	v_add_u32_e32 v52, 0x6000, v51
	v_readfirstlane_b32 s25, v53
	v_add_u32_e32 v16, v11, v7
	v_add_u32_e32 v24, v50, v7
	s_mov_b32 m0, s25
	v_readfirstlane_b32 s25, v52
	ds_read_b128 v[12:15], v16
	ds_read_b128 v[16:19], v16 offset:4096
	ds_read_b128 v[20:23], v24 offset:16384
	ds_read_b128 v[24:27], v24 offset:20480
	v_lshl_add_u64 v[48:49], v[44:45], 0, s[88:89]
	global_load_lds_dwordx4 v[46:47], off
	s_mov_b32 m0, s25
	s_nop 0
	global_load_lds_dwordx4 v[48:49], off
	s_setprio 1
	v_mfma_f32_32x32x16_f16 v[112:127], v[36:39], v[28:31], v[112:127]
	v_mfma_f32_32x32x16_f16 v[96:111], v[40:43], v[28:31], v[96:111]
	v_mfma_f32_32x32x16_f16 v[80:95], v[36:39], v[32:35], v[80:95]
	v_mfma_f32_32x32x16_f16 v[64:79], v[40:43], v[32:35], v[64:79]
	s_setprio 0
	v_add_u32_e32 v11, v11, v5
	ds_read_b128 v[28:31], v11
	ds_read_b128 v[32:35], v11 offset:4096
	v_add_u32_e32 v11, v50, v5
	v_add_u32_e32 v48, 0x8000, v51
	ds_read_b128 v[36:39], v11 offset:16384
	ds_read_b128 v[40:43], v11 offset:20480
	v_add_u32_e32 v11, 0xa000, v51
	v_readfirstlane_b32 s25, v48
	v_lshl_add_u64 v[46:47], v[44:45], 0, s[34:35]
	v_lshl_add_u64 v[44:45], v[44:45], 0, s[68:69]
	s_mov_b32 m0, s25
	v_readfirstlane_b32 s25, v11
	global_load_lds_dwordx4 v[44:45], off
	s_mov_b32 m0, s25
	s_nop 0
	global_load_lds_dwordx4 v[46:47], off
	s_setprio 1
	s_waitcnt lgkmcnt(0)
	v_mfma_f32_32x32x16_f16 v[112:127], v[20:23], v[12:15], v[112:127]
	v_mfma_f32_32x32x16_f16 v[96:111], v[24:27], v[12:15], v[96:111]
	v_mfma_f32_32x32x16_f16 v[80:95], v[20:23], v[16:19], v[80:95]
	v_mfma_f32_32x32x16_f16 v[64:79], v[24:27], v[16:19], v[64:79]
	s_setprio 0
	s_setprio 1
	v_mfma_f32_32x32x16_f16 v[112:127], v[36:39], v[28:31], v[112:127]
	v_mfma_f32_32x32x16_f16 v[96:111], v[40:43], v[28:31], v[96:111]
	v_mfma_f32_32x32x16_f16 v[80:95], v[36:39], v[32:35], v[80:95]
	v_mfma_f32_32x32x16_f16 v[64:79], v[40:43], v[32:35], v[64:79]
	s_setprio 0
	s_add_i32 s25, s24, 1
	s_cmp_lg_u32 s24, 2
	s_cselect_b32 s24, s25, 0
	s_add_u32 s80, s80, 0x80
	s_addc_u32 s81, s81, 0
	s_cmpk_eq_i32 s80, 0x700
	s_cbranch_scc0 .LBB0_40
	s_branch .Lstg40_join
.Lstg40_top:
	s_mul_i32 s25, s24, 0xc000
	s_add_i32 s33, s25, 0
	s_add_i32 s25, s25, 0xffff4000
	s_cmp_lg_u32 s24, 0
	s_cselect_b32 s25, s25, 0x18000
	v_add_u32_e32 v51, s25, v10
	v_add_u32_e32 v11, s33, v6
	v_add_u32_e32 v50, s33, v4
	v_add_u32_e32 v48, 0x2000, v51
	v_lshl_add_u64 v[44:45], v[0:1], 0, s[80:81]
	v_readfirstlane_b32 s25, v51
	v_lshl_add_u64 v[46:47], v[44:45], 0, s[52:53]
	v_lshl_add_u64 v[44:45], v[44:45], 0, s[90:91]
	s_mov_b32 m0, s25
	v_readfirstlane_b32 s25, v48
	s_waitcnt vmcnt(6)
	s_waitcnt lgkmcnt(0)
	s_barrier
	s_cmp_eq_u32 s80, 0
	s_cbranch_scc1 .Lstg40_skip
	s_setprio 1
	v_mfma_f32_32x32x16_f16 v[112:127], v[20:23], v[12:15], v[112:127]
	v_mfma_f32_32x32x16_f16 v[96:111], v[24:27], v[12:15], v[96:111]
	v_mfma_f32_32x32x16_f16 v[80:95], v[20:23], v[16:19], v[80:95]
	v_mfma_f32_32x32x16_f16 v[64:79], v[24:27], v[16:19], v[64:79]
	v_mfma_f32_32x32x16_f16 v[112:127], v[36:39], v[28:31], v[112:127]
	v_mfma_f32_32x32x16_f16 v[96:111], v[40:43], v[28:31], v[96:111]
	v_mfma_f32_32x32x16_f16 v[80:95], v[36:39], v[32:35], v[80:95]
	v_mfma_f32_32x32x16_f16 v[64:79], v[40:43], v[32:35], v[64:79]
	s_setprio 0
; DI void wait_vm0() { asm volatile("s_waitcnt vmcnt(0)" ::: "memory"); }
; template <int MB, bool SWAP>
; DI void gemm_kloop(f32x16 (&acc)[MB][2], const h16* __restrict__ A, int lda, const h16* __restrict__ B, int ldb, int K, char* lds) {
;     ...
;   for (int kt = 0; kt < nk; ++kt) {
;     if (kt + 1 < nk) { if (MB == 2) asm volatile("s_waitcnt vmcnt(6)" ::: "memory"); else asm volatile("s_waitcnt vmcnt(5)" ::: "memory"); }
;     else wait_vm0();
;     __syncthreads();
;     const char* s = lds + cur * STAGE;
;     const int nbuf = cur == 0 ? 2 : cur - 1;
;     const bool more = kt + 2 < nk;
;     half8 af[2][MB], bf[2][2];
; #pragma unroll
;     for (int mb = 0; mb < MB; ++mb) af[0][mb] = *(const half8*)(s + a_rd + mb * 4096 + (((0 + hh) ^ sw) * 16));
; #pragma unroll
;     for (int nb = 0; nb < 2; ++nb) bf[0][nb] = *(const half8*)(s + b_rd + nb * 4096 + (((0 + hh) ^ sw) * 16));
; #pragma unroll
;     for (int ks = 0; ks < 4; ++ks) {
;       if (ks < 3) {
; #pragma unroll
;         for (int mb = 0; mb < MB; ++mb) af[(ks + 1) & 1][mb] = *(const half8*)(s + a_rd + mb * 4096 + (((2 * (ks + 1) + hh) ^ sw) * 16));
; #pragma unroll
;         for (int nb = 0; nb < 2; ++nb) bf[(ks + 1) & 1][nb] = *(const half8*)(s + b_rd + nb * 4096 + (((2 * (ks + 1) + hh) ^ sw) * 16));
;       }
;       if (more) {
;         if (2 * ks < NP) piece(2 * ks, kt + 2, nbuf);
;         if (2 * ks + 1 < NP) piece(2 * ks + 1, kt + 2, nbuf);
;       }
;       __builtin_amdgcn_sched_barrier(0);
;       __builtin_amdgcn_s_setprio(1);
; #pragma unroll
;       for (int mb = 0; mb < MB; ++mb)
; #pragma unroll
;         for (int nb = 0; nb < 2; ++nb)
;           acc[mb][nb] = SWAP ? __builtin_amdgcn_mfma_f32_32x32x16_f16(bf[ks & 1][nb], af[ks & 1][mb], acc[mb][nb], 0, 0, 0)
;                              : __builtin_amdgcn_mfma_f32_32x32x16_f16(af[ks & 1][mb], bf[ks & 1][nb], acc[mb][nb], 0, 0, 0);
;       __builtin_amdgcn_s_setprio(0);
;       __builtin_amdgcn_sched_barrier(0);
;     }
.Lstg40_skip:
	v_add_u32_e32 v16, v11, v9
	v_add_u32_e32 v24, v50, v9
	v_add_u32_e32 v32, v11, v8
	v_add_u32_e32 v40, v50, v8
	ds_read_b128 v[12:15], v16
	ds_read_b128 v[16:19], v16 offset:4096
	ds_read_b128 v[20:23], v24 offset:16384
	ds_read_b128 v[24:27], v24 offset:20480
	ds_read_b128 v[28:31], v32
	ds_read_b128 v[32:35], v32 offset:4096
	ds_read_b128 v[36:39], v40 offset:16384
	ds_read_b128 v[40:43], v40 offset:20480
	global_load_lds_dwordx4 v[44:45], off
	s_mov_b32 m0, s25
	v_lshl_add_u64 v[44:45], v[2:3], 0, s[80:81]
	global_load_lds_dwordx4 v[46:47], off
	v_lshl_add_u64 v[46:47], v[44:45], 0, s[72:73]
	s_setprio 1
	s_waitcnt lgkmcnt(0)
	v_mfma_f32_32x32x16_f16 v[112:127], v[20:23], v[12:15], v[112:127]
	v_mfma_f32_32x32x16_f16 v[96:111], v[24:27], v[12:15], v[96:111]
	v_mfma_f32_32x32x16_f16 v[80:95], v[20:23], v[16:19], v[80:95]
	v_mfma_f32_32x32x16_f16 v[64:79], v[24:27], v[16:19], v[64:79]
	s_setprio 0
	v_add_u32_e32 v53, 0x4000, v51
	v_add_u32_e32 v52, 0x6000, v51
	v_readfirstlane_b32 s25, v53
	v_add_u32_e32 v16, v11, v7
	v_add_u32_e32 v24, v50, v7
	s_mov_b32 m0, s25
	v_readfirstlane_b32 s25, v52
	ds_read_b128 v[12:15], v16
	ds_read_b128 v[16:19], v16 offset:4096
	ds_read_b128 v[20:23], v24 offset:16384
	ds_read_b128 v[24:27], v24 offset:20480
	v_lshl_add_u64 v[48:49], v[44:45], 0, s[88:89]
	global_load_lds_dwordx4 v[46:47], off
	s_mov_b32 m0, s25
	s_nop 0
	global_load_lds_dwordx4 v[48:49], off
	s_setprio 1
	v_mfma_f32_32x32x16_f16 v[112:127], v[36:39], v[28:31], v[112:127]
	v_mfma_f32_32x32x16_f16 v[96:111], v[40:43], v[28:31], v[96:111]
	v_mfma_f32_32x32x16_f16 v[80:95], v[36:39], v[32:35], v[80:95]
	v_mfma_f32_32x32x16_f16 v[64:79], v[40:43], v[32:35], v[64:79]
	s_setprio 0
	v_add_u32_e32 v11, v11, v5
	ds_read_b128 v[28:31], v11
	ds_read_b128 v[32:35], v11 offset:4096
	v_add_u32_e32 v11, v50, v5
	v_add_u32_e32 v48, 0x8000, v51
	ds_read_b128 v[36:39], v11 offset:16384
	ds_read_b128 v[40:43], v11 offset:20480
	v_add_u32_e32 v11, 0xa000, v51
	v_readfirstlane_b32 s25, v48
	v_lshl_add_u64 v[46:47], v[44:45], 0, s[34:35]
	v_lshl_add_u64 v[44:45], v[44:45], 0, s[68:69]
	s_mov_b32 m0, s25
	v_readfirstlane_b32 s25, v11
	global_load_lds_dwordx4 v[44:45], off
	s_mov_b32 m0, s25
	s_nop 0
	global_load_lds_dwordx4 v[46:47], off
	s_add_i32 s25, s24, 1
	s_cmp_lg_u32 s24, 2
	s_cselect_b32 s24, s25, 0
	s_add_u32 s80, s80, 0x80
	s_addc_u32 s81, s81, 0
	s_cmpk_eq_i32 s80, 0x700
	s_cbranch_scc0 .Lstg40_top
	s_waitcnt lgkmcnt(0)
	s_setprio 1
	v_mfma_f32_32x32x16_f16 v[112:127], v[20:23], v[12:15], v[112:127]
	v_mfma_f32_32x32x16_f16 v[96:111], v[24:27], v[12:15], v[96:111]
	v_mfma_f32_32x32x16_f16 v[80:95], v[20:23], v[16:19], v[80:95]
	v_mfma_f32_32x32x16_f16 v[64:79], v[24:27], v[16:19], v[64:79]
	v_mfma_f32_32x32x16_f16 v[112:127], v[36:39], v[28:31], v[112:127]
	v_mfma_f32_32x32x16_f16 v[96:111], v[40:43], v[28:31], v[96:111]
	v_mfma_f32_32x32x16_f16 v[80:95], v[36:39], v[32:35], v[80:95]
	v_mfma_f32_32x32x16_f16 v[64:79], v[40:43], v[32:35], v[64:79]
	s_setprio 0
.Lstg40_join:
	s_cmp_eq_u32 s45, 1
	s_cselect_b32 s24, s12, 0x1ba66000
	s_cmp_lg_u32 s45, 0
	s_cselect_b32 s24, s24, 0x10f66000
	s_add_i32 s25, 0, 0x18000
	v_add_u32_e32 v38, s25, v6
	v_add_u32_e32 v10, v38, v9
	v_add3_u32 v18, s25, v9, v4
	v_add_u32_e32 v26, v38, v8
	v_add3_u32 v34, s25, v8, v4
	s_waitcnt vmcnt(6)
	s_waitcnt lgkmcnt(0)
	s_barrier
	ds_read_b128 v[0:3], v10
	ds_read_b128 v[10:13], v10 offset:4096
	ds_read_b128 v[14:17], v18 offset:16384
	ds_read_b128 v[18:21], v18 offset:20480
	ds_read_b128 v[22:25], v26
	ds_read_b128 v[26:29], v26 offset:4096
	ds_read_b128 v[30:33], v34 offset:16384
	ds_read_b128 v[34:37], v34 offset:20480
	s_mov_b32 vcc_hi, 0
	s_setprio 1
	s_waitcnt lgkmcnt(5)
	v_mfma_f32_32x32x16_f16 v[112:127], v[14:17], v[0:3], v[112:127]
	s_waitcnt lgkmcnt(4)
	v_mfma_f32_32x32x16_f16 v[96:111], v[18:21], v[0:3], v[96:111]
	v_mfma_f32_32x32x16_f16 v[80:95], v[14:17], v[10:13], v[80:95]
	v_mfma_f32_32x32x16_f16 v[64:79], v[18:21], v[10:13], v[64:79]
	s_setprio 0
	v_add_u32_e32 v10, v38, v7
	v_add3_u32 v18, s25, v7, v4
	ds_read_b128 v[0:3], v10
	ds_read_b128 v[10:13], v10 offset:4096
	ds_read_b128 v[14:17], v18 offset:16384
	ds_read_b128 v[18:21], v18 offset:20480
	s_setprio 1
	s_waitcnt lgkmcnt(5)
	v_mfma_f32_32x32x16_f16 v[112:127], v[30:33], v[22:25], v[112:127]
	s_waitcnt lgkmcnt(4)
	v_mfma_f32_32x32x16_f16 v[96:111], v[34:37], v[22:25], v[96:111]
	v_mfma_f32_32x32x16_f16 v[80:95], v[30:33], v[26:29], v[80:95]
	v_mfma_f32_32x32x16_f16 v[64:79], v[34:37], v[26:29], v[64:79]
	s_setprio 0
	v_add_u32_e32 v26, v38, v5
	v_add3_u32 v34, s25, v5, v4
	ds_read_b128 v[22:25], v26
	ds_read_b128 v[26:29], v26 offset:4096
	ds_read_b128 v[30:33], v34 offset:16384
	ds_read_b128 v[34:37], v34 offset:20480
	s_setprio 1
	s_waitcnt lgkmcnt(5)
	v_mfma_f32_32x32x16_f16 v[112:127], v[14:17], v[0:3], v[112:127]
	s_waitcnt lgkmcnt(4)
	v_mfma_f32_32x32x16_f16 v[96:111], v[18:21], v[0:3], v[96:111]
	v_mfma_f32_32x32x16_f16 v[80:95], v[14:17], v[10:13], v[80:95]
	v_mfma_f32_32x32x16_f16 v[64:79], v[18:21], v[10:13], v[64:79]
	s_setprio 0
	s_setprio 1
	s_waitcnt lgkmcnt(1)
	v_mfma_f32_32x32x16_f16 v[112:127], v[30:33], v[22:25], v[112:127]
	s_waitcnt lgkmcnt(0)
	v_mfma_f32_32x32x16_f16 v[96:111], v[34:37], v[22:25], v[96:111]
	v_mfma_f32_32x32x16_f16 v[80:95], v[30:33], v[26:29], v[80:95]
	v_mfma_f32_32x32x16_f16 v[64:79], v[34:37], v[26:29], v[64:79]
	s_setprio 0
	v_add_u32_e32 v6, 0, v6
	v_add_u32_e32 v4, 0, v4
	v_add_u32_e32 v10, v6, v9
	v_add_u32_e32 v9, v4, v9
	s_waitcnt vmcnt(0)
	s_barrier
; DI int otid() { int t = threadIdx.x; asm volatile("" : "+v"(t)); return t; }
; template <int MB, bool SWAP>
; DI void gemm_kloop(f32x16 (&acc)[MB][2], const h16* __restrict__ A, int lda, const h16* __restrict__ B, int ldb, int K, char* lds) {
;     ...
;   const int tid = otid(), w = tid >> 6, lane = tid & 63;
;   const int wr = w >> 2, wc = w & 3;
;   const int lrow = w * 8 + (lane >> 3), pch = lane & 7;
;   const int gch = pch ^ ((lrow >> 1) & 7);
;   const unsigned voa = (unsigned)(lrow * lda + gch * 8) * 2u, vob = (unsigned)(lrow * ldb + gch * 8) * 2u;
;   const int lofs = lrow * 128 + pch * 16;
;   const int r32 = lane & 31, hh = lane >> 5, sw = (r32 >> 1) & 7;
;   const int a_rd = (wr * 32 * MB + r32) * 128;
;   const int b_rd = A_BYTES + (wc * 64 + r32) * 128;
;   const int nk = K >> 6;
;   constexpr int NP = MB + 4;
;   auto piece = [&](int p, int kt, int buf) {
;     char* s = lds + buf * STAGE;
;     ...
;     for (int mb = 0; mb < MB; ++mb) af[0][mb] = *(const half8*)(s + a_rd + mb * 4096 + (((0 + hh) ^ sw) * 16));
; #pragma unroll
;     for (int nb = 0; nb < 2; ++nb) bf[0][nb] = *(const half8*)(s + b_rd + nb * 4096 + (((0 + hh) ^ sw) * 16));
; #pragma unroll
;     for (int ks = 0; ks < 4; ++ks) {
;       if (ks < 3) {
; #pragma unroll
;         for (int mb = 0; mb < MB; ++mb) af[(ks + 1) & 1][mb] = *(const half8*)(s + a_rd + mb * 4096 + (((2 * (ks + 1) + hh) ^ sw) * 16));
; #pragma unroll
;         for (int nb = 0; nb < 2; ++nb) bf[(ks + 1) & 1][nb] = *(const half8*)(s + b_rd + nb * 4096 + (((2 * (ks + 1) + hh) ^ sw) * 16));
;       }
;       if (more) {
;         if (2 * ks < NP) piece(2 * ks, kt + 2, nbuf);
;         if (2 * ks + 1 < NP) piece(2 * ks + 1, kt + 2, nbuf);
;       }
;       __builtin_amdgcn_sched_barrier(0);
;       __builtin_amdgcn_s_setprio(1);
; #pragma unroll
;       for (int mb = 0; mb < MB; ++mb)
; #pragma unroll
;         for (int nb = 0; nb < 2; ++nb)
;           acc[mb][nb] = SWAP ? __builtin_amdgcn_mfma_f32_32x32x16_f16(bf[ks & 1][nb], af[ks & 1][mb], acc[mb][nb], 0, 0, 0)
;                              : __builtin_amdgcn_mfma_f32_32x32x16_f16(af[ks & 1][mb], bf[ks & 1][nb], acc[mb][nb], 0, 0, 0);
;       __builtin_amdgcn_s_setprio(0);
;       __builtin_amdgcn_sched_barrier(0);
;     }
;     cur = cur == 2 ? 0 : cur + 1;
;   }
;   __syncthreads();
	ds_read_b128 v[0:3], v10
	ds_read_b128 v[10:13], v10 offset:4096
	ds_read_b128 v[14:17], v9 offset:16384
	ds_read_b128 v[18:21], v9 offset:20480
	v_add_u32_e32 v9, v6, v8
	v_add_u32_e32 v8, v4, v8
	ds_read_b128 v[22:25], v9
	ds_read_b128 v[26:29], v9 offset:4096
	ds_read_b128 v[30:33], v8 offset:16384
	ds_read_b128 v[34:37], v8 offset:20480
	s_setprio 1
	s_waitcnt lgkmcnt(5)
	v_mfma_f32_32x32x16_f16 v[112:127], v[14:17], v[0:3], v[112:127]
	s_waitcnt lgkmcnt(4)
	v_mfma_f32_32x32x16_f16 v[96:111], v[18:21], v[0:3], v[96:111]
	v_mfma_f32_32x32x16_f16 v[80:95], v[14:17], v[10:13], v[80:95]
	v_mfma_f32_32x32x16_f16 v[64:79], v[18:21], v[10:13], v[64:79]
	s_setprio 0
	v_add_u32_e32 v8, v6, v7
	v_add_u32_e32 v7, v4, v7
	ds_read_b128 v[0:3], v8
	ds_read_b128 v[8:11], v8 offset:4096
	ds_read_b128 v[12:15], v7 offset:16384
	ds_read_b128 v[16:19], v7 offset:20480
	s_setprio 1
	s_waitcnt lgkmcnt(5)
	v_mfma_f32_32x32x16_f16 v[112:127], v[30:33], v[22:25], v[112:127]
	s_waitcnt lgkmcnt(4)
	v_mfma_f32_32x32x16_f16 v[96:111], v[34:37], v[22:25], v[96:111]
	v_mfma_f32_32x32x16_f16 v[80:95], v[30:33], v[26:29], v[80:95]
	v_mfma_f32_32x32x16_f16 v[64:79], v[34:37], v[26:29], v[64:79]
	s_setprio 0
	v_add_u32_e32 v6, v6, v5
	v_add_u32_e32 v28, v4, v5
	ds_read_b128 v[20:23], v6
	ds_read_b128 v[24:27], v6 offset:4096
	ds_read_b128 v[4:7], v28 offset:16384
	ds_read_b128 v[28:31], v28 offset:20480
	s_setprio 1
	s_waitcnt lgkmcnt(5)
	v_mfma_f32_32x32x16_f16 v[112:127], v[12:15], v[0:3], v[112:127]
	s_waitcnt lgkmcnt(4)
	v_mfma_f32_32x32x16_f16 v[96:111], v[16:19], v[0:3], v[96:111]
	v_mfma_f32_32x32x16_f16 v[80:95], v[12:15], v[8:11], v[80:95]
	v_mfma_f32_32x32x16_f16 v[64:79], v[16:19], v[8:11], v[64:79]
	s_setprio 0
	s_setprio 1
	s_waitcnt lgkmcnt(1)
	v_mfma_f32_32x32x16_f16 v[112:127], v[4:7], v[20:23], v[112:127]
	s_waitcnt lgkmcnt(0)
	v_mfma_f32_32x32x16_f16 v[96:111], v[28:31], v[20:23], v[96:111]
	v_mfma_f32_32x32x16_f16 v[80:95], v[4:7], v[24:27], v[80:95]
	v_mfma_f32_32x32x16_f16 v[64:79], v[28:31], v[24:27], v[64:79]
	s_setprio 0
	v_mov_b32_e32 v6, v208
	s_barrier
	s_add_u32 s52, s3, s24
	v_ashrrev_i32_e32 v7, 3, v6
	v_bfe_u32 v8, v6, 3, 3
	v_and_or_b32 v0, v7, -8, v8
	v_lshrrev_b32_e32 v1, 1, v0
	v_xor_b32_e32 v1, v1, v6
	v_lshlrev_b32_e32 v1, 3, v1
	v_mul_lo_u32 v2, v0, s13
	v_and_b32_e32 v9, 56, v1
	v_or_b32_e32 v1, v9, v2
	v_lshlrev_b32_e32 v128, 1, v1
	v_lshlrev_b32_e32 v1, 4, v6
	v_and_b32_e32 v1, 0x70, v1
	v_lshl_or_b32 v10, v0, 7, v1
	s_addc_u32 s53, s2, 0
	s_or_b32 s25, vcc_lo, s71
	v_add_u32_e32 v205, 0, v10
	s_mul_i32 s84, s25, 0x240
	v_readfirstlane_b32 s25, v205
	s_waitcnt vmcnt(0)
	s_mov_b32 m0, s25
	v_add_u32_e32 v13, 0x2000, v205
	v_lshl_add_u64 v[2:3], s[52:53], 0, v[128:129]
	global_load_lds_dwordx4 v128, s[52:53]
	s_mov_b64 s[52:53], 0x12000
	v_readfirstlane_b32 s25, v13
	s_lshl_b64 s[54:55], s[84:85], 1
	v_lshl_add_u64 v[4:5], v[2:3], 0, s[52:53]
	s_mov_b32 m0, s25
	s_add_u32 s54, s75, s54
	v_and_b32_e32 v0, 31, v6
	v_lshrrev_b32_e32 v1, 2, v6
	global_load_lds_dwordx4 v[4:5], off
	v_add_u32_e32 v4, 0x4000, v205
	s_addc_u32 s55, s76, s55
	v_and_or_b32 v12, v1, s7, v0
	v_lshlrev_b32_e32 v0, 7, v6
	v_readfirstlane_b32 s25, v4
	v_add_u32_e32 v13, 0x6000, v205
	v_and_b32_e32 v199, 0x6f80, v0
	v_lshl_add_u64 v[0:1], s[54:55], 0, v[128:129]
	s_mov_b32 m0, s25
	v_readfirstlane_b32 s25, v13
	v_add_u32_e32 v13, 0x8000, v205
	global_load_lds_dwordx4 v128, s[54:55]
	v_lshl_add_u64 v[4:5], v[0:1], 0, s[52:53]
	s_mov_b32 m0, s25
	s_mov_b64 s[52:53], 0x24000
	v_readfirstlane_b32 s25, v13
	v_add_u32_e32 v13, 0xa000, v205
	global_load_lds_dwordx4 v[4:5], off
	v_lshl_add_u64 v[4:5], v[0:1], 0, s[52:53]
	s_mov_b32 m0, s25
	s_mov_b64 s[52:53], 0x36000
	v_readfirstlane_b32 s25, v13
	v_lshlrev_b32_e32 v204, 7, v12
	v_add_u32_e32 v12, 0xc000, v205
	global_load_lds_dwordx4 v[4:5], off
	v_lshl_add_u64 v[4:5], v[0:1], 0, s[52:53]
	s_mov_b32 m0, s25
	v_readfirstlane_b32 s25, v12
	global_load_lds_dwordx4 v[4:5], off
	v_lshl_add_u64 v[4:5], v[2:3], 0, s[22:23]
	s_mov_b32 m0, s25
	s_mov_b64 s[52:53], 0x12080
	global_load_lds_dwordx4 v[4:5], off
	v_add_u32_e32 v4, 0xe000, v205
	v_lshl_add_u64 v[2:3], v[2:3], 0, s[52:53]
	v_readfirstlane_b32 s25, v4
	v_add_u32_e32 v4, s8, v10
	s_mov_b32 m0, s25
	v_readfirstlane_b32 s25, v4
	v_add_u32_e32 v4, s9, v10
	global_load_lds_dwordx4 v[2:3], off
	v_lshl_add_u64 v[2:3], v[0:1], 0, s[22:23]
	s_mov_b32 m0, s25
	v_readfirstlane_b32 s25, v4
	v_add_u32_e32 v4, s79, v10
	global_load_lds_dwordx4 v[2:3], off
	v_lshl_add_u64 v[2:3], v[0:1], 0, s[52:53]
	s_mov_b32 m0, s25
	s_mov_b64 s[52:53], 0x24080
	v_readfirstlane_b32 s25, v4
	global_load_lds_dwordx4 v[2:3], off
	v_lshl_add_u64 v[2:3], v[0:1], 0, s[52:53]
	s_mov_b32 m0, s25
	s_mov_b64 s[52:53], 0x36080
	global_load_lds_dwordx4 v[2:3], off
	v_add_u32_e32 v2, s10, v10
	v_lshl_add_u64 v[0:1], v[0:1], 0, s[52:53]
	v_readfirstlane_b32 s25, v2
	s_mov_b32 m0, s25
	v_lshrrev_b32_e32 v11, 1, v6
	global_load_lds_dwordx4 v[0:1], off
	v_bfe_u32 v13, v6, 5, 1
	v_bfe_u32 v0, v6, 1, 3
	v_bitop3_b32 v1, v13, v11, 7 bitop3:0x78
	v_lshlrev_b32_e32 v203, 4, v1
	v_bitop3_b32 v1, v13, v0, 2 bitop3:0x36
	v_lshlrev_b32_e32 v202, 4, v1
	v_bitop3_b32 v1, v13, v0, 4 bitop3:0x36
	v_bitop3_b32 v0, v13, v0, 6 bitop3:0x36
	v_lshlrev_b32_e32 v200, 4, v0
	v_lshrrev_b32_e32 v0, 3, v7
	v_mul_lo_u32 v0, v0, s14
	v_mad_u32_u24 v0, v8, s13, v0
	v_or_b32_e32 v0, v0, v9
	s_add_u32 s24, s70, s24
	v_lshlrev_b32_e32 v128, 1, v0
	s_addc_u32 s25, s44, 0
	v_mov_b32_e32 v0, 0
	v_lshlrev_b32_e32 v201, 4, v1
	v_lshl_add_u64 v[186:187], s[24:25], 0, v[128:129]
	v_lshl_add_u64 v[188:189], s[40:41], 0, v[128:129]
	s_mov_b64 s[80:81], 0
; DI void wait_vm0() { asm volatile("s_waitcnt vmcnt(0)" ::: "memory"); }
; template <int MB, bool SWAP>
; DI void gemm_kloop(f32x16 (&acc)[MB][2], const h16* __restrict__ A, int lda, const h16* __restrict__ B, int ldb, int K, char* lds) {
;     ...
;   for (int kt = 0; kt < nk; ++kt) {
;     if (kt + 1 < nk) { if (MB == 2) asm volatile("s_waitcnt vmcnt(6)" ::: "memory"); else asm volatile("s_waitcnt vmcnt(5)" ::: "memory"); }
;     else wait_vm0();
;     __syncthreads();
;     const char* s = lds + cur * STAGE;
;     const int nbuf = cur == 0 ? 2 : cur - 1;
;     const bool more = kt + 2 < nk;
;     half8 af[2][MB], bf[2][2];
; #pragma unroll
;     for (int mb = 0; mb < MB; ++mb) af[0][mb] = *(const half8*)(s + a_rd + mb * 4096 + (((0 + hh) ^ sw) * 16));
; #pragma unroll
;     for (int nb = 0; nb < 2; ++nb) bf[0][nb] = *(const half8*)(s + b_rd + nb * 4096 + (((0 + hh) ^ sw) * 16));
; #pragma unroll
;     for (int ks = 0; ks < 4; ++ks) {
;       if (ks < 3) {
; #pragma unroll
;         for (int mb = 0; mb < MB; ++mb) af[(ks + 1) & 1][mb] = *(const half8*)(s + a_rd + mb * 4096 + (((2 * (ks + 1) + hh) ^ sw) * 16));
; #pragma unroll
;         for (int nb = 0; nb < 2; ++nb) bf[(ks + 1) & 1][nb] = *(const half8*)(s + b_rd + nb * 4096 + (((2 * (ks + 1) + hh) ^ sw) * 16));
;       }
;       if (more) {
;         if (2 * ks < NP) piece(2 * ks, kt + 2, nbuf);
;         if (2 * ks + 1 < NP) piece(2 * ks + 1, kt + 2, nbuf);
;       }
;       __builtin_amdgcn_sched_barrier(0);
;       __builtin_amdgcn_s_setprio(1);
; #pragma unroll
;       for (int mb = 0; mb < MB; ++mb)
; #pragma unroll
;         for (int nb = 0; nb < 2; ++nb)
;           acc[mb][nb] = SWAP ? __builtin_amdgcn_mfma_f32_32x32x16_f16(bf[ks & 1][nb], af[ks & 1][mb], acc[mb][nb], 0, 0, 0)
;                              : __builtin_amdgcn_mfma_f32_32x32x16_f16(af[ks & 1][mb], bf[ks & 1][nb], acc[mb][nb], 0, 0, 0);
;       __builtin_amdgcn_s_setprio(0);
;       __builtin_amdgcn_sched_barrier(0);
;     }
	v_mov_b32_e32 v1, v0
	v_mov_b32_e32 v2, v0
	v_mov_b32_e32 v3, v0
	v_mov_b32_e32 v4, v0
	v_mov_b32_e32 v5, v0
	v_mov_b32_e32 v6, v0
	v_mov_b32_e32 v7, v0
	v_mov_b32_e32 v8, v0
	v_mov_b32_e32 v9, v0
	v_mov_b32_e32 v10, v0
	v_mov_b32_e32 v11, v0
	v_mov_b32_e32 v12, v0
	v_mov_b32_e32 v13, v0
	v_mov_b32_e32 v14, v0
	v_mov_b32_e32 v15, v0
	v_mov_b32_e32 v16, v0
	v_mov_b32_e32 v17, v0
	v_mov_b32_e32 v18, v0
	v_mov_b32_e32 v19, v0
	v_mov_b32_e32 v20, v0
	v_mov_b32_e32 v21, v0
	v_mov_b32_e32 v22, v0
	v_mov_b32_e32 v23, v0
	v_mov_b32_e32 v24, v0
	v_mov_b32_e32 v25, v0
	v_mov_b32_e32 v26, v0
	v_mov_b32_e32 v27, v0
	v_mov_b32_e32 v28, v0
	v_mov_b32_e32 v29, v0
	v_mov_b32_e32 v30, v0
	v_mov_b32_e32 v31, v0
	v_mov_b32_e32 v32, v0
	v_mov_b32_e32 v33, v0
	v_mov_b32_e32 v34, v0
	v_mov_b32_e32 v35, v0
	v_mov_b32_e32 v36, v0
	v_mov_b32_e32 v37, v0
	v_mov_b32_e32 v38, v0
	v_mov_b32_e32 v39, v0
	v_mov_b32_e32 v40, v0
	v_mov_b32_e32 v41, v0
	v_mov_b32_e32 v42, v0
	v_mov_b32_e32 v43, v0
	v_mov_b32_e32 v44, v0
	v_mov_b32_e32 v45, v0
	v_mov_b32_e32 v46, v0
	v_mov_b32_e32 v47, v0
	v_mov_b32_e32 v48, v0
	v_mov_b32_e32 v49, v0
	v_mov_b32_e32 v50, v0
	v_mov_b32_e32 v51, v0
	v_mov_b32_e32 v52, v0
	v_mov_b32_e32 v53, v0
	v_mov_b32_e32 v54, v0
	v_mov_b32_e32 v55, v0
	v_mov_b32_e32 v56, v0
	v_mov_b32_e32 v57, v0
	v_mov_b32_e32 v58, v0
	v_mov_b32_e32 v59, v0
	v_mov_b32_e32 v60, v0
	v_mov_b32_e32 v61, v0
	v_mov_b32_e32 v62, v0
	v_mov_b32_e32 v63, v0
	s_mov_b64 s[52:53], 0x1188100
	v_readfirstlane_b32 s25, v208
	s_nop 0
	s_lshr_b32 s25, s25, 8
	s_cmp_lg_u32 s25, 0
	s_cbranch_scc1 .Lstg42_top
.LBB0_42:
	s_mul_i32 s24, vcc_hi, 0xc000
	s_add_i32 s25, s24, 0
	v_add_u32_e32 v128, s25, v204
	v_add_u32_e32 v206, v128, v203
	v_add_u32_e32 v215, s25, v199
	s_add_i32 s24, s24, 0xffff4000
	s_waitcnt vmcnt(6)
	s_waitcnt lgkmcnt(0)
	s_barrier
	ds_read_b128 v[210:213], v206
	ds_read_b128 v[224:227], v206 offset:4096
	v_add_u32_e32 v206, v215, v203
	s_cmp_lg_u32 vcc_hi, 0
	ds_read_b128 v[228:231], v206 offset:16384
	ds_read_b128 v[232:235], v206 offset:20480
	s_cselect_b32 s24, s24, 0x18000
	v_add_u32_e32 v206, v128, v202
	ds_read_b128 v[236:239], v206
	ds_read_b128 v[240:243], v206 offset:4096
	v_add_u32_e32 v206, v215, v202
	v_add_u32_e32 v218, s24, v205
	ds_read_b128 v[244:247], v206 offset:16384
	ds_read_b128 v[248:251], v206 offset:20480
	v_add_u32_e32 v220, 0x2000, v218
	v_lshl_add_u64 v[206:207], v[186:187], 0, s[80:81]
	v_readfirstlane_b32 s24, v218
	v_lshl_add_u64 v[216:217], v[206:207], 0, s[92:93]
	v_lshl_add_u64 v[206:207], v[206:207], 0, s[30:31]
	s_mov_b32 m0, s24
	v_readfirstlane_b32 s24, v220
	global_load_lds_dwordx4 v[206:207], off
	s_mov_b32 m0, s24
	v_lshl_add_u64 v[206:207], v[188:189], 0, s[80:81]
	global_load_lds_dwordx4 v[216:217], off
	v_lshl_add_u64 v[216:217], v[206:207], 0, s[52:53]
	s_setprio 1
	s_waitcnt lgkmcnt(0)
	v_mfma_f32_32x32x16_f16 v[48:63], v[228:231], v[210:213], v[48:63]
	v_mfma_f32_32x32x16_f16 v[32:47], v[232:235], v[210:213], v[32:47]
	v_mfma_f32_32x32x16_f16 v[16:31], v[228:231], v[224:227], v[16:31]
	v_mfma_f32_32x32x16_f16 v[0:15], v[232:235], v[224:227], v[0:15]
	s_setprio 0
	v_add_u32_e32 v252, 0x4000, v218
	v_add_u32_e32 v220, v128, v201
	v_add_u32_e32 v223, 0x6000, v218
	v_readfirstlane_b32 s24, v252
	ds_read_b128 v[210:213], v220
	ds_read_b128 v[224:227], v220 offset:4096
	v_add_u32_e32 v220, v215, v201
	s_mov_b32 m0, s24
	v_readfirstlane_b32 s24, v223
	ds_read_b128 v[228:231], v220 offset:16384
	ds_read_b128 v[232:235], v220 offset:20480
	v_lshl_add_u64 v[220:221], v[206:207], 0, s[82:83]
	global_load_lds_dwordx4 v[216:217], off
	s_mov_b32 m0, s24
	s_nop 0
	global_load_lds_dwordx4 v[220:221], off
	s_setprio 1
	v_mfma_f32_32x32x16_f16 v[48:63], v[244:247], v[236:239], v[48:63]
	v_mfma_f32_32x32x16_f16 v[32:47], v[248:251], v[236:239], v[32:47]
	v_mfma_f32_32x32x16_f16 v[16:31], v[244:247], v[240:243], v[16:31]
	v_mfma_f32_32x32x16_f16 v[0:15], v[248:251], v[240:243], v[0:15]
	s_setprio 0
	v_add_u32_e32 v128, v128, v200
	ds_read_b128 v[236:239], v128
	ds_read_b128 v[240:243], v128 offset:4096
	v_add_u32_e32 v128, v215, v200
	v_add_u32_e32 v215, 0x8000, v218
	ds_read_b128 v[244:247], v128 offset:16384
	ds_read_b128 v[248:251], v128 offset:20480
	v_add_u32_e32 v128, 0xa000, v218
	v_readfirstlane_b32 s24, v215
	v_lshl_add_u64 v[216:217], v[206:207], 0, s[26:27]
	v_lshl_add_u64 v[206:207], v[206:207], 0, s[20:21]
	s_mov_b32 m0, s24
	v_readfirstlane_b32 s24, v128
	global_load_lds_dwordx4 v[206:207], off
	s_mov_b32 m0, s24
	s_nop 0
	global_load_lds_dwordx4 v[216:217], off
	s_setprio 1
	s_waitcnt lgkmcnt(0)
	v_mfma_f32_32x32x16_f16 v[48:63], v[228:231], v[210:213], v[48:63]
	v_mfma_f32_32x32x16_f16 v[32:47], v[232:235], v[210:213], v[32:47]
	v_mfma_f32_32x32x16_f16 v[16:31], v[228:231], v[224:227], v[16:31]
	v_mfma_f32_32x32x16_f16 v[0:15], v[232:235], v[224:227], v[0:15]
	s_setprio 0
	s_setprio 1
	v_mfma_f32_32x32x16_f16 v[48:63], v[244:247], v[236:239], v[48:63]
	v_mfma_f32_32x32x16_f16 v[32:47], v[248:251], v[236:239], v[32:47]
	v_mfma_f32_32x32x16_f16 v[16:31], v[244:247], v[240:243], v[16:31]
	v_mfma_f32_32x32x16_f16 v[0:15], v[248:251], v[240:243], v[0:15]
	s_setprio 0
	s_add_i32 s24, vcc_hi, 1
	s_cmp_lg_u32 vcc_hi, 2
	s_cselect_b32 vcc_hi, s24, 0
	s_add_u32 s80, s80, 0x80
	s_addc_u32 s81, s81, 0
	s_cmpk_eq_i32 s80, 0x300
	s_cbranch_scc0 .LBB0_42
	s_branch .Lstg42_join
; DI void wait_vm0() { asm volatile("s_waitcnt vmcnt(0)" ::: "memory"); }
; template <int MB, bool SWAP>
; DI void gemm_kloop(f32x16 (&acc)[MB][2], const h16* __restrict__ A, int lda, const h16* __restrict__ B, int ldb, int K, char* lds) {
;     ...
;   for (int kt = 0; kt < nk; ++kt) {
;     if (kt + 1 < nk) { if (MB == 2) asm volatile("s_waitcnt vmcnt(6)" ::: "memory"); else asm volatile("s_waitcnt vmcnt(5)" ::: "memory"); }
;     else wait_vm0();
;     __syncthreads();
;     const char* s = lds + cur * STAGE;
;     const int nbuf = cur == 0 ? 2 : cur - 1;
;     const bool more = kt + 2 < nk;
;     half8 af[2][MB], bf[2][2];
; #pragma unroll
;     for (int mb = 0; mb < MB; ++mb) af[0][mb] = *(const half8*)(s + a_rd + mb * 4096 + (((0 + hh) ^ sw) * 16));
; #pragma unroll
;     for (int nb = 0; nb < 2; ++nb) bf[0][nb] = *(const half8*)(s + b_rd + nb * 4096 + (((0 + hh) ^ sw) * 16));
; #pragma unroll
;     for (int ks = 0; ks < 4; ++ks) {
;       if (ks < 3) {
; #pragma unroll
;         for (int mb = 0; mb < MB; ++mb) af[(ks + 1) & 1][mb] = *(const half8*)(s + a_rd + mb * 4096 + (((2 * (ks + 1) + hh) ^ sw) * 16));
; #pragma unroll
;         for (int nb = 0; nb < 2; ++nb) bf[(ks + 1) & 1][nb] = *(const half8*)(s + b_rd + nb * 4096 + (((2 * (ks + 1) + hh) ^ sw) * 16));
;       }
;       if (more) {
;         if (2 * ks < NP) piece(2 * ks, kt + 2, nbuf);
;         if (2 * ks + 1 < NP) piece(2 * ks + 1, kt + 2, nbuf);
;       }
;       __builtin_amdgcn_sched_barrier(0);
;       __builtin_amdgcn_s_setprio(1);
; #pragma unroll
;       for (int mb = 0; mb < MB; ++mb)
; #pragma unroll
;         for (int nb = 0; nb < 2; ++nb)
;           acc[mb][nb] = SWAP ? __builtin_amdgcn_mfma_f32_32x32x16_f16(bf[ks & 1][nb], af[ks & 1][mb], acc[mb][nb], 0, 0, 0)
;                              : __builtin_amdgcn_mfma_f32_32x32x16_f16(af[ks & 1][mb], bf[ks & 1][nb], acc[mb][nb], 0, 0, 0);
;       __builtin_amdgcn_s_setprio(0);
;       __builtin_amdgcn_sched_barrier(0);
;     }
.Lstg42_top:
	s_mul_i32 s24, vcc_hi, 0xc000
	s_add_i32 s25, s24, 0
	v_add_u32_e32 v128, s25, v204
	v_add_u32_e32 v206, v128, v203
	v_add_u32_e32 v215, s25, v199
	s_add_i32 s24, s24, 0xffff4000
	s_waitcnt vmcnt(6)
	s_waitcnt lgkmcnt(0)
	s_barrier
	s_cmp_eq_u32 s80, 0
	s_cbranch_scc1 .Lstg42_skip
	s_setprio 1
	v_mfma_f32_32x32x16_f16 v[48:63], v[228:231], v[210:213], v[48:63]
	v_mfma_f32_32x32x16_f16 v[32:47], v[232:235], v[210:213], v[32:47]
	v_mfma_f32_32x32x16_f16 v[16:31], v[228:231], v[224:227], v[16:31]
	v_mfma_f32_32x32x16_f16 v[0:15], v[232:235], v[224:227], v[0:15]
	v_mfma_f32_32x32x16_f16 v[48:63], v[244:247], v[236:239], v[48:63]
	v_mfma_f32_32x32x16_f16 v[32:47], v[248:251], v[236:239], v[32:47]
	v_mfma_f32_32x32x16_f16 v[16:31], v[244:247], v[240:243], v[16:31]
	v_mfma_f32_32x32x16_f16 v[0:15], v[248:251], v[240:243], v[0:15]
	s_setprio 0
.Lstg42_skip:
	ds_read_b128 v[210:213], v206
	ds_read_b128 v[224:227], v206 offset:4096
	v_add_u32_e32 v206, v215, v203
	s_cmp_lg_u32 vcc_hi, 0
	ds_read_b128 v[228:231], v206 offset:16384
	ds_read_b128 v[232:235], v206 offset:20480
	s_cselect_b32 s24, s24, 0x18000
	v_add_u32_e32 v206, v128, v202
	ds_read_b128 v[236:239], v206
	ds_read_b128 v[240:243], v206 offset:4096
	v_add_u32_e32 v206, v215, v202
	v_add_u32_e32 v218, s24, v205
	ds_read_b128 v[244:247], v206 offset:16384
	ds_read_b128 v[248:251], v206 offset:20480
	v_add_u32_e32 v220, 0x2000, v218
	v_lshl_add_u64 v[206:207], v[186:187], 0, s[80:81]
	v_readfirstlane_b32 s24, v218
	v_lshl_add_u64 v[216:217], v[206:207], 0, s[92:93]
	v_lshl_add_u64 v[206:207], v[206:207], 0, s[30:31]
	s_mov_b32 m0, s24
	v_readfirstlane_b32 s24, v220
	global_load_lds_dwordx4 v[206:207], off
	s_mov_b32 m0, s24
	v_lshl_add_u64 v[206:207], v[188:189], 0, s[80:81]
	global_load_lds_dwordx4 v[216:217], off
	v_lshl_add_u64 v[216:217], v[206:207], 0, s[52:53]
	s_setprio 1
	s_waitcnt lgkmcnt(0)
	v_mfma_f32_32x32x16_f16 v[48:63], v[228:231], v[210:213], v[48:63]
	v_mfma_f32_32x32x16_f16 v[32:47], v[232:235], v[210:213], v[32:47]
	v_mfma_f32_32x32x16_f16 v[16:31], v[228:231], v[224:227], v[16:31]
	v_mfma_f32_32x32x16_f16 v[0:15], v[232:235], v[224:227], v[0:15]
	s_setprio 0
	v_add_u32_e32 v252, 0x4000, v218
	v_add_u32_e32 v220, v128, v201
	v_add_u32_e32 v223, 0x6000, v218
	v_readfirstlane_b32 s24, v252
	ds_read_b128 v[210:213], v220
	ds_read_b128 v[224:227], v220 offset:4096
	v_add_u32_e32 v220, v215, v201
	s_mov_b32 m0, s24
	v_readfirstlane_b32 s24, v223
	ds_read_b128 v[228:231], v220 offset:16384
	ds_read_b128 v[232:235], v220 offset:20480
	v_lshl_add_u64 v[220:221], v[206:207], 0, s[82:83]
	global_load_lds_dwordx4 v[216:217], off
	s_mov_b32 m0, s24
	s_nop 0
	global_load_lds_dwordx4 v[220:221], off
	s_setprio 1
	v_mfma_f32_32x32x16_f16 v[48:63], v[244:247], v[236:239], v[48:63]
	v_mfma_f32_32x32x16_f16 v[32:47], v[248:251], v[236:239], v[32:47]
	v_mfma_f32_32x32x16_f16 v[16:31], v[244:247], v[240:243], v[16:31]
	v_mfma_f32_32x32x16_f16 v[0:15], v[248:251], v[240:243], v[0:15]
	s_setprio 0
	v_add_u32_e32 v128, v128, v200
	ds_read_b128 v[236:239], v128
	ds_read_b128 v[240:243], v128 offset:4096
	v_add_u32_e32 v128, v215, v200
	v_add_u32_e32 v215, 0x8000, v218
	ds_read_b128 v[244:247], v128 offset:16384
	ds_read_b128 v[248:251], v128 offset:20480
	v_add_u32_e32 v128, 0xa000, v218
	v_readfirstlane_b32 s24, v215
	v_lshl_add_u64 v[216:217], v[206:207], 0, s[26:27]
	v_lshl_add_u64 v[206:207], v[206:207], 0, s[20:21]
	s_mov_b32 m0, s24
	v_readfirstlane_b32 s24, v128
	global_load_lds_dwordx4 v[206:207], off
	s_mov_b32 m0, s24
	s_nop 0
	global_load_lds_dwordx4 v[216:217], off
	s_add_i32 s24, vcc_hi, 1
	s_cmp_lg_u32 vcc_hi, 2
	s_cselect_b32 vcc_hi, s24, 0
	s_add_u32 s80, s80, 0x80
	s_addc_u32 s81, s81, 0
	s_cmpk_eq_i32 s80, 0x300
	s_cbranch_scc0 .Lstg42_top
	s_waitcnt lgkmcnt(0)
	s_setprio 1
	v_mfma_f32_32x32x16_f16 v[48:63], v[228:231], v[210:213], v[48:63]
	v_mfma_f32_32x32x16_f16 v[32:47], v[232:235], v[210:213], v[32:47]
	v_mfma_f32_32x32x16_f16 v[16:31], v[228:231], v[224:227], v[16:31]
	v_mfma_f32_32x32x16_f16 v[0:15], v[232:235], v[224:227], v[0:15]
	v_mfma_f32_32x32x16_f16 v[48:63], v[244:247], v[236:239], v[48:63]
	v_mfma_f32_32x32x16_f16 v[32:47], v[248:251], v[236:239], v[32:47]
	v_mfma_f32_32x32x16_f16 v[16:31], v[244:247], v[240:243], v[16:31]
	v_mfma_f32_32x32x16_f16 v[0:15], v[248:251], v[240:243], v[0:15]
	s_setprio 0
; DI float sigmoid_f(float x) { return 1.f / (1.f + __expf(-x)); }
; template <int MB>
; DI void merge_tile(const Params& P, int layer, size_t row0, int nt, char* smem) {
;     ...
; #pragma unroll
;     for (int mb = 0; mb < MB; ++mb)
; #pragma unroll
;       for (int nb = 0; nb < 2; ++nb)
; #pragma unroll
;         for (int v = 0; v < 16; ++v) gpk[mb][nb][v >> 3][v & 7] = (h16)sigmoid_f(pa2[mb][nb][v]);
.Lstg42_join:
	v_mul_f32_e32 v112, 0xbfb8aa3b, v112
	v_exp_f32_e32 v237, v112
	v_mul_f32_e32 v113, 0xbfb8aa3b, v113
	v_mul_f32_e32 v120, 0xbfb8aa3b, v120
	v_mul_f32_e32 v127, 0xbfb8aa3b, v127
	v_mul_f32_e32 v128, 0xbfb8aa3b, v116
	v_mul_f32_e32 v187, 0xbfb8aa3b, v118
	v_exp_f32_e32 v118, v113
	v_exp_f32_e32 v113, v120
	v_exp_f32_e32 v120, v127
	v_add_f32_e32 v127, 1.0, v237
	v_mul_f32_e32 v114, 0xbfb8aa3b, v114
	v_mul_f32_e32 v186, 0xbfb8aa3b, v117
	v_exp_f32_e32 v117, v128
	v_div_scale_f32 v128, s[24:25], v127, v127, 1.0
	v_mul_f32_e32 v188, 0xbfb8aa3b, v119
	v_exp_f32_e32 v119, v114
	v_exp_f32_e32 v114, v186
	v_rcp_f32_e32 v186, v128
	v_mul_f32_e32 v115, 0xbfb8aa3b, v115
	v_exp_f32_e32 v116, v115
	v_exp_f32_e32 v115, v187
	v_fma_f32 v187, -v128, v186, 1.0
	v_fmac_f32_e32 v186, v187, v186
	v_div_scale_f32 v187, vcc, 1.0, v127, 1.0
	v_mul_f32_e32 v100, 0xbfb8aa3b, v100
	v_mul_f32_e32 v101, 0xbfb8aa3b, v101
	v_mul_f32_e32 v189, 0xbfb8aa3b, v102
	v_exp_f32_e32 v112, v188
	v_mul_f32_e32 v188, v187, v186
	v_mul_f32_e32 v205, 0xbfb8aa3b, v103
	v_exp_f32_e32 v103, v100
	v_exp_f32_e32 v100, v101
	v_exp_f32_e32 v101, v189
	v_fma_f32 v189, -v128, v188, v187
	v_fmac_f32_e32 v188, v189, v186
	v_fma_f32 v128, -v128, v188, v187
	v_add_f32_e32 v120, 1.0, v120
	v_div_fmas_f32 v128, v128, v186, v188
	v_div_fixup_f32 v127, v128, v127, 1.0
	v_div_scale_f32 v128, s[24:25], v120, v120, 1.0
	v_rcp_f32_e32 v186, v128
	v_mul_f32_e32 v121, 0xbfb8aa3b, v121
	v_mul_f32_e32 v96, 0xbfb8aa3b, v96
	v_mul_f32_e32 v215, 0xbfb8aa3b, v110
	v_fma_f32 v187, -v128, v186, 1.0
	v_fmac_f32_e32 v186, v187, v186
	v_div_scale_f32 v187, vcc, 1.0, v120, 1.0
	v_exp_f32_e32 v110, v121
	v_exp_f32_e32 v121, v96
	v_mul_f32_e32 v188, v187, v186
	v_fma_f32 v189, -v128, v188, v187
	v_fmac_f32_e32 v188, v189, v186
	v_fma_f32 v128, -v128, v188, v187
	v_add_f32_e32 v121, 1.0, v121
	v_div_fmas_f32 v128, v128, v186, v188
	v_div_fixup_f32 v120, v128, v120, 1.0
	v_div_scale_f32 v128, s[24:25], v121, v121, 1.0
	v_rcp_f32_e32 v186, v128
	v_mul_f32_e32 v122, 0xbfb8aa3b, v122
	v_mul_f32_e32 v216, 0xbfb8aa3b, v111
	v_exp_f32_e32 v111, v122
	v_fma_f32 v187, -v128, v186, 1.0
	v_fmac_f32_e32 v186, v187, v186
	v_div_scale_f32 v187, vcc, 1.0, v121, 1.0
	v_exp_f32_e32 v122, v216
	v_mul_f32_e32 v188, v187, v186
	v_fma_f32 v189, -v128, v188, v187
	v_fmac_f32_e32 v188, v189, v186
	v_fma_f32 v128, -v128, v188, v187
	v_add_f32_e32 v122, 1.0, v122
	v_div_fmas_f32 v128, v128, v186, v188
	v_div_fixup_f32 v121, v128, v121, 1.0
	v_div_scale_f32 v128, s[24:25], v122, v122, 1.0
	v_rcp_f32_e32 v186, v128
	v_mul_f32_e32 v123, 0xbfb8aa3b, v123
	v_mul_f32_e32 v80, 0xbfb8aa3b, v80
	v_mul_f32_e32 v212, 0xbfb8aa3b, v108
	v_fma_f32 v187, -v128, v186, 1.0
	v_fmac_f32_e32 v186, v187, v186
	v_div_scale_f32 v187, vcc, 1.0, v122, 1.0
	v_exp_f32_e32 v108, v123
	v_exp_f32_e32 v123, v80
	v_mul_f32_e32 v188, v187, v186
	v_fma_f32 v189, -v128, v188, v187
	v_fmac_f32_e32 v188, v189, v186
	v_fma_f32 v128, -v128, v188, v187
	v_add_f32_e32 v123, 1.0, v123
	v_div_fmas_f32 v128, v128, v186, v188
	v_div_fixup_f32 v122, v128, v122, 1.0
	v_div_scale_f32 v128, s[24:25], v123, v123, 1.0
	v_rcp_f32_e32 v186, v128
	v_mul_f32_e32 v124, 0xbfb8aa3b, v124
	v_mul_f32_e32 v228, 0xbfb8aa3b, v95
	v_mul_f32_e32 v213, 0xbfb8aa3b, v109
	v_fma_f32 v187, -v128, v186, 1.0
	v_fmac_f32_e32 v186, v187, v186
	v_div_scale_f32 v187, vcc, 1.0, v123, 1.0
	v_exp_f32_e32 v109, v124
	v_exp_f32_e32 v124, v228
	v_mul_f32_e32 v188, v187, v186
	v_fma_f32 v189, -v128, v188, v187
	v_fmac_f32_e32 v188, v189, v186
	v_fma_f32 v128, -v128, v188, v187
	v_add_f32_e32 v124, 1.0, v124
	v_div_fmas_f32 v128, v128, v186, v188
	v_div_fixup_f32 v128, v128, v123, 1.0
	v_div_scale_f32 v123, s[24:25], v124, v124, 1.0
	v_rcp_f32_e32 v186, v123
	v_mul_f32_e32 v125, 0xbfb8aa3b, v125
	v_mul_f32_e32 v64, 0xbfb8aa3b, v64
	v_mul_f32_e32 v210, 0xbfb8aa3b, v106
	v_fma_f32 v187, -v123, v186, 1.0
	v_fmac_f32_e32 v186, v187, v186
	v_div_scale_f32 v187, vcc, 1.0, v124, 1.0
	v_exp_f32_e32 v106, v125
	v_exp_f32_e32 v125, v64
	v_mul_f32_e32 v188, v187, v186
	v_fma_f32 v189, -v123, v188, v187
	v_fmac_f32_e32 v188, v189, v186
	v_fma_f32 v123, -v123, v188, v187
	v_add_f32_e32 v125, 1.0, v125
	v_div_fmas_f32 v123, v123, v186, v188
	v_div_fixup_f32 v186, v123, v124, 1.0
	v_div_scale_f32 v123, s[24:25], v125, v125, 1.0
	v_rcp_f32_e32 v124, v123
	v_mul_f32_e32 v126, 0xbfb8aa3b, v126
	v_mul_f32_e32 v236, 0xbfb8aa3b, v79
	v_mul_f32_e32 v211, 0xbfb8aa3b, v107
	v_fma_f32 v187, -v123, v124, 1.0
	v_fmac_f32_e32 v124, v187, v124
	v_div_scale_f32 v187, vcc, 1.0, v125, 1.0
	v_exp_f32_e32 v107, v126
	v_exp_f32_e32 v126, v236
	v_mul_f32_e32 v188, v187, v124
	v_fma_f32 v189, -v123, v188, v187
	v_fmac_f32_e32 v188, v189, v124
	v_fma_f32 v123, -v123, v188, v187
	v_add_f32_e32 v126, 1.0, v126
	v_div_fmas_f32 v123, v123, v124, v188
	v_div_fixup_f32 v187, v123, v125, 1.0
	v_div_scale_f32 v123, s[24:25], v126, v126, 1.0
	v_rcp_f32_e32 v124, v123
	v_mul_f32_e32 v217, 0xbfb8aa3b, v86
	v_add_u32_e32 v216, 0, v199
	v_mul_f32_e32 v97, 0xbfb8aa3b, v97
	v_fma_f32 v125, -v123, v124, 1.0
	v_fmac_f32_e32 v124, v125, v124
	v_div_scale_f32 v125, vcc, 1.0, v126, 1.0
	v_mul_f32_e32 v188, v125, v124
	v_fma_f32 v189, -v123, v188, v125
	v_fmac_f32_e32 v188, v189, v124
	v_fma_f32 v123, -v123, v188, v125
	v_div_fmas_f32 v123, v123, v124, v188
	v_cvt_f16_f32_e32 v124, v128
	v_add_u32_e32 v128, 0, v204
	v_mul_f32_e32 v98, 0xbfb8aa3b, v98
	v_mul_f32_e32 v99, 0xbfb8aa3b, v99
	v_mul_f32_e32 v206, 0xbfb8aa3b, v104
	v_mul_f32_e32 v207, 0xbfb8aa3b, v105
	v_mul_f32_e32 v81, 0xbfb8aa3b, v81
	v_mul_f32_e32 v84, 0xbfb8aa3b, v84
	v_mul_f32_e32 v218, 0xbfb8aa3b, v87
; DI float sigmoid_f(float x) { return 1.f / (1.f + __expf(-x)); }
; template <int MB, bool SWAP>
; DI void gemm_kloop(f32x16 (&acc)[MB][2], const h16* __restrict__ A, int lda, const h16* __restrict__ B, int ldb, int K, char* lds) {
;     ...
;     for (int mb = 0; mb < MB; ++mb) af[0][mb] = *(const half8*)(s + a_rd + mb * 4096 + (((0 + hh) ^ sw) * 16));
; #pragma unroll
;     for (int nb = 0; nb < 2; ++nb) bf[0][nb] = *(const half8*)(s + b_rd + nb * 4096 + (((0 + hh) ^ sw) * 16));
; #pragma unroll
;     for (int ks = 0; ks < 4; ++ks) {
;       if (ks < 3) {
; #pragma unroll
;         for (int mb = 0; mb < MB; ++mb) af[(ks + 1) & 1][mb] = *(const half8*)(s + a_rd + mb * 4096 + (((2 * (ks + 1) + hh) ^ sw) * 16));
; #pragma unroll
;         for (int nb = 0; nb < 2; ++nb) bf[(ks + 1) & 1][nb] = *(const half8*)(s + b_rd + nb * 4096 + (((2 * (ks + 1) + hh) ^ sw) * 16));
;       }
;       if (more) {
;         if (2 * ks < NP) piece(2 * ks, kt + 2, nbuf);
;         if (2 * ks + 1 < NP) piece(2 * ks + 1, kt + 2, nbuf);
;       }
;       __builtin_amdgcn_sched_barrier(0);
;       __builtin_amdgcn_s_setprio(1);
; #pragma unroll
;       for (int mb = 0; mb < MB; ++mb)
; #pragma unroll
;         for (int nb = 0; nb < 2; ++nb)
;           acc[mb][nb] = SWAP ? __builtin_amdgcn_mfma_f32_32x32x16_f16(bf[ks & 1][nb], af[ks & 1][mb], acc[mb][nb], 0, 0, 0)
;                              : __builtin_amdgcn_mfma_f32_32x32x16_f16(af[ks & 1][mb], bf[ks & 1][nb], acc[mb][nb], 0, 0, 0);
;       __builtin_amdgcn_s_setprio(0);
;       __builtin_amdgcn_sched_barrier(0);
;     }
; template <int MB>
; DI void merge_tile(const Params& P, int layer, size_t row0, int nt, char* smem) {
;     ...
; #pragma unroll
;     for (int mb = 0; mb < MB; ++mb)
; #pragma unroll
;       for (int nb = 0; nb < 2; ++nb)
; #pragma unroll
;         for (int v = 0; v < 16; ++v) gpk[mb][nb][v >> 3][v & 7] = (h16)sigmoid_f(pa2[mb][nb][v]);
	v_mul_f32_e32 v224, 0xbfb8aa3b, v91
	v_mul_f32_e32 v225, 0xbfb8aa3b, v92
	v_mul_f32_e32 v226, 0xbfb8aa3b, v93
	v_mul_f32_e32 v227, 0xbfb8aa3b, v94
	v_exp_f32_e32 v93, v215
	v_exp_f32_e32 v87, v217
	v_div_fixup_f32 v188, v123, v126, 1.0
	v_add_u32_e32 v215, v128, v203
	v_add_u32_e32 v217, v216, v203
	v_mul_f32_e32 v221, 0xbfb8aa3b, v89
	v_mul_f32_e32 v223, 0xbfb8aa3b, v90
	v_mul_f32_e32 v65, 0xbfb8aa3b, v65
	v_mul_f32_e32 v66, 0xbfb8aa3b, v66
	v_mul_f32_e32 v67, 0xbfb8aa3b, v67
	v_mul_f32_e32 v68, 0xbfb8aa3b, v68
	v_mul_f32_e32 v69, 0xbfb8aa3b, v69
	v_mul_f32_e32 v70, 0xbfb8aa3b, v70
	v_mul_f32_e32 v71, 0xbfb8aa3b, v71
	v_mul_f32_e32 v229, 0xbfb8aa3b, v72
	v_mul_f32_e32 v230, 0xbfb8aa3b, v73
	v_mul_f32_e32 v231, 0xbfb8aa3b, v74
	v_mul_f32_e32 v232, 0xbfb8aa3b, v75
	v_mul_f32_e32 v233, 0xbfb8aa3b, v76
	v_mul_f32_e32 v234, 0xbfb8aa3b, v77
	v_mul_f32_e32 v235, 0xbfb8aa3b, v78
	v_exp_f32_e32 v104, v97
	v_exp_f32_e32 v105, v98
	v_exp_f32_e32 v102, v99
	v_exp_f32_e32 v98, v205
	v_exp_f32_e32 v99, v206
	v_exp_f32_e32 v96, v207
	v_exp_f32_e32 v97, v210
	v_exp_f32_e32 v94, v211
	v_exp_f32_e32 v95, v212
	v_exp_f32_e32 v92, v213
	v_exp_f32_e32 v90, v81
	v_exp_f32_e32 v89, v84
	v_exp_f32_e32 v84, v218
	v_exp_f32_e32 v80, v224
	v_exp_f32_e32 v81, v225
	v_exp_f32_e32 v78, v226
	v_exp_f32_e32 v79, v227
	v_cvt_f16_f32_e32 v125, v120
	v_cvt_f16_f32_e32 v126, v121
	v_cvt_f16_f32_e32 v123, v122
	v_cvt_f16_f32_e32 v121, v186
	v_cvt_f16_f32_e32 v122, v187
	v_cvt_f16_f32_e32 v120, v188
	s_waitcnt vmcnt(6)
	s_waitcnt lgkmcnt(0)
	s_barrier
	ds_read_b128 v[186:189], v215
	ds_read_b128 v[204:207], v215 offset:4096
	ds_read_b128 v[210:213], v217 offset:16384
	ds_read_b128 v[224:227], v217 offset:20480
	v_add_u32_e32 v217, v128, v202
	v_add_u32_e32 v218, v216, v202
	v_exp_f32_e32 v76, v65
	v_exp_f32_e32 v77, v66
	v_exp_f32_e32 v74, v67
	v_exp_f32_e32 v75, v68
	v_exp_f32_e32 v72, v69
	v_exp_f32_e32 v73, v70
	v_exp_f32_e32 v70, v71
	v_exp_f32_e32 v71, v229
	v_exp_f32_e32 v68, v230
	v_exp_f32_e32 v69, v231
	v_exp_f32_e32 v66, v232
	v_exp_f32_e32 v67, v233
	v_exp_f32_e32 v64, v234
	v_exp_f32_e32 v65, v235
	ds_read_b128 v[228:231], v217
	ds_read_b128 v[232:235], v217 offset:4096
	ds_read_b128 v[236:239], v218 offset:16384
	ds_read_b128 v[240:243], v218 offset:20480
	v_mul_f32_e32 v82, 0xbfb8aa3b, v82
	v_mul_f32_e32 v83, 0xbfb8aa3b, v83
	v_mul_f32_e32 v85, 0xbfb8aa3b, v85
	v_mul_f32_e32 v220, 0xbfb8aa3b, v88
	v_exp_f32_e32 v91, v82
	v_exp_f32_e32 v88, v83
	v_exp_f32_e32 v86, v85
	v_exp_f32_e32 v85, v220
	v_exp_f32_e32 v82, v221
	v_exp_f32_e32 v83, v223
	v_cvt_f16_f32_e32 v127, v127
	s_setprio 1
	s_waitcnt lgkmcnt(5)
	v_mfma_f32_32x32x16_f16 v[48:63], v[210:213], v[186:189], v[48:63]
	s_waitcnt lgkmcnt(4)
	v_mfma_f32_32x32x16_f16 v[32:47], v[224:227], v[186:189], v[32:47]
	v_mfma_f32_32x32x16_f16 v[16:31], v[210:213], v[204:207], v[16:31]
	v_mfma_f32_32x32x16_f16 v[0:15], v[224:227], v[204:207], v[0:15]
	s_setprio 0
	v_add_u32_e32 v218, v128, v201
	v_add_u32_e32 v220, v216, v201
	ds_read_b128 v[186:189], v218
	ds_read_b128 v[204:207], v218 offset:4096
	ds_read_b128 v[210:213], v220 offset:16384
	ds_read_b128 v[224:227], v220 offset:20480
	s_setprio 1
	s_waitcnt lgkmcnt(5)
	v_mfma_f32_32x32x16_f16 v[48:63], v[236:239], v[228:231], v[48:63]
	s_waitcnt lgkmcnt(4)
	v_mfma_f32_32x32x16_f16 v[32:47], v[240:243], v[228:231], v[32:47]
	v_mfma_f32_32x32x16_f16 v[16:31], v[236:239], v[232:235], v[16:31]
	v_mfma_f32_32x32x16_f16 v[0:15], v[240:243], v[232:235], v[0:15]
	s_setprio 0
	v_add_u32_e32 v128, v128, v200
	v_add_u32_e32 v216, v216, v200
	ds_read_b128 v[228:231], v128
	ds_read_b128 v[232:235], v128 offset:4096
	ds_read_b128 v[236:239], v216 offset:16384
	ds_read_b128 v[240:243], v216 offset:20480
	s_setprio 1
	s_waitcnt lgkmcnt(5)
	v_mfma_f32_32x32x16_f16 v[48:63], v[210:213], v[186:189], v[48:63]
	s_waitcnt lgkmcnt(4)
	v_mfma_f32_32x32x16_f16 v[32:47], v[224:227], v[186:189], v[32:47]
	v_mfma_f32_32x32x16_f16 v[16:31], v[210:213], v[204:207], v[16:31]
	v_mfma_f32_32x32x16_f16 v[0:15], v[224:227], v[204:207], v[0:15]
	s_setprio 0
	s_setprio 1
	s_waitcnt lgkmcnt(1)
	v_mfma_f32_32x32x16_f16 v[48:63], v[236:239], v[228:231], v[48:63]
	s_waitcnt lgkmcnt(0)
	v_mfma_f32_32x32x16_f16 v[32:47], v[240:243], v[228:231], v[32:47]
	v_mfma_f32_32x32x16_f16 v[16:31], v[236:239], v[232:235], v[16:31]
	v_mfma_f32_32x32x16_f16 v[0:15], v[240:243], v[232:235], v[0:15]
	s_setprio 0
	s_add_i32 s24, 0, 0xc000
	v_add3_u32 v203, s24, v203, v199
	s_waitcnt vmcnt(0)
	s_barrier
; template <int MB, bool SWAP>
; DI void gemm_kloop(f32x16 (&acc)[MB][2], const h16* __restrict__ A, int lda, const h16* __restrict__ B, int ldb, int K, char* lds) {
;     ...
;     for (int mb = 0; mb < MB; ++mb) af[0][mb] = *(const half8*)(s + a_rd + mb * 4096 + (((0 + hh) ^ sw) * 16));
; #pragma unroll
;     for (int nb = 0; nb < 2; ++nb) bf[0][nb] = *(const half8*)(s + b_rd + nb * 4096 + (((0 + hh) ^ sw) * 16));
; #pragma unroll
;     for (int ks = 0; ks < 4; ++ks) {
;       if (ks < 3) {
; #pragma unroll
;         for (int mb = 0; mb < MB; ++mb) af[(ks + 1) & 1][mb] = *(const half8*)(s + a_rd + mb * 4096 + (((2 * (ks + 1) + hh) ^ sw) * 16));
; #pragma unroll
;         for (int nb = 0; nb < 2; ++nb) bf[(ks + 1) & 1][nb] = *(const half8*)(s + b_rd + nb * 4096 + (((2 * (ks + 1) + hh) ^ sw) * 16));
;       }
;       if (more) {
;         if (2 * ks < NP) piece(2 * ks, kt + 2, nbuf);
;         if (2 * ks + 1 < NP) piece(2 * ks + 1, kt + 2, nbuf);
;       }
;       __builtin_amdgcn_sched_barrier(0);
;       __builtin_amdgcn_s_setprio(1);
; #pragma unroll
;       for (int mb = 0; mb < MB; ++mb)
; #pragma unroll
;         for (int nb = 0; nb < 2; ++nb)
;           acc[mb][nb] = SWAP ? __builtin_amdgcn_mfma_f32_32x32x16_f16(bf[ks & 1][nb], af[ks & 1][mb], acc[mb][nb], 0, 0, 0)
;                              : __builtin_amdgcn_mfma_f32_32x32x16_f16(af[ks & 1][mb], bf[ks & 1][nb], acc[mb][nb], 0, 0, 0);
;       __builtin_amdgcn_s_setprio(0);
;       __builtin_amdgcn_sched_barrier(0);
;     }
; template <int MB>
; DI void merge_tile(const Params& P, int layer, size_t row0, int nt, char* smem) {
;     ...
; #pragma unroll
;     for (int mb = 0; mb < MB; ++mb)
; #pragma unroll
;       for (int nb = 0; nb < 2; ++nb)
; #pragma unroll
;         for (int v = 0; v < 16; ++v) macc[mb][nb][v] += (float)gpk[mb][nb][v >> 3][v & 7] * pa2[mb][nb][v];
	ds_read_b128 v[186:189], v215 offset:49152
	ds_read_b128 v[204:207], v215 offset:53248
	ds_read_b128 v[210:213], v203 offset:16384
	ds_read_b128 v[224:227], v203 offset:20480
	ds_read_b128 v[228:231], v217 offset:49152
	ds_read_b128 v[232:235], v217 offset:53248
	v_add3_u32 v202, s24, v202, v199
	ds_read_b128 v[236:239], v202 offset:16384
	ds_read_b128 v[240:243], v202 offset:20480
	s_setprio 1
	s_waitcnt lgkmcnt(5)
	v_mfma_f32_32x32x16_f16 v[48:63], v[210:213], v[186:189], v[48:63]
	s_waitcnt lgkmcnt(4)
	v_mfma_f32_32x32x16_f16 v[32:47], v[224:227], v[186:189], v[32:47]
	v_mfma_f32_32x32x16_f16 v[16:31], v[210:213], v[204:207], v[16:31]
	v_mfma_f32_32x32x16_f16 v[0:15], v[224:227], v[204:207], v[0:15]
	s_setprio 0
	v_add3_u32 v201, s24, v201, v199
	ds_read_b128 v[186:189], v218 offset:49152
	ds_read_b128 v[202:205], v218 offset:53248
	ds_read_b128 v[210:213], v201 offset:16384
	ds_read_b128 v[224:227], v201 offset:20480
	s_setprio 1
	s_waitcnt lgkmcnt(5)
	v_mfma_f32_32x32x16_f16 v[48:63], v[236:239], v[228:231], v[48:63]
	s_waitcnt lgkmcnt(4)
	v_mfma_f32_32x32x16_f16 v[32:47], v[240:243], v[228:231], v[32:47]
	v_mfma_f32_32x32x16_f16 v[16:31], v[236:239], v[232:235], v[16:31]
	v_mfma_f32_32x32x16_f16 v[0:15], v[240:243], v[232:235], v[0:15]
	s_setprio 0
	ds_read_b128 v[228:231], v128 offset:49152
	ds_read_b128 v[232:235], v128 offset:53248
	v_add3_u32 v128, s24, v200, v199
	ds_read_b128 v[236:239], v128 offset:16384
	ds_read_b128 v[240:243], v128 offset:20480
	s_setprio 1
	s_waitcnt lgkmcnt(5)
	v_mfma_f32_32x32x16_f16 v[48:63], v[210:213], v[186:189], v[48:63]
	s_waitcnt lgkmcnt(4)
	v_mfma_f32_32x32x16_f16 v[32:47], v[224:227], v[186:189], v[32:47]
	v_mfma_f32_32x32x16_f16 v[16:31], v[210:213], v[202:205], v[16:31]
	v_mfma_f32_32x32x16_f16 v[0:15], v[224:227], v[202:205], v[0:15]
	s_setprio 0
	s_setprio 1
	s_waitcnt lgkmcnt(1)
	v_mfma_f32_32x32x16_f16 v[48:63], v[236:239], v[228:231], v[48:63]
	s_waitcnt lgkmcnt(0)
	v_mfma_f32_32x32x16_f16 v[32:47], v[240:243], v[228:231], v[32:47]
	v_mfma_f32_32x32x16_f16 v[16:31], v[236:239], v[232:235], v[16:31]
	v_mfma_f32_32x32x16_f16 v[0:15], v[240:243], v[232:235], v[0:15]
	s_setprio 0
	v_add_f32_e64 v118, v118, 1.0
	v_add_f32_e64 v119, v119, 1.0
	s_nop 4
	v_fma_mix_f32 v198, v48, v127, v198 op_sel_hi:[0,1,0]
	v_div_scale_f32 v48, s[24:25], v119, v119, 1.0
	v_rcp_f32_e32 v127, v48
	v_fma_mix_f32 v195, v32, v126, v195 op_sel_hi:[0,1,0]
	v_fma_mix_f32 v193, v16, v124, v193 op_sel_hi:[0,1,0]
	v_fma_mix_f32 v191, v0, v122, v191 op_sel_hi:[0,1,0]
	v_fma_f32 v128, -v48, v127, 1.0
	v_fmac_f32_e32 v127, v128, v127
	v_div_scale_f32 v128, vcc, 1.0, v119, 1.0
	v_mul_f32_e32 v186, v128, v127
	v_fma_f32 v187, -v48, v186, v128
	v_fmac_f32_e32 v186, v187, v127
	v_fma_f32 v48, -v48, v186, v128
	v_div_fmas_f32 v48, v48, v127, v186
	v_div_fixup_f32 v48, v48, v119, 1.0
	v_div_scale_f32 v119, s[24:25], v118, v118, 1.0
	v_rcp_f32_e32 v127, v119
	s_add_i32 s45, s45, 1
	s_add_u32 s42, s42, 0x220000
	s_addc_u32 s43, s43, 0
	v_fma_f32 v128, -v119, v127, 1.0
	v_fmac_f32_e32 v127, v128, v127
	v_div_scale_f32 v128, vcc, 1.0, v118, 1.0
	v_mul_f32_e32 v186, v128, v127
	v_fma_f32 v187, -v119, v186, v128
	v_fmac_f32_e32 v186, v187, v127
	v_fma_f32 v119, -v119, v186, v128
	v_div_fmas_f32 v119, v119, v127, v186
	v_div_fixup_f32 v118, v119, v118, 1.0
	v_cvt_pk_f16_f32 v48, v118, v48
	v_cvt_f32_f16_e32 v118, v48
	v_cvt_f32_f16_sdwa v119, v48 dst_sel:DWORD dst_unused:UNUSED_PAD src0_sel:WORD_1
	v_mov_b32_e32 v48, v49
	v_mov_b32_e32 v49, v50
	s_add_u32 s40, s40, 0x120000
	v_pk_fma_f32 v[184:185], v[48:49], v[118:119], v[184:185]
	v_pk_add_f32 v[48:49], v[116:117], 1.0 op_sel_hi:[1,0]
	s_addc_u32 s41, s41, 0
	v_div_scale_f32 v50, s[24:25], v49, v49, 1.0
	v_rcp_f32_e32 v116, v50
	v_fma_mix_f32 v196, v63, v125, v196 op_sel_hi:[0,1,0]
	v_fma_mix_f32 v194, v47, v123, v194 op_sel_hi:[0,1,0]
	v_fma_mix_f32 v192, v31, v121, v192 op_sel_hi:[0,1,0]
	v_fma_f32 v117, -v50, v116, 1.0
	v_fmac_f32_e32 v116, v117, v116
	v_div_scale_f32 v117, vcc, 1.0, v49, 1.0
	v_mul_f32_e32 v118, v117, v116
	v_fma_f32 v119, -v50, v118, v117
	v_fmac_f32_e32 v118, v119, v116
	v_fma_f32 v50, -v50, v118, v117
	v_div_fmas_f32 v50, v50, v116, v118
	v_div_fixup_f32 v49, v50, v49, 1.0
	v_div_scale_f32 v50, s[24:25], v48, v48, 1.0
	v_rcp_f32_e32 v116, v50
	v_fma_mix_f32 v190, v15, v120, v190 op_sel_hi:[0,1,0]
	s_cmp_eq_u32 s45, 3
	v_fma_f32 v117, -v50, v116, 1.0
	v_fmac_f32_e32 v116, v117, v116
	v_div_scale_f32 v117, vcc, 1.0, v48, 1.0
	v_mul_f32_e32 v118, v117, v116
	v_fma_f32 v119, -v50, v118, v117
	v_fmac_f32_e32 v118, v119, v116
	v_fma_f32 v50, -v50, v118, v117
	v_div_fmas_f32 v50, v50, v116, v118
	v_div_fixup_f32 v48, v50, v48, 1.0
	v_cvt_pk_f16_f32 v49, v48, v49
	v_cvt_f32_f16_e32 v48, v49
	v_cvt_f32_f16_sdwa v49, v49 dst_sel:DWORD dst_unused:UNUSED_PAD src0_sel:WORD_1
	v_mov_b32_e32 v50, v51
	v_mov_b32_e32 v51, v52
	s_barrier
; DI float sigmoid_f(float x) { return 1.f / (1.f + __expf(-x)); }
; template <int MB>
; DI void merge_tile(const Params& P, int layer, size_t row0, int nt, char* smem) {
;     ...
; #pragma unroll
;     for (int mb = 0; mb < MB; ++mb)
; #pragma unroll
;       for (int nb = 0; nb < 2; ++nb)
; #pragma unroll
;         for (int v = 0; v < 16; ++v) gpk[mb][nb][v >> 3][v & 7] = (h16)sigmoid_f(pa2[mb][nb][v]);
;     zero_acc<MB>(pa2);
;     gemm_kloop<MB, true>(pa2, yn + row0 * LDY, LDY, wbrT + (size_t)(n * 1024 + nt * 256) * LDY, LDY, WB, smem);
; #pragma unroll
;     for (int mb = 0; mb < MB; ++mb)
; #pragma unroll
;       for (int nb = 0; nb < 2; ++nb)
; #pragma unroll
;         for (int v = 0; v < 16; ++v) macc[mb][nb][v] += (float)gpk[mb][nb][v >> 3][v & 7] * pa2[mb][nb][v];
	v_pk_fma_f32 v[182:183], v[50:51], v[48:49], v[182:183]
	v_pk_add_f32 v[48:49], v[114:115], 1.0 op_sel_hi:[1,0]
	s_nop 0
	v_div_scale_f32 v50, s[24:25], v49, v49, 1.0
	v_rcp_f32_e32 v51, v50
	s_nop 0
	v_fma_f32 v52, -v50, v51, 1.0
	v_fmac_f32_e32 v51, v52, v51
	v_div_scale_f32 v52, vcc, 1.0, v49, 1.0
	v_mul_f32_e32 v114, v52, v51
	v_fma_f32 v115, -v50, v114, v52
	v_fmac_f32_e32 v114, v115, v51
	v_fma_f32 v50, -v50, v114, v52
	v_div_fmas_f32 v50, v50, v51, v114
	v_div_fixup_f32 v49, v50, v49, 1.0
	v_div_scale_f32 v50, s[24:25], v48, v48, 1.0
	v_rcp_f32_e32 v51, v50
	s_nop 0
	v_fma_f32 v52, -v50, v51, 1.0
	v_fmac_f32_e32 v51, v52, v51
	v_div_scale_f32 v52, vcc, 1.0, v48, 1.0
	v_mul_f32_e32 v114, v52, v51
	v_fma_f32 v115, -v50, v114, v52
	v_fmac_f32_e32 v114, v115, v51
	v_fma_f32 v50, -v50, v114, v52
	v_div_fmas_f32 v50, v50, v51, v114
	v_div_fixup_f32 v48, v50, v48, 1.0
	v_cvt_pk_f16_f32 v49, v48, v49
	v_cvt_f32_f16_e32 v48, v49
	v_cvt_f32_f16_sdwa v49, v49 dst_sel:DWORD dst_unused:UNUSED_PAD src0_sel:WORD_1
	v_mov_b32_e32 v50, v53
	v_mov_b32_e32 v51, v54
	v_pk_fma_f32 v[180:181], v[50:51], v[48:49], v[180:181]
	v_pk_add_f32 v[48:49], v[112:113], 1.0 op_sel_hi:[1,0]
	s_nop 0
	v_div_scale_f32 v50, s[24:25], v49, v49, 1.0
	v_rcp_f32_e32 v51, v50
	s_nop 0
	v_fma_f32 v52, -v50, v51, 1.0
	v_fmac_f32_e32 v51, v52, v51
	v_div_scale_f32 v52, vcc, 1.0, v49, 1.0
	v_mul_f32_e32 v53, v52, v51
	v_fma_f32 v54, -v50, v53, v52
	v_fmac_f32_e32 v53, v54, v51
	v_fma_f32 v50, -v50, v53, v52
	v_div_fmas_f32 v50, v50, v51, v53
	v_div_fixup_f32 v49, v50, v49, 1.0
	v_div_scale_f32 v50, s[24:25], v48, v48, 1.0
	v_rcp_f32_e32 v51, v50
	s_nop 0
	v_fma_f32 v52, -v50, v51, 1.0
	v_fmac_f32_e32 v51, v52, v51
	v_div_scale_f32 v52, vcc, 1.0, v48, 1.0
	v_mul_f32_e32 v53, v52, v51
	v_fma_f32 v54, -v50, v53, v52
	v_fmac_f32_e32 v53, v54, v51
	v_fma_f32 v50, -v50, v53, v52
	v_div_fmas_f32 v50, v50, v51, v53
	v_div_fixup_f32 v48, v50, v48, 1.0
	v_cvt_pk_f16_f32 v49, v48, v49
	v_cvt_f32_f16_e32 v48, v49
	v_cvt_f32_f16_sdwa v49, v49 dst_sel:DWORD dst_unused:UNUSED_PAD src0_sel:WORD_1
	v_mov_b32_e32 v50, v55
	v_mov_b32_e32 v51, v56
	v_pk_fma_f32 v[178:179], v[50:51], v[48:49], v[178:179]
	v_pk_add_f32 v[48:49], v[110:111], 1.0 op_sel_hi:[1,0]
	s_nop 0
	v_div_scale_f32 v50, s[24:25], v49, v49, 1.0
	v_rcp_f32_e32 v51, v50
	s_nop 0
	v_fma_f32 v52, -v50, v51, 1.0
	v_fmac_f32_e32 v51, v52, v51
	v_div_scale_f32 v52, vcc, 1.0, v49, 1.0
	v_mul_f32_e32 v53, v52, v51
	v_fma_f32 v54, -v50, v53, v52
	v_fmac_f32_e32 v53, v54, v51
	v_fma_f32 v50, -v50, v53, v52
	v_div_fmas_f32 v50, v50, v51, v53
	v_div_fixup_f32 v49, v50, v49, 1.0
	v_div_scale_f32 v50, s[24:25], v48, v48, 1.0
	v_rcp_f32_e32 v51, v50
	s_nop 0
	v_fma_f32 v52, -v50, v51, 1.0
	v_fmac_f32_e32 v51, v52, v51
	v_div_scale_f32 v52, vcc, 1.0, v48, 1.0
	v_mul_f32_e32 v53, v52, v51
	v_fma_f32 v54, -v50, v53, v52
	v_fmac_f32_e32 v53, v54, v51
	v_fma_f32 v50, -v50, v53, v52
	v_div_fmas_f32 v50, v50, v51, v53
	v_div_fixup_f32 v48, v50, v48, 1.0
	v_cvt_pk_f16_f32 v49, v48, v49
	v_cvt_f32_f16_e32 v48, v49
	v_cvt_f32_f16_sdwa v49, v49 dst_sel:DWORD dst_unused:UNUSED_PAD src0_sel:WORD_1
	v_mov_b32_e32 v50, v57
	v_mov_b32_e32 v51, v58
	v_pk_fma_f32 v[176:177], v[50:51], v[48:49], v[176:177]
	v_pk_add_f32 v[48:49], v[108:109], 1.0 op_sel_hi:[1,0]
	s_nop 0
	v_div_scale_f32 v50, s[24:25], v49, v49, 1.0
	v_rcp_f32_e32 v51, v50
	s_nop 0
	v_fma_f32 v52, -v50, v51, 1.0
	v_fmac_f32_e32 v51, v52, v51
	v_div_scale_f32 v52, vcc, 1.0, v49, 1.0
	v_mul_f32_e32 v53, v52, v51
	v_fma_f32 v54, -v50, v53, v52
	v_fmac_f32_e32 v53, v54, v51
	v_fma_f32 v50, -v50, v53, v52
	v_div_fmas_f32 v50, v50, v51, v53
	v_div_fixup_f32 v49, v50, v49, 1.0
	v_div_scale_f32 v50, s[24:25], v48, v48, 1.0
	v_rcp_f32_e32 v51, v50
	s_nop 0
	v_fma_f32 v52, -v50, v51, 1.0
	v_fmac_f32_e32 v51, v52, v51
	v_div_scale_f32 v52, vcc, 1.0, v48, 1.0
	v_mul_f32_e32 v53, v52, v51
	v_fma_f32 v54, -v50, v53, v52
	v_fmac_f32_e32 v53, v54, v51
	v_fma_f32 v50, -v50, v53, v52
	v_div_fmas_f32 v50, v50, v51, v53
	v_div_fixup_f32 v48, v50, v48, 1.0
	v_cvt_pk_f16_f32 v49, v48, v49
	v_cvt_f32_f16_e32 v48, v49
	v_cvt_f32_f16_sdwa v49, v49 dst_sel:DWORD dst_unused:UNUSED_PAD src0_sel:WORD_1
	v_mov_b32_e32 v50, v59
	v_mov_b32_e32 v51, v60
	v_pk_fma_f32 v[174:175], v[50:51], v[48:49], v[174:175]
	v_pk_add_f32 v[48:49], v[106:107], 1.0 op_sel_hi:[1,0]
	s_nop 0
	v_div_scale_f32 v50, s[24:25], v49, v49, 1.0
	v_rcp_f32_e32 v51, v50
	s_nop 0
	v_fma_f32 v52, -v50, v51, 1.0
	v_fmac_f32_e32 v51, v52, v51
	v_div_scale_f32 v52, vcc, 1.0, v49, 1.0
	v_mul_f32_e32 v53, v52, v51
	v_fma_f32 v54, -v50, v53, v52
	v_fmac_f32_e32 v53, v54, v51
	v_fma_f32 v50, -v50, v53, v52
	v_div_fmas_f32 v50, v50, v51, v53
	v_div_fixup_f32 v49, v50, v49, 1.0
	v_div_scale_f32 v50, s[24:25], v48, v48, 1.0
	v_rcp_f32_e32 v51, v50
	s_nop 0
	v_fma_f32 v52, -v50, v51, 1.0
	v_fmac_f32_e32 v51, v52, v51
	v_div_scale_f32 v52, vcc, 1.0, v48, 1.0
	v_mul_f32_e32 v53, v52, v51
	v_fma_f32 v54, -v50, v53, v52
	v_fmac_f32_e32 v53, v54, v51
	v_fma_f32 v50, -v50, v53, v52
	v_div_fmas_f32 v50, v50, v51, v53
	v_div_fixup_f32 v48, v50, v48, 1.0
	v_cvt_pk_f16_f32 v49, v48, v49
	v_cvt_f32_f16_e32 v48, v49
	v_cvt_f32_f16_sdwa v49, v49 dst_sel:DWORD dst_unused:UNUSED_PAD src0_sel:WORD_1
	v_mov_b32_e32 v50, v61
	v_mov_b32_e32 v51, v62
	v_pk_fma_f32 v[172:173], v[50:51], v[48:49], v[172:173]
	v_pk_add_f32 v[48:49], v[104:105], 1.0 op_sel_hi:[1,0]
	s_nop 0
	v_div_scale_f32 v32, s[24:25], v49, v49, 1.0
	v_rcp_f32_e32 v50, v32
	s_nop 0
	v_fma_f32 v51, -v32, v50, 1.0
	v_fmac_f32_e32 v50, v51, v50
	v_div_scale_f32 v51, vcc, 1.0, v49, 1.0
	v_mul_f32_e32 v52, v51, v50
; DI float sigmoid_f(float x) { return 1.f / (1.f + __expf(-x)); }
; template <int MB>
; DI void merge_tile(const Params& P, int layer, size_t row0, int nt, char* smem) {
;     ...
; #pragma unroll
;     for (int mb = 0; mb < MB; ++mb)
; #pragma unroll
;       for (int nb = 0; nb < 2; ++nb)
; #pragma unroll
;         for (int v = 0; v < 16; ++v) gpk[mb][nb][v >> 3][v & 7] = (h16)sigmoid_f(pa2[mb][nb][v]);
;     zero_acc<MB>(pa2);
;     gemm_kloop<MB, true>(pa2, yn + row0 * LDY, LDY, wbrT + (size_t)(n * 1024 + nt * 256) * LDY, LDY, WB, smem);
; #pragma unroll
;     for (int mb = 0; mb < MB; ++mb)
; #pragma unroll
;       for (int nb = 0; nb < 2; ++nb)
; #pragma unroll
;         for (int v = 0; v < 16; ++v) macc[mb][nb][v] += (float)gpk[mb][nb][v >> 3][v & 7] * pa2[mb][nb][v];
	v_fma_f32 v53, -v32, v52, v51
	v_fmac_f32_e32 v52, v53, v50
	v_fma_f32 v32, -v32, v52, v51
	v_div_fmas_f32 v32, v32, v50, v52
	v_div_fixup_f32 v32, v32, v49, 1.0
	v_div_scale_f32 v49, s[24:25], v48, v48, 1.0
	v_rcp_f32_e32 v50, v49
	s_nop 0
	v_fma_f32 v51, -v49, v50, 1.0
	v_fmac_f32_e32 v50, v51, v50
	v_div_scale_f32 v51, vcc, 1.0, v48, 1.0
	v_mul_f32_e32 v52, v51, v50
	v_fma_f32 v53, -v49, v52, v51
	v_fmac_f32_e32 v52, v53, v50
	v_fma_f32 v49, -v49, v52, v51
	v_div_fmas_f32 v49, v49, v50, v52
	v_div_fixup_f32 v48, v49, v48, 1.0
	v_cvt_pk_f16_f32 v32, v48, v32
	v_cvt_f32_f16_e32 v48, v32
	v_cvt_f32_f16_sdwa v49, v32 dst_sel:DWORD dst_unused:UNUSED_PAD src0_sel:WORD_1
	v_mov_b32_e32 v32, v33
	v_mov_b32_e32 v33, v34
	v_pk_fma_f32 v[170:171], v[32:33], v[48:49], v[170:171]
	v_pk_add_f32 v[32:33], v[102:103], 1.0 op_sel_hi:[1,0]
	s_nop 0
	v_div_scale_f32 v34, s[24:25], v33, v33, 1.0
	v_rcp_f32_e32 v48, v34
	s_nop 0
	v_fma_f32 v49, -v34, v48, 1.0
	v_fmac_f32_e32 v48, v49, v48
	v_div_scale_f32 v49, vcc, 1.0, v33, 1.0
	v_mul_f32_e32 v50, v49, v48
	v_fma_f32 v51, -v34, v50, v49
	v_fmac_f32_e32 v50, v51, v48
	v_fma_f32 v34, -v34, v50, v49
	v_div_fmas_f32 v34, v34, v48, v50
	v_div_fixup_f32 v33, v34, v33, 1.0
	v_div_scale_f32 v34, s[24:25], v32, v32, 1.0
	v_rcp_f32_e32 v48, v34
	s_nop 0
	v_fma_f32 v49, -v34, v48, 1.0
	v_fmac_f32_e32 v48, v49, v48
	v_div_scale_f32 v49, vcc, 1.0, v32, 1.0
	v_mul_f32_e32 v50, v49, v48
	v_fma_f32 v51, -v34, v50, v49
	v_fmac_f32_e32 v50, v51, v48
	v_fma_f32 v34, -v34, v50, v49
	v_div_fmas_f32 v34, v34, v48, v50
	v_div_fixup_f32 v32, v34, v32, 1.0
	v_cvt_pk_f16_f32 v33, v32, v33
	v_cvt_f32_f16_e32 v32, v33
	v_cvt_f32_f16_sdwa v33, v33 dst_sel:DWORD dst_unused:UNUSED_PAD src0_sel:WORD_1
	v_mov_b32_e32 v34, v35
	v_mov_b32_e32 v35, v36
	v_pk_fma_f32 v[168:169], v[34:35], v[32:33], v[168:169]
	v_pk_add_f32 v[32:33], v[100:101], 1.0 op_sel_hi:[1,0]
	s_nop 0
	v_div_scale_f32 v34, s[24:25], v33, v33, 1.0
	v_rcp_f32_e32 v35, v34
	s_nop 0
	v_fma_f32 v36, -v34, v35, 1.0
	v_fmac_f32_e32 v35, v36, v35
	v_div_scale_f32 v36, vcc, 1.0, v33, 1.0
	v_mul_f32_e32 v48, v36, v35
	v_fma_f32 v49, -v34, v48, v36
	v_fmac_f32_e32 v48, v49, v35
	v_fma_f32 v34, -v34, v48, v36
	v_div_fmas_f32 v34, v34, v35, v48
	v_div_fixup_f32 v33, v34, v33, 1.0
	v_div_scale_f32 v34, s[24:25], v32, v32, 1.0
	v_rcp_f32_e32 v35, v34
	s_nop 0
	v_fma_f32 v36, -v34, v35, 1.0
	v_fmac_f32_e32 v35, v36, v35
	v_div_scale_f32 v36, vcc, 1.0, v32, 1.0
	v_mul_f32_e32 v48, v36, v35
	v_fma_f32 v49, -v34, v48, v36
	v_fmac_f32_e32 v48, v49, v35
	v_fma_f32 v34, -v34, v48, v36
	v_div_fmas_f32 v34, v34, v35, v48
	v_div_fixup_f32 v32, v34, v32, 1.0
	v_cvt_pk_f16_f32 v33, v32, v33
	v_cvt_f32_f16_e32 v32, v33
	v_cvt_f32_f16_sdwa v33, v33 dst_sel:DWORD dst_unused:UNUSED_PAD src0_sel:WORD_1
	v_mov_b32_e32 v34, v37
	v_mov_b32_e32 v35, v38
	v_pk_fma_f32 v[166:167], v[34:35], v[32:33], v[166:167]
	v_pk_add_f32 v[32:33], v[98:99], 1.0 op_sel_hi:[1,0]
	s_nop 0
	v_div_scale_f32 v34, s[24:25], v33, v33, 1.0
	v_rcp_f32_e32 v35, v34
	s_nop 0
	v_fma_f32 v36, -v34, v35, 1.0
	v_fmac_f32_e32 v35, v36, v35
	v_div_scale_f32 v36, vcc, 1.0, v33, 1.0
	v_mul_f32_e32 v37, v36, v35
	v_fma_f32 v38, -v34, v37, v36
	v_fmac_f32_e32 v37, v38, v35
	v_fma_f32 v34, -v34, v37, v36
	v_div_fmas_f32 v34, v34, v35, v37
	v_div_fixup_f32 v33, v34, v33, 1.0
	v_div_scale_f32 v34, s[24:25], v32, v32, 1.0
	v_rcp_f32_e32 v35, v34
	s_nop 0
	v_fma_f32 v36, -v34, v35, 1.0
	v_fmac_f32_e32 v35, v36, v35
	v_div_scale_f32 v36, vcc, 1.0, v32, 1.0
	v_mul_f32_e32 v37, v36, v35
	v_fma_f32 v38, -v34, v37, v36
	v_fmac_f32_e32 v37, v38, v35
	v_fma_f32 v34, -v34, v37, v36
	v_div_fmas_f32 v34, v34, v35, v37
	v_div_fixup_f32 v32, v34, v32, 1.0
	v_cvt_pk_f16_f32 v33, v32, v33
	v_cvt_f32_f16_e32 v32, v33
	v_cvt_f32_f16_sdwa v33, v33 dst_sel:DWORD dst_unused:UNUSED_PAD src0_sel:WORD_1
	v_mov_b32_e32 v34, v39
	v_mov_b32_e32 v35, v40
	v_pk_fma_f32 v[164:165], v[34:35], v[32:33], v[164:165]
	v_pk_add_f32 v[32:33], v[96:97], 1.0 op_sel_hi:[1,0]
	s_nop 0
	v_div_scale_f32 v34, s[24:25], v33, v33, 1.0
	v_rcp_f32_e32 v35, v34
	s_nop 0
	v_fma_f32 v36, -v34, v35, 1.0
	v_fmac_f32_e32 v35, v36, v35
	v_div_scale_f32 v36, vcc, 1.0, v33, 1.0
	v_mul_f32_e32 v37, v36, v35
	v_fma_f32 v38, -v34, v37, v36
	v_fmac_f32_e32 v37, v38, v35
	v_fma_f32 v34, -v34, v37, v36
	v_div_fmas_f32 v34, v34, v35, v37
	v_div_fixup_f32 v33, v34, v33, 1.0
	v_div_scale_f32 v34, s[24:25], v32, v32, 1.0
	v_rcp_f32_e32 v35, v34
	s_nop 0
	v_fma_f32 v36, -v34, v35, 1.0
	v_fmac_f32_e32 v35, v36, v35
	v_div_scale_f32 v36, vcc, 1.0, v32, 1.0
	v_mul_f32_e32 v37, v36, v35
	v_fma_f32 v38, -v34, v37, v36
	v_fmac_f32_e32 v37, v38, v35
	v_fma_f32 v34, -v34, v37, v36
	v_div_fmas_f32 v34, v34, v35, v37
	v_div_fixup_f32 v32, v34, v32, 1.0
	v_cvt_pk_f16_f32 v33, v32, v33
	v_cvt_f32_f16_e32 v32, v33
	v_cvt_f32_f16_sdwa v33, v33 dst_sel:DWORD dst_unused:UNUSED_PAD src0_sel:WORD_1
	v_mov_b32_e32 v34, v41
	v_mov_b32_e32 v35, v42
	v_pk_fma_f32 v[162:163], v[34:35], v[32:33], v[162:163]
	v_pk_add_f32 v[32:33], v[94:95], 1.0 op_sel_hi:[1,0]
	s_nop 0
	v_div_scale_f32 v34, s[24:25], v33, v33, 1.0
	v_rcp_f32_e32 v35, v34
	s_nop 0
	v_fma_f32 v36, -v34, v35, 1.0
	v_fmac_f32_e32 v35, v36, v35
	v_div_scale_f32 v36, vcc, 1.0, v33, 1.0
	v_mul_f32_e32 v37, v36, v35
	v_fma_f32 v38, -v34, v37, v36
	v_fmac_f32_e32 v37, v38, v35
	v_fma_f32 v34, -v34, v37, v36
	v_div_fmas_f32 v34, v34, v35, v37
	v_div_fixup_f32 v33, v34, v33, 1.0
	v_div_scale_f32 v34, s[24:25], v32, v32, 1.0
	v_rcp_f32_e32 v35, v34
	s_nop 0
	v_fma_f32 v36, -v34, v35, 1.0
	v_fmac_f32_e32 v35, v36, v35
	v_div_scale_f32 v36, vcc, 1.0, v32, 1.0
	v_mul_f32_e32 v37, v36, v35
; DI float sigmoid_f(float x) { return 1.f / (1.f + __expf(-x)); }
; template <int MB>
; DI void merge_tile(const Params& P, int layer, size_t row0, int nt, char* smem) {
;     ...
; #pragma unroll
;     for (int mb = 0; mb < MB; ++mb)
; #pragma unroll
;       for (int nb = 0; nb < 2; ++nb)
; #pragma unroll
;         for (int v = 0; v < 16; ++v) gpk[mb][nb][v >> 3][v & 7] = (h16)sigmoid_f(pa2[mb][nb][v]);
;     zero_acc<MB>(pa2);
;     gemm_kloop<MB, true>(pa2, yn + row0 * LDY, LDY, wbrT + (size_t)(n * 1024 + nt * 256) * LDY, LDY, WB, smem);
; #pragma unroll
;     for (int mb = 0; mb < MB; ++mb)
; #pragma unroll
;       for (int nb = 0; nb < 2; ++nb)
; #pragma unroll
;         for (int v = 0; v < 16; ++v) macc[mb][nb][v] += (float)gpk[mb][nb][v >> 3][v & 7] * pa2[mb][nb][v];
	v_fma_f32 v38, -v34, v37, v36
	v_fmac_f32_e32 v37, v38, v35
	v_fma_f32 v34, -v34, v37, v36
	v_div_fmas_f32 v34, v34, v35, v37
	v_div_fixup_f32 v32, v34, v32, 1.0
	v_cvt_pk_f16_f32 v33, v32, v33
	v_cvt_f32_f16_e32 v32, v33
	v_cvt_f32_f16_sdwa v33, v33 dst_sel:DWORD dst_unused:UNUSED_PAD src0_sel:WORD_1
	v_mov_b32_e32 v34, v43
	v_mov_b32_e32 v35, v44
	v_pk_fma_f32 v[160:161], v[34:35], v[32:33], v[160:161]
	v_pk_add_f32 v[32:33], v[92:93], 1.0 op_sel_hi:[1,0]
	s_nop 0
	v_div_scale_f32 v34, s[24:25], v33, v33, 1.0
	v_rcp_f32_e32 v35, v34
	s_nop 0
	v_fma_f32 v36, -v34, v35, 1.0
	v_fmac_f32_e32 v35, v36, v35
	v_div_scale_f32 v36, vcc, 1.0, v33, 1.0
	v_mul_f32_e32 v37, v36, v35
	v_fma_f32 v38, -v34, v37, v36
	v_fmac_f32_e32 v37, v38, v35
	v_fma_f32 v34, -v34, v37, v36
	v_div_fmas_f32 v34, v34, v35, v37
	v_div_fixup_f32 v33, v34, v33, 1.0
	v_div_scale_f32 v34, s[24:25], v32, v32, 1.0
	v_rcp_f32_e32 v35, v34
	s_nop 0
	v_fma_f32 v36, -v34, v35, 1.0
	v_fmac_f32_e32 v35, v36, v35
	v_div_scale_f32 v36, vcc, 1.0, v32, 1.0
	v_mul_f32_e32 v37, v36, v35
	v_fma_f32 v38, -v34, v37, v36
	v_fmac_f32_e32 v37, v38, v35
	v_fma_f32 v34, -v34, v37, v36
	v_div_fmas_f32 v34, v34, v35, v37
	v_div_fixup_f32 v32, v34, v32, 1.0
	v_cvt_pk_f16_f32 v33, v32, v33
	v_cvt_f32_f16_e32 v32, v33
	v_cvt_f32_f16_sdwa v33, v33 dst_sel:DWORD dst_unused:UNUSED_PAD src0_sel:WORD_1
	v_mov_b32_e32 v34, v45
	v_mov_b32_e32 v35, v46
	v_pk_fma_f32 v[158:159], v[34:35], v[32:33], v[158:159]
	v_pk_add_f32 v[32:33], v[90:91], 1.0 op_sel_hi:[1,0]
	s_nop 0
	v_div_scale_f32 v16, s[24:25], v33, v33, 1.0
	v_rcp_f32_e32 v34, v16
	s_nop 0
	v_fma_f32 v35, -v16, v34, 1.0
	v_fmac_f32_e32 v34, v35, v34
	v_div_scale_f32 v35, vcc, 1.0, v33, 1.0
	v_mul_f32_e32 v36, v35, v34
	v_fma_f32 v37, -v16, v36, v35
	v_fmac_f32_e32 v36, v37, v34
	v_fma_f32 v16, -v16, v36, v35
	v_div_fmas_f32 v16, v16, v34, v36
	v_div_fixup_f32 v16, v16, v33, 1.0
	v_div_scale_f32 v33, s[24:25], v32, v32, 1.0
	v_rcp_f32_e32 v34, v33
	s_nop 0
	v_fma_f32 v35, -v33, v34, 1.0
	v_fmac_f32_e32 v34, v35, v34
	v_div_scale_f32 v35, vcc, 1.0, v32, 1.0
	v_mul_f32_e32 v36, v35, v34
	v_fma_f32 v37, -v33, v36, v35
	v_fmac_f32_e32 v36, v37, v34
	v_fma_f32 v33, -v33, v36, v35
	v_div_fmas_f32 v33, v33, v34, v36
	v_div_fixup_f32 v32, v33, v32, 1.0
	v_cvt_pk_f16_f32 v16, v32, v16
	v_cvt_f32_f16_e32 v32, v16
	v_cvt_f32_f16_sdwa v33, v16 dst_sel:DWORD dst_unused:UNUSED_PAD src0_sel:WORD_1
	v_mov_b32_e32 v16, v17
	v_mov_b32_e32 v17, v18
	v_pk_fma_f32 v[156:157], v[16:17], v[32:33], v[156:157]
	v_pk_add_f32 v[16:17], v[88:89], 1.0 op_sel_hi:[1,0]
	s_nop 0
	v_div_scale_f32 v18, s[24:25], v17, v17, 1.0
	v_rcp_f32_e32 v32, v18
	s_nop 0
	v_fma_f32 v33, -v18, v32, 1.0
	v_fmac_f32_e32 v32, v33, v32
	v_div_scale_f32 v33, vcc, 1.0, v17, 1.0
	v_mul_f32_e32 v34, v33, v32
	v_fma_f32 v35, -v18, v34, v33
	v_fmac_f32_e32 v34, v35, v32
	v_fma_f32 v18, -v18, v34, v33
	v_div_fmas_f32 v18, v18, v32, v34
	v_div_fixup_f32 v17, v18, v17, 1.0
	v_div_scale_f32 v18, s[24:25], v16, v16, 1.0
	v_rcp_f32_e32 v32, v18
	s_nop 0
	v_fma_f32 v33, -v18, v32, 1.0
	v_fmac_f32_e32 v32, v33, v32
	v_div_scale_f32 v33, vcc, 1.0, v16, 1.0
	v_mul_f32_e32 v34, v33, v32
	v_fma_f32 v35, -v18, v34, v33
	v_fmac_f32_e32 v34, v35, v32
	v_fma_f32 v18, -v18, v34, v33
	v_div_fmas_f32 v18, v18, v32, v34
	v_div_fixup_f32 v16, v18, v16, 1.0
	v_cvt_pk_f16_f32 v17, v16, v17
	v_cvt_f32_f16_e32 v16, v17
	v_cvt_f32_f16_sdwa v17, v17 dst_sel:DWORD dst_unused:UNUSED_PAD src0_sel:WORD_1
	v_mov_b32_e32 v18, v19
	v_mov_b32_e32 v19, v20
	v_pk_fma_f32 v[154:155], v[18:19], v[16:17], v[154:155]
	v_pk_add_f32 v[16:17], v[86:87], 1.0 op_sel_hi:[1,0]
	s_nop 0
	v_div_scale_f32 v18, s[24:25], v17, v17, 1.0
	v_rcp_f32_e32 v19, v18
	s_nop 0
	v_fma_f32 v20, -v18, v19, 1.0
	v_fmac_f32_e32 v19, v20, v19
	v_div_scale_f32 v20, vcc, 1.0, v17, 1.0
	v_mul_f32_e32 v32, v20, v19
	v_fma_f32 v33, -v18, v32, v20
	v_fmac_f32_e32 v32, v33, v19
	v_fma_f32 v18, -v18, v32, v20
	v_div_fmas_f32 v18, v18, v19, v32
	v_div_fixup_f32 v17, v18, v17, 1.0
	v_div_scale_f32 v18, s[24:25], v16, v16, 1.0
	v_rcp_f32_e32 v19, v18
	s_nop 0
	v_fma_f32 v20, -v18, v19, 1.0
	v_fmac_f32_e32 v19, v20, v19
	v_div_scale_f32 v20, vcc, 1.0, v16, 1.0
	v_mul_f32_e32 v32, v20, v19
	v_fma_f32 v33, -v18, v32, v20
	v_fmac_f32_e32 v32, v33, v19
	v_fma_f32 v18, -v18, v32, v20
	v_div_fmas_f32 v18, v18, v19, v32
	v_div_fixup_f32 v16, v18, v16, 1.0
	v_cvt_pk_f16_f32 v17, v16, v17
	v_cvt_f32_f16_e32 v16, v17
	v_cvt_f32_f16_sdwa v17, v17 dst_sel:DWORD dst_unused:UNUSED_PAD src0_sel:WORD_1
	v_mov_b32_e32 v18, v21
	v_mov_b32_e32 v19, v22
	v_pk_fma_f32 v[152:153], v[18:19], v[16:17], v[152:153]
	v_pk_add_f32 v[16:17], v[84:85], 1.0 op_sel_hi:[1,0]
	s_nop 0
	v_div_scale_f32 v18, s[24:25], v17, v17, 1.0
	v_rcp_f32_e32 v19, v18
	s_nop 0
	v_fma_f32 v20, -v18, v19, 1.0
	v_fmac_f32_e32 v19, v20, v19
	v_div_scale_f32 v20, vcc, 1.0, v17, 1.0
	v_mul_f32_e32 v21, v20, v19
	v_fma_f32 v22, -v18, v21, v20
	v_fmac_f32_e32 v21, v22, v19
	v_fma_f32 v18, -v18, v21, v20
	v_div_fmas_f32 v18, v18, v19, v21
	v_div_fixup_f32 v17, v18, v17, 1.0
	v_div_scale_f32 v18, s[24:25], v16, v16, 1.0
	v_rcp_f32_e32 v19, v18
	s_nop 0
	v_fma_f32 v20, -v18, v19, 1.0
	v_fmac_f32_e32 v19, v20, v19
	v_div_scale_f32 v20, vcc, 1.0, v16, 1.0
	v_mul_f32_e32 v21, v20, v19
	v_fma_f32 v22, -v18, v21, v20
	v_fmac_f32_e32 v21, v22, v19
	v_fma_f32 v18, -v18, v21, v20
	v_div_fmas_f32 v18, v18, v19, v21
	v_div_fixup_f32 v16, v18, v16, 1.0
	v_cvt_pk_f16_f32 v17, v16, v17
	v_cvt_f32_f16_e32 v16, v17
	v_cvt_f32_f16_sdwa v17, v17 dst_sel:DWORD dst_unused:UNUSED_PAD src0_sel:WORD_1
	v_mov_b32_e32 v18, v23
	v_mov_b32_e32 v19, v24
; DI float sigmoid_f(float x) { return 1.f / (1.f + __expf(-x)); }
; template <int MB>
; DI void merge_tile(const Params& P, int layer, size_t row0, int nt, char* smem) {
;     ...
; #pragma unroll
;     for (int mb = 0; mb < MB; ++mb)
; #pragma unroll
;       for (int nb = 0; nb < 2; ++nb)
; #pragma unroll
;         for (int v = 0; v < 16; ++v) gpk[mb][nb][v >> 3][v & 7] = (h16)sigmoid_f(pa2[mb][nb][v]);
;     zero_acc<MB>(pa2);
;     gemm_kloop<MB, true>(pa2, yn + row0 * LDY, LDY, wbrT + (size_t)(n * 1024 + nt * 256) * LDY, LDY, WB, smem);
; #pragma unroll
;     for (int mb = 0; mb < MB; ++mb)
; #pragma unroll
;       for (int nb = 0; nb < 2; ++nb)
; #pragma unroll
;         for (int v = 0; v < 16; ++v) macc[mb][nb][v] += (float)gpk[mb][nb][v >> 3][v & 7] * pa2[mb][nb][v];
	v_pk_fma_f32 v[150:151], v[18:19], v[16:17], v[150:151]
	v_pk_add_f32 v[16:17], v[82:83], 1.0 op_sel_hi:[1,0]
	s_nop 0
	v_div_scale_f32 v18, s[24:25], v17, v17, 1.0
	v_rcp_f32_e32 v19, v18
	s_nop 0
	v_fma_f32 v20, -v18, v19, 1.0
	v_fmac_f32_e32 v19, v20, v19
	v_div_scale_f32 v20, vcc, 1.0, v17, 1.0
	v_mul_f32_e32 v21, v20, v19
	v_fma_f32 v22, -v18, v21, v20
	v_fmac_f32_e32 v21, v22, v19
	v_fma_f32 v18, -v18, v21, v20
	v_div_fmas_f32 v18, v18, v19, v21
	v_div_fixup_f32 v17, v18, v17, 1.0
	v_div_scale_f32 v18, s[24:25], v16, v16, 1.0
	v_rcp_f32_e32 v19, v18
	s_nop 0
	v_fma_f32 v20, -v18, v19, 1.0
	v_fmac_f32_e32 v19, v20, v19
	v_div_scale_f32 v20, vcc, 1.0, v16, 1.0
	v_mul_f32_e32 v21, v20, v19
	v_fma_f32 v22, -v18, v21, v20
	v_fmac_f32_e32 v21, v22, v19
	v_fma_f32 v18, -v18, v21, v20
	v_div_fmas_f32 v18, v18, v19, v21
	v_div_fixup_f32 v16, v18, v16, 1.0
	v_cvt_pk_f16_f32 v17, v16, v17
	v_cvt_f32_f16_e32 v16, v17
	v_cvt_f32_f16_sdwa v17, v17 dst_sel:DWORD dst_unused:UNUSED_PAD src0_sel:WORD_1
	v_mov_b32_e32 v18, v25
	v_mov_b32_e32 v19, v26
	v_pk_fma_f32 v[148:149], v[18:19], v[16:17], v[148:149]
	v_pk_add_f32 v[16:17], v[80:81], 1.0 op_sel_hi:[1,0]
	s_nop 0
	v_div_scale_f32 v18, s[24:25], v17, v17, 1.0
	v_rcp_f32_e32 v19, v18
	s_nop 0
	v_fma_f32 v20, -v18, v19, 1.0
	v_fmac_f32_e32 v19, v20, v19
	v_div_scale_f32 v20, vcc, 1.0, v17, 1.0
	v_mul_f32_e32 v21, v20, v19
	v_fma_f32 v22, -v18, v21, v20
	v_fmac_f32_e32 v21, v22, v19
	v_fma_f32 v18, -v18, v21, v20
	v_div_fmas_f32 v18, v18, v19, v21
	v_div_fixup_f32 v17, v18, v17, 1.0
	v_div_scale_f32 v18, s[24:25], v16, v16, 1.0
	v_rcp_f32_e32 v19, v18
	s_nop 0
	v_fma_f32 v20, -v18, v19, 1.0
	v_fmac_f32_e32 v19, v20, v19
	v_div_scale_f32 v20, vcc, 1.0, v16, 1.0
	v_mul_f32_e32 v21, v20, v19
	v_fma_f32 v22, -v18, v21, v20
	v_fmac_f32_e32 v21, v22, v19
	v_fma_f32 v18, -v18, v21, v20
	v_div_fmas_f32 v18, v18, v19, v21
	v_div_fixup_f32 v16, v18, v16, 1.0
	v_cvt_pk_f16_f32 v17, v16, v17
	v_cvt_f32_f16_e32 v16, v17
	v_cvt_f32_f16_sdwa v17, v17 dst_sel:DWORD dst_unused:UNUSED_PAD src0_sel:WORD_1
	v_mov_b32_e32 v18, v27
	v_mov_b32_e32 v19, v28
	v_pk_fma_f32 v[146:147], v[18:19], v[16:17], v[146:147]
	v_pk_add_f32 v[16:17], v[78:79], 1.0 op_sel_hi:[1,0]
	s_nop 0
	v_div_scale_f32 v18, s[24:25], v17, v17, 1.0
	v_rcp_f32_e32 v19, v18
	s_nop 0
	v_fma_f32 v20, -v18, v19, 1.0
	v_fmac_f32_e32 v19, v20, v19
	v_div_scale_f32 v20, vcc, 1.0, v17, 1.0
	v_mul_f32_e32 v21, v20, v19
	v_fma_f32 v22, -v18, v21, v20
	v_fmac_f32_e32 v21, v22, v19
	v_fma_f32 v18, -v18, v21, v20
	v_div_fmas_f32 v18, v18, v19, v21
	v_div_fixup_f32 v17, v18, v17, 1.0
	v_div_scale_f32 v18, s[24:25], v16, v16, 1.0
	v_rcp_f32_e32 v19, v18
	s_nop 0
	v_fma_f32 v20, -v18, v19, 1.0
	v_fmac_f32_e32 v19, v20, v19
	v_div_scale_f32 v20, vcc, 1.0, v16, 1.0
	v_mul_f32_e32 v21, v20, v19
	v_fma_f32 v22, -v18, v21, v20
	v_fmac_f32_e32 v21, v22, v19
	v_fma_f32 v18, -v18, v21, v20
	v_div_fmas_f32 v18, v18, v19, v21
	v_div_fixup_f32 v16, v18, v16, 1.0
	v_cvt_pk_f16_f32 v17, v16, v17
	v_cvt_f32_f16_e32 v16, v17
	v_cvt_f32_f16_sdwa v17, v17 dst_sel:DWORD dst_unused:UNUSED_PAD src0_sel:WORD_1
	v_mov_b32_e32 v18, v29
	v_mov_b32_e32 v19, v30
	v_pk_fma_f32 v[144:145], v[18:19], v[16:17], v[144:145]
	v_pk_add_f32 v[16:17], v[76:77], 1.0 op_sel_hi:[1,0]
	s_nop 0
	v_div_scale_f32 v0, s[24:25], v17, v17, 1.0
	v_rcp_f32_e32 v18, v0
	s_nop 0
	v_fma_f32 v19, -v0, v18, 1.0
	v_fmac_f32_e32 v18, v19, v18
	v_div_scale_f32 v19, vcc, 1.0, v17, 1.0
	v_mul_f32_e32 v20, v19, v18
	v_fma_f32 v21, -v0, v20, v19
	v_fmac_f32_e32 v20, v21, v18
	v_fma_f32 v0, -v0, v20, v19
	v_div_fmas_f32 v0, v0, v18, v20
	v_div_fixup_f32 v0, v0, v17, 1.0
	v_div_scale_f32 v17, s[24:25], v16, v16, 1.0
	v_rcp_f32_e32 v18, v17
	s_nop 0
	v_fma_f32 v19, -v17, v18, 1.0
	v_fmac_f32_e32 v18, v19, v18
	v_div_scale_f32 v19, vcc, 1.0, v16, 1.0
	v_mul_f32_e32 v20, v19, v18
	v_fma_f32 v21, -v17, v20, v19
	v_fmac_f32_e32 v20, v21, v18
	v_fma_f32 v17, -v17, v20, v19
	v_div_fmas_f32 v17, v17, v18, v20
	v_div_fixup_f32 v16, v17, v16, 1.0
	v_cvt_pk_f16_f32 v0, v16, v0
	v_cvt_f32_f16_e32 v16, v0
	v_cvt_f32_f16_sdwa v17, v0 dst_sel:DWORD dst_unused:UNUSED_PAD src0_sel:WORD_1
	v_mov_b32_e32 v0, v1
	v_mov_b32_e32 v1, v2
	v_pk_fma_f32 v[142:143], v[0:1], v[16:17], v[142:143]
	v_pk_add_f32 v[0:1], v[74:75], 1.0 op_sel_hi:[1,0]
	s_nop 0
	v_div_scale_f32 v2, s[24:25], v1, v1, 1.0
	v_rcp_f32_e32 v16, v2
	s_nop 0
	v_fma_f32 v17, -v2, v16, 1.0
	v_fmac_f32_e32 v16, v17, v16
	v_div_scale_f32 v17, vcc, 1.0, v1, 1.0
	v_mul_f32_e32 v18, v17, v16
	v_fma_f32 v19, -v2, v18, v17
	v_fmac_f32_e32 v18, v19, v16
	v_fma_f32 v2, -v2, v18, v17
	v_div_fmas_f32 v2, v2, v16, v18
	v_div_fixup_f32 v1, v2, v1, 1.0
	v_div_scale_f32 v2, s[24:25], v0, v0, 1.0
	v_rcp_f32_e32 v16, v2
	s_nop 0
	v_fma_f32 v17, -v2, v16, 1.0
	v_fmac_f32_e32 v16, v17, v16
	v_div_scale_f32 v17, vcc, 1.0, v0, 1.0
	v_mul_f32_e32 v18, v17, v16
	v_fma_f32 v19, -v2, v18, v17
	v_fmac_f32_e32 v18, v19, v16
	v_fma_f32 v2, -v2, v18, v17
	v_div_fmas_f32 v2, v2, v16, v18
	v_div_fixup_f32 v0, v2, v0, 1.0
	v_cvt_pk_f16_f32 v1, v0, v1
	v_cvt_f32_f16_e32 v0, v1
	v_cvt_f32_f16_sdwa v1, v1 dst_sel:DWORD dst_unused:UNUSED_PAD src0_sel:WORD_1
	v_mov_b32_e32 v2, v3
	v_mov_b32_e32 v3, v4
	v_pk_fma_f32 v[140:141], v[2:3], v[0:1], v[140:141]
	v_pk_add_f32 v[0:1], v[72:73], 1.0 op_sel_hi:[1,0]
	s_nop 0
	v_div_scale_f32 v2, s[24:25], v1, v1, 1.0
	v_rcp_f32_e32 v3, v2
	s_nop 0
	v_fma_f32 v4, -v2, v3, 1.0
	v_fmac_f32_e32 v3, v4, v3
	v_div_scale_f32 v4, vcc, 1.0, v1, 1.0
	v_mul_f32_e32 v16, v4, v3
	v_fma_f32 v17, -v2, v16, v4
	v_fmac_f32_e32 v16, v17, v3
	v_fma_f32 v2, -v2, v16, v4
	v_div_fmas_f32 v2, v2, v3, v16
; DI float sigmoid_f(float x) { return 1.f / (1.f + __expf(-x)); }
; template <int MB>
; DI void merge_tile(const Params& P, int layer, size_t row0, int nt, char* smem) {
;     ...
; #pragma unroll
;     for (int mb = 0; mb < MB; ++mb)
; #pragma unroll
;       for (int nb = 0; nb < 2; ++nb)
; #pragma unroll
;         for (int v = 0; v < 16; ++v) gpk[mb][nb][v >> 3][v & 7] = (h16)sigmoid_f(pa2[mb][nb][v]);
;     zero_acc<MB>(pa2);
;     gemm_kloop<MB, true>(pa2, yn + row0 * LDY, LDY, wbrT + (size_t)(n * 1024 + nt * 256) * LDY, LDY, WB, smem);
; #pragma unroll
;     for (int mb = 0; mb < MB; ++mb)
; #pragma unroll
;       for (int nb = 0; nb < 2; ++nb)
; #pragma unroll
;         for (int v = 0; v < 16; ++v) macc[mb][nb][v] += (float)gpk[mb][nb][v >> 3][v & 7] * pa2[mb][nb][v];
	v_div_fixup_f32 v1, v2, v1, 1.0
	v_div_scale_f32 v2, s[24:25], v0, v0, 1.0
	v_rcp_f32_e32 v3, v2
	s_nop 0
	v_fma_f32 v4, -v2, v3, 1.0
	v_fmac_f32_e32 v3, v4, v3
	v_div_scale_f32 v4, vcc, 1.0, v0, 1.0
	v_mul_f32_e32 v16, v4, v3
	v_fma_f32 v17, -v2, v16, v4
	v_fmac_f32_e32 v16, v17, v3
	v_fma_f32 v2, -v2, v16, v4
	v_div_fmas_f32 v2, v2, v3, v16
	v_div_fixup_f32 v0, v2, v0, 1.0
	v_cvt_pk_f16_f32 v1, v0, v1
	v_cvt_f32_f16_e32 v0, v1
	v_cvt_f32_f16_sdwa v1, v1 dst_sel:DWORD dst_unused:UNUSED_PAD src0_sel:WORD_1
	v_mov_b32_e32 v2, v5
	v_mov_b32_e32 v3, v6
	v_pk_fma_f32 v[138:139], v[2:3], v[0:1], v[138:139]
	v_pk_add_f32 v[0:1], v[70:71], 1.0 op_sel_hi:[1,0]
	s_nop 0
	v_div_scale_f32 v2, s[24:25], v1, v1, 1.0
	v_rcp_f32_e32 v3, v2
	s_nop 0
	v_fma_f32 v4, -v2, v3, 1.0
	v_fmac_f32_e32 v3, v4, v3
	v_div_scale_f32 v4, vcc, 1.0, v1, 1.0
	v_mul_f32_e32 v5, v4, v3
	v_fma_f32 v6, -v2, v5, v4
	v_fmac_f32_e32 v5, v6, v3
	v_fma_f32 v2, -v2, v5, v4
	v_div_fmas_f32 v2, v2, v3, v5
	v_div_fixup_f32 v1, v2, v1, 1.0
	v_div_scale_f32 v2, s[24:25], v0, v0, 1.0
	v_rcp_f32_e32 v3, v2
	s_nop 0
	v_fma_f32 v4, -v2, v3, 1.0
	v_fmac_f32_e32 v3, v4, v3
	v_div_scale_f32 v4, vcc, 1.0, v0, 1.0
	v_mul_f32_e32 v5, v4, v3
	v_fma_f32 v6, -v2, v5, v4
	v_fmac_f32_e32 v5, v6, v3
	v_fma_f32 v2, -v2, v5, v4
	v_div_fmas_f32 v2, v2, v3, v5
	v_div_fixup_f32 v0, v2, v0, 1.0
	v_cvt_pk_f16_f32 v1, v0, v1
	v_cvt_f32_f16_e32 v0, v1
	v_cvt_f32_f16_sdwa v1, v1 dst_sel:DWORD dst_unused:UNUSED_PAD src0_sel:WORD_1
	v_mov_b32_e32 v2, v7
	v_mov_b32_e32 v3, v8
	v_pk_fma_f32 v[136:137], v[2:3], v[0:1], v[136:137]
	v_pk_add_f32 v[0:1], v[68:69], 1.0 op_sel_hi:[1,0]
	s_nop 0
	v_div_scale_f32 v2, s[24:25], v1, v1, 1.0
	v_rcp_f32_e32 v3, v2
	s_nop 0
	v_fma_f32 v4, -v2, v3, 1.0
	v_fmac_f32_e32 v3, v4, v3
	v_div_scale_f32 v4, vcc, 1.0, v1, 1.0
	v_mul_f32_e32 v5, v4, v3
	v_fma_f32 v6, -v2, v5, v4
	v_fmac_f32_e32 v5, v6, v3
	v_fma_f32 v2, -v2, v5, v4
	v_div_fmas_f32 v2, v2, v3, v5
	v_div_fixup_f32 v1, v2, v1, 1.0
	v_div_scale_f32 v2, s[24:25], v0, v0, 1.0
	v_rcp_f32_e32 v3, v2
	s_nop 0
	v_fma_f32 v4, -v2, v3, 1.0
	v_fmac_f32_e32 v3, v4, v3
	v_div_scale_f32 v4, vcc, 1.0, v0, 1.0
	v_mul_f32_e32 v5, v4, v3
	v_fma_f32 v6, -v2, v5, v4
	v_fmac_f32_e32 v5, v6, v3
	v_fma_f32 v2, -v2, v5, v4
	v_div_fmas_f32 v2, v2, v3, v5
	v_div_fixup_f32 v0, v2, v0, 1.0
	v_cvt_pk_f16_f32 v1, v0, v1
	v_cvt_f32_f16_e32 v0, v1
	v_cvt_f32_f16_sdwa v1, v1 dst_sel:DWORD dst_unused:UNUSED_PAD src0_sel:WORD_1
	v_mov_b32_e32 v2, v9
	v_mov_b32_e32 v3, v10
	v_pk_fma_f32 v[134:135], v[2:3], v[0:1], v[134:135]
	v_pk_add_f32 v[0:1], v[66:67], 1.0 op_sel_hi:[1,0]
	s_nop 0
	v_div_scale_f32 v2, s[24:25], v1, v1, 1.0
	v_rcp_f32_e32 v3, v2
	s_nop 0
	v_fma_f32 v4, -v2, v3, 1.0
	v_fmac_f32_e32 v3, v4, v3
	v_div_scale_f32 v4, vcc, 1.0, v1, 1.0
	v_mul_f32_e32 v5, v4, v3
	v_fma_f32 v6, -v2, v5, v4
	v_fmac_f32_e32 v5, v6, v3
	v_fma_f32 v2, -v2, v5, v4
	v_div_fmas_f32 v2, v2, v3, v5
	v_div_fixup_f32 v1, v2, v1, 1.0
	v_div_scale_f32 v2, s[24:25], v0, v0, 1.0
	v_rcp_f32_e32 v3, v2
	s_nop 0
	v_fma_f32 v4, -v2, v3, 1.0
	v_fmac_f32_e32 v3, v4, v3
	v_div_scale_f32 v4, vcc, 1.0, v0, 1.0
	v_mul_f32_e32 v5, v4, v3
	v_fma_f32 v6, -v2, v5, v4
	v_fmac_f32_e32 v5, v6, v3
	v_fma_f32 v2, -v2, v5, v4
	v_div_fmas_f32 v2, v2, v3, v5
	v_div_fixup_f32 v0, v2, v0, 1.0
	v_cvt_pk_f16_f32 v1, v0, v1
	v_cvt_f32_f16_e32 v0, v1
	v_cvt_f32_f16_sdwa v1, v1 dst_sel:DWORD dst_unused:UNUSED_PAD src0_sel:WORD_1
	v_mov_b32_e32 v2, v11
	v_mov_b32_e32 v3, v12
	v_pk_fma_f32 v[132:133], v[2:3], v[0:1], v[132:133]
	v_pk_add_f32 v[0:1], v[64:65], 1.0 op_sel_hi:[1,0]
	s_nop 0
	v_div_scale_f32 v2, s[24:25], v1, v1, 1.0
	v_rcp_f32_e32 v3, v2
	s_nop 0
	v_fma_f32 v4, -v2, v3, 1.0
	v_fmac_f32_e32 v3, v4, v3
	v_div_scale_f32 v4, vcc, 1.0, v1, 1.0
	v_mul_f32_e32 v5, v4, v3
	v_fma_f32 v6, -v2, v5, v4
	v_fmac_f32_e32 v5, v6, v3
	v_fma_f32 v2, -v2, v5, v4
	v_div_fmas_f32 v2, v2, v3, v5
	v_div_fixup_f32 v1, v2, v1, 1.0
	v_div_scale_f32 v2, s[24:25], v0, v0, 1.0
	v_rcp_f32_e32 v3, v2
	s_nop 0
	v_fma_f32 v4, -v2, v3, 1.0
	v_fmac_f32_e32 v3, v4, v3
	v_div_scale_f32 v4, vcc, 1.0, v0, 1.0
	v_mul_f32_e32 v5, v4, v3
	v_fma_f32 v6, -v2, v5, v4
	v_fmac_f32_e32 v5, v6, v3
	v_fma_f32 v2, -v2, v5, v4
	v_div_fmas_f32 v2, v2, v3, v5
	v_div_fixup_f32 v0, v2, v0, 1.0
	v_cvt_pk_f16_f32 v1, v0, v1
	v_cvt_f32_f16_e32 v0, v1
	v_cvt_f32_f16_sdwa v1, v1 dst_sel:DWORD dst_unused:UNUSED_PAD src0_sel:WORD_1
	v_mov_b32_e32 v2, v13
	v_mov_b32_e32 v3, v14
	v_pk_fma_f32 v[130:131], v[2:3], v[0:1], v[130:131]
	s_cbranch_scc0 .LBB0_39
; DI int otid() { int t = threadIdx.x; asm volatile("" : "+v"(t)); return t; }
; template <int MB>
; DI void merge_tile(const Params& P, int layer, size_t row0, int nt, char* smem) {
;     ...
;   const int tid = otid(), lane = tid & 63, w = tid >> 6, wr = w >> 2, wc = w & 3, r32 = lane & 31, hh = lane >> 5;
; #pragma unroll
;   for (int mb = 0; mb < MB; ++mb) {
;     const size_t row = row0 + wr * 32 * MB + mb * 32 + r32;
; #pragma unroll
;     for (int nb = 0; nb < 2; ++nb)
; #pragma unroll
;       for (int g = 0; g < 4; ++g)
;         *(half4*)(mg + row * LDH + nt * 256 + wc * 64 + nb * 32 + 8 * g + 4 * hh) =
;             cvt4(macc[mb][nb][4 * g], macc[mb][nb][4 * g + 1], macc[mb][nb][4 * g + 2], macc[mb][nb][4 * g + 3]);
;   }
	s_lshl_b64 s[2:3], s[46:47], 7
	v_mov_b32_e32 v4, v208
	v_mov_b32_e32 v3, s3
	v_ashrrev_i32_e32 v0, 2, v4
	v_and_or_b32 v2, v4, 31, s2
	s_lshl_b32 s2, s71, 1
	v_and_b32_e32 v5, 0xc0, v4
	v_and_b32_e32 v0, 0xffffffc0, v0
	s_add_u32 s2, s48, s2
	v_ashrrev_i32_e32 v1, 31, v0
	s_addc_u32 s3, s49, 0
	v_lshlrev_b32_e32 v128, 1, v5
	v_lshrrev_b32_e32 v4, 2, v4
	v_lshl_add_u64 v[0:1], v[2:3], 0, v[0:1]
	v_lshl_add_u64 v[2:3], s[2:3], 0, v[128:129]
	v_and_b32_e32 v128, 8, v4
	v_lshl_add_u64 v[2:3], v[2:3], 0, v[128:129]
	v_mad_u64_u32 v[2:3], s[2:3], v0, s15, v[2:3]
	v_cvt_f16_f32_e32 v0, v198
	v_cvt_f16_f32_e32 v4, v182
	v_mad_i32_i24 v3, v1, s15, v3
	v_cvt_pk_f16_f32 v1, v184, v185
	v_pack_b32_f16 v0, v0, v1
	v_alignbit_b32 v1, v4, v1, 16
	v_cvt_f16_f32_e32 v4, v183
	v_cvt_f16_f32_e32 v5, v178
	global_store_dwordx2 v[2:3], v[0:1], off
	v_cvt_pk_f16_f32 v1, v180, v181
	v_pack_b32_f16 v0, v4, v1
	v_alignbit_b32 v1, v5, v1, 16
	v_cvt_f16_f32_e32 v4, v179
	v_cvt_f16_f32_e32 v5, v174
	global_store_dwordx2 v[2:3], v[0:1], off offset:16
	v_cvt_pk_f16_f32 v1, v176, v177
	v_pack_b32_f16 v0, v4, v1
	v_alignbit_b32 v1, v5, v1, 16
	v_cvt_f16_f32_e32 v4, v175
	v_cvt_f16_f32_e32 v5, v196
	global_store_dwordx2 v[2:3], v[0:1], off offset:32
	v_cvt_pk_f16_f32 v1, v172, v173
	v_pack_b32_f16 v0, v4, v1
	v_alignbit_b32 v1, v5, v1, 16
	v_cvt_f16_f32_e32 v4, v195
	v_cvt_f16_f32_e32 v5, v168
	global_store_dwordx2 v[2:3], v[0:1], off offset:48
	v_cvt_pk_f16_f32 v1, v170, v171
	v_pack_b32_f16 v0, v4, v1
	v_alignbit_b32 v1, v5, v1, 16
	v_cvt_f16_f32_e32 v4, v169
	v_cvt_f16_f32_e32 v5, v164
	global_store_dwordx2 v[2:3], v[0:1], off offset:64
	v_cvt_pk_f16_f32 v1, v166, v167
	v_pack_b32_f16 v0, v4, v1
	v_alignbit_b32 v1, v5, v1, 16
	v_cvt_f16_f32_e32 v4, v165
	v_cvt_f16_f32_e32 v5, v160
	global_store_dwordx2 v[2:3], v[0:1], off offset:80
	v_cvt_pk_f16_f32 v1, v162, v163
	v_pack_b32_f16 v0, v4, v1
	v_alignbit_b32 v1, v5, v1, 16
	v_cvt_f16_f32_e32 v4, v161
	v_cvt_f16_f32_e32 v5, v194
	global_store_dwordx2 v[2:3], v[0:1], off offset:96
	v_cvt_pk_f16_f32 v1, v158, v159
	v_pack_b32_f16 v0, v4, v1
	v_alignbit_b32 v1, v5, v1, 16
	v_cvt_f16_f32_e32 v4, v193
	v_cvt_f16_f32_e32 v5, v154
	global_store_dwordx2 v[2:3], v[0:1], off offset:112
	v_cvt_pk_f16_f32 v1, v156, v157
	v_pack_b32_f16 v0, v4, v1
	v_alignbit_b32 v1, v5, v1, 16
	s_mov_b32 s2, 0x11000
	v_cvt_f16_f32_e32 v4, v155
	v_cvt_f16_f32_e32 v5, v150
	v_add_co_u32_e32 v2, vcc, s2, v2
	v_readlane_b32 s24, v255, 43
	s_nop 0
	v_addc_co_u32_e32 v3, vcc, 0, v3, vcc
	global_store_dwordx2 v[2:3], v[0:1], off
	v_cvt_pk_f16_f32 v1, v152, v153
	v_pack_b32_f16 v0, v4, v1
	v_alignbit_b32 v1, v5, v1, 16
	v_cvt_f16_f32_e32 v4, v151
	v_cvt_f16_f32_e32 v5, v146
	global_store_dwordx2 v[2:3], v[0:1], off offset:16
	v_cvt_pk_f16_f32 v1, v148, v149
	v_pack_b32_f16 v0, v4, v1
	v_alignbit_b32 v1, v5, v1, 16
	v_cvt_f16_f32_e32 v4, v147
	v_cvt_f16_f32_e32 v5, v192
	global_store_dwordx2 v[2:3], v[0:1], off offset:32
	v_cvt_pk_f16_f32 v1, v144, v145
	v_pack_b32_f16 v0, v4, v1
	v_alignbit_b32 v1, v5, v1, 16
	v_cvt_f16_f32_e32 v4, v191
	v_cvt_f16_f32_e32 v5, v140
	global_store_dwordx2 v[2:3], v[0:1], off offset:48
	v_cvt_pk_f16_f32 v1, v142, v143
	v_pack_b32_f16 v0, v4, v1
	v_alignbit_b32 v1, v5, v1, 16
	v_cvt_f16_f32_e32 v4, v141
	v_cvt_f16_f32_e32 v5, v136
	global_store_dwordx2 v[2:3], v[0:1], off offset:64
	v_cvt_pk_f16_f32 v1, v138, v139
	v_pack_b32_f16 v0, v4, v1
	v_alignbit_b32 v1, v5, v1, 16
	v_cvt_f16_f32_e32 v4, v137
	v_cvt_f16_f32_e32 v5, v132
	global_store_dwordx2 v[2:3], v[0:1], off offset:80
	v_cvt_pk_f16_f32 v1, v134, v135
	v_pack_b32_f16 v0, v4, v1
	v_alignbit_b32 v1, v5, v1, 16
	v_cvt_f16_f32_e32 v4, v133
	v_cvt_f16_f32_e32 v5, v190
	global_store_dwordx2 v[2:3], v[0:1], off offset:96
	v_cvt_pk_f16_f32 v1, v130, v131
	v_pack_b32_f16 v0, v4, v1
	v_alignbit_b32 v1, v5, v1, 16
	v_readlane_b32 s3, v255, 41
	v_readlane_b32 s25, v255, 47
	v_readlane_b32 s33, v255, 55
	v_mov_b32_e32 v215, 0x3c0881c4
	v_mov_b32_e32 v216, 0xbab64f3b
	global_store_dwordx2 v[2:3], v[0:1], off offset:112
	s_branch .LBB0_36

; DI void wait_vm0() { asm volatile("s_waitcnt vmcnt(0)" ::: "memory"); }
; DI int otid() { int t = threadIdx.x; asm volatile("" : "+v"(t)); return t; }
;   DI int item(int i) const { const int li = j + i * nxb; if (li >= per) return -1; const int lin = xcd * per + li; return lin < total ? lin : -1; }
; template <int MB, bool SWAP>
; DI void gemm_kloop(f32x16 (&acc)[MB][2], const h16* __restrict__ A, int lda, const h16* __restrict__ B, int ldb, int K, char* lds) {
;     ...
;   const int tid = otid(), w = tid >> 6, lane = tid & 63;
;   const int wr = w >> 2, wc = w & 3;
;   const int lrow = w * 8 + (lane >> 3), pch = lane & 7;
;   const int gch = pch ^ ((lrow >> 1) & 7);
;   const unsigned voa = (unsigned)(lrow * lda + gch * 8) * 2u, vob = (unsigned)(lrow * ldb + gch * 8) * 2u;
;   const int lofs = lrow * 128 + pch * 16;
;   const int r32 = lane & 31, hh = lane >> 5, sw = (r32 >> 1) & 7;
;   const int a_rd = (wr * 32 * MB + r32) * 128;
;   const int b_rd = A_BYTES + (wc * 64 + r32) * 128;
;   const int nk = K >> 6;
;   constexpr int NP = MB + 4;
;   auto piece = [&](int p, int kt, int buf) {
;     char* s = lds + buf * STAGE;
;     if (p < MB) __builtin_amdgcn_global_load_lds((const unsigned*)((const char*)(A + (size_t)p * 64 * lda + kt * 64) + voa), (unsigned*)(s + p * 8192 + lofs), 16, 0, 0);
;     else __builtin_amdgcn_global_load_lds((const unsigned*)((const char*)(B + (size_t)(p - MB) * 64 * ldb + kt * 64) + vob), (unsigned*)(s + A_BYTES + (p - MB) * 8192 + lofs), 16, 0, 0);
;   };
;   wait_vm0();
; #pragma unroll
;   for (int p = 0; p < NP; ++p) piece(p, 0, 0);
; #pragma unroll
;   for (int p = 0; p < NP; ++p) piece(p, 1, 1);
; DI void phase_out(const Params& P, int layer, char* smem) {
;     ...
;   for_items_xcd(nfull, [&](int item) {
;     const int mt = (item >> 5) * 8 + (item & 7), nt = (item & 31) >> 3;
;     out_tile<2>(P, layer, mt * 128, nt, smem);
.LBB0_721:
	s_add_i32 s2, s39, s81
	s_cmp_ge_i32 s2, s70
	s_cbranch_scc1 .LBB0_720
	v_mov_b32_e32 v6, v208
	s_bfe_u32 s24, s38, 0x20003
	v_ashrrev_i32_e32 v7, 3, v6
	v_bfe_u32 v8, v6, 3, 3
	v_and_or_b32 v0, v7, -8, v8
	v_lshrrev_b32_e32 v1, 1, v0
	v_xor_b32_e32 v1, v1, v6
	v_lshlrev_b32_e32 v1, 3, v1
	v_mul_lo_u32 v2, v0, s6
	v_and_b32_e32 v9, 56, v1
	v_or_b32_e32 v1, v9, v2
	s_ashr_i32 s52, s2, 2
	v_lshlrev_b32_e32 v128, 1, v1
	v_lshlrev_b32_e32 v1, 4, v6
	s_mul_i32 s33, s24, 0x88000
	s_and_b32 s24, s52, 0x1fffff8
	s_and_b32 s25, s2, 7
	v_and_b32_e32 v1, 0x70, v1
	s_and_b32 s3, s97, 7
	s_or_b32 s24, s24, s25
	v_lshl_or_b32 v10, v0, 7, v1
	s_lshl_b32 s3, s3, 7
	s_bfe_u32 s75, s2, 0x20003
	s_lshl_b32 s2, s24, 7
	s_mul_i32 s24, s24, 0x44000
	v_add_u32_e32 v74, 0, v10
	s_mul_hi_i32 s25, s2, 0x880
	s_add_u32 s24, s48, s24
	v_readfirstlane_b32 s53, v74
	s_addc_u32 s25, s49, s25
	s_waitcnt vmcnt(0)
	s_mov_b32 m0, s53
	v_add_u32_e32 v13, 0x2000, v74
	v_lshl_add_u64 v[2:3], s[24:25], 0, v[128:129]
	global_load_lds_dwordx4 v128, s[24:25]
	s_mov_b64 s[54:55], 0x22000
	v_readfirstlane_b32 s24, v13
	s_mul_i32 s50, s75, 0x88000
	v_lshl_add_u64 v[4:5], v[2:3], 0, s[54:55]
	s_mov_b32 m0, s24
	s_add_u32 s50, s87, s50
	v_and_b32_e32 v0, 31, v6
	v_lshrrev_b32_e32 v1, 2, v6
	global_load_lds_dwordx4 v[4:5], off
	v_add_u32_e32 v4, 0x4000, v74
	s_addc_u32 s51, s96, 0
	v_and_or_b32 v12, v1, s7, v0
	v_lshlrev_b32_e32 v0, 7, v6
	v_readfirstlane_b32 s24, v4
	v_add_u32_e32 v13, 0x6000, v74
	v_and_b32_e32 v68, 0x6f80, v0
	v_lshl_add_u64 v[0:1], s[50:51], 0, v[128:129]
	s_mov_b32 m0, s24
	v_readfirstlane_b32 s24, v13
	global_load_lds_dwordx4 v128, s[50:51]
	v_lshl_add_u64 v[4:5], v[0:1], 0, s[54:55]
	s_mov_b32 m0, s24
	s_mov_b64 s[24:25], 0x44000
	v_add_u32_e32 v13, 0x8000, v74
	global_load_lds_dwordx4 v[4:5], off
	v_lshl_add_u64 v[4:5], v[0:1], 0, s[24:25]
	v_readfirstlane_b32 s24, v13
	s_mov_b32 m0, s24
	s_mov_b64 s[24:25], 0x66000
	v_add_u32_e32 v13, 0xa000, v74
	global_load_lds_dwordx4 v[4:5], off
	v_lshl_add_u64 v[4:5], v[0:1], 0, s[24:25]
	v_readfirstlane_b32 s24, v13
	v_lshlrev_b32_e32 v70, 7, v12
	v_add_u32_e32 v12, 0xc000, v74
	s_mov_b32 m0, s24
	v_readfirstlane_b32 s24, v12
	global_load_lds_dwordx4 v[4:5], off
	v_lshl_add_u64 v[4:5], v[2:3], 0, s[22:23]
	s_mov_b32 m0, s24
	s_mov_b64 s[50:51], 0x22080
	global_load_lds_dwordx4 v[4:5], off
	v_add_u32_e32 v4, 0xe000, v74
	v_lshl_add_u64 v[2:3], v[2:3], 0, s[50:51]
	v_readfirstlane_b32 s24, v4
	v_add_u32_e32 v4, s8, v10
	s_mov_b32 m0, s24
	v_readfirstlane_b32 s24, v4
	v_add_u32_e32 v4, s9, v10
	global_load_lds_dwordx4 v[2:3], off
	v_lshl_add_u64 v[2:3], v[0:1], 0, s[22:23]
	s_mov_b32 m0, s24
	v_readfirstlane_b32 s24, v4
	global_load_lds_dwordx4 v[2:3], off
	v_lshl_add_u64 v[2:3], v[0:1], 0, s[50:51]
	s_mov_b32 m0, s24
	s_mov_b64 s[24:25], 0x44080
	v_add_u32_e32 v4, s79, v10
	global_load_lds_dwordx4 v[2:3], off
	v_lshl_add_u64 v[2:3], v[0:1], 0, s[24:25]
	v_readfirstlane_b32 s24, v4
	s_mov_b32 m0, s24
	s_mov_b64 s[24:25], 0x66080
	global_load_lds_dwordx4 v[2:3], off
	v_add_u32_e32 v2, s10, v10
	v_lshl_add_u64 v[0:1], v[0:1], 0, s[24:25]
	v_readfirstlane_b32 s24, v2
	s_mov_b32 m0, s24
	v_lshrrev_b32_e32 v11, 1, v6
	global_load_lds_dwordx4 v[0:1], off
	v_bfe_u32 v13, v6, 5, 1
	v_bfe_u32 v0, v6, 1, 3
	v_bitop3_b32 v1, v13, v11, 7 bitop3:0x78
	v_lshlrev_b32_e32 v73, 4, v1
	v_bitop3_b32 v1, v13, v0, 2 bitop3:0x36
	v_lshlrev_b32_e32 v72, 4, v1
	v_bitop3_b32 v1, v13, v0, 4 bitop3:0x36
	v_bitop3_b32 v0, v13, v0, 6 bitop3:0x36
	s_lshl_b32 s24, s52, 7
	v_lshlrev_b32_e32 v69, 4, v0
	s_and_b32 s24, s24, 0xfffffc00
	v_lshrrev_b32_e32 v0, 3, v7
	s_or_b32 s3, s24, s3
	v_mul_lo_u32 v0, v0, s11
	v_readlane_b32 s52, v253, 1
	s_mul_hi_i32 s25, s3, 0x880
	s_mulk_i32 s3, 0x880
	v_mad_u32_u24 v0, v8, s6, v0
	v_readlane_b32 s66, v253, 15
	v_or_b32_e32 v0, v0, v9
	v_readlane_b32 s67, v253, 16
	s_add_u32 s24, s66, s3
	v_lshlrev_b32_e32 v128, 1, v0
	s_addc_u32 s25, s67, s25
	v_lshl_add_u64 v[64:65], s[24:25], 0, v[128:129]
	s_add_u32 s24, s84, s33
	v_readlane_b32 s53, v253, 2
	v_readlane_b32 s54, v253, 3
	v_readlane_b32 s55, v253, 4
	v_readlane_b32 s56, v253, 5
	v_readlane_b32 s57, v253, 6
	v_readlane_b32 s58, v253, 7
	v_readlane_b32 s59, v253, 8
	v_readlane_b32 s60, v253, 9
	v_readlane_b32 s61, v253, 10
	v_readlane_b32 s62, v253, 11
	v_readlane_b32 s63, v253, 12
	s_addc_u32 s25, s86, 0
	v_mov_b32_e32 v0, 0
	v_lshlrev_b32_e32 v71, 4, v1
	v_lshl_add_u64 v[66:67], s[24:25], 0, v[128:129]
	s_mov_b32 s3, 0
	s_mov_b64 s[50:51], 0
	v_mov_b32_e32 v1, v0
	v_mov_b32_e32 v2, v0
	v_mov_b32_e32 v3, v0
	v_mov_b32_e32 v4, v0
	v_mov_b32_e32 v5, v0
	v_mov_b32_e32 v6, v0
	v_mov_b32_e32 v7, v0
	v_mov_b32_e32 v8, v0
	v_mov_b32_e32 v9, v0
	v_mov_b32_e32 v10, v0
	v_mov_b32_e32 v11, v0
	v_mov_b32_e32 v12, v0
	v_mov_b32_e32 v13, v0
	v_mov_b32_e32 v14, v0
	v_mov_b32_e32 v15, v0
	v_mov_b32_e32 v16, v0
	v_mov_b32_e32 v17, v0
	v_mov_b32_e32 v18, v0
	v_mov_b32_e32 v19, v0
	v_mov_b32_e32 v20, v0
	v_mov_b32_e32 v21, v0
	v_mov_b32_e32 v22, v0
	v_mov_b32_e32 v23, v0
	v_mov_b32_e32 v24, v0
	v_mov_b32_e32 v25, v0
	v_mov_b32_e32 v26, v0
	v_mov_b32_e32 v27, v0
	v_mov_b32_e32 v28, v0
	v_mov_b32_e32 v29, v0
	v_mov_b32_e32 v30, v0
	v_mov_b32_e32 v31, v0
	v_mov_b32_e32 v32, v0
	v_mov_b32_e32 v33, v0
	v_mov_b32_e32 v34, v0
	v_mov_b32_e32 v35, v0
	v_mov_b32_e32 v36, v0
	v_mov_b32_e32 v37, v0
	v_mov_b32_e32 v38, v0
	v_mov_b32_e32 v39, v0
	v_mov_b32_e32 v40, v0
	v_mov_b32_e32 v41, v0
	v_mov_b32_e32 v42, v0
	v_mov_b32_e32 v43, v0
	v_mov_b32_e32 v44, v0
	v_mov_b32_e32 v45, v0
	v_mov_b32_e32 v46, v0
	v_mov_b32_e32 v47, v0
	v_mov_b32_e32 v48, v0
	v_mov_b32_e32 v49, v0
	v_mov_b32_e32 v50, v0
	v_mov_b32_e32 v51, v0
	v_mov_b32_e32 v52, v0
	v_mov_b32_e32 v53, v0
	v_mov_b32_e32 v54, v0
	v_mov_b32_e32 v55, v0
	v_mov_b32_e32 v56, v0
	v_mov_b32_e32 v57, v0
	v_mov_b32_e32 v58, v0
	v_mov_b32_e32 v59, v0
	v_mov_b32_e32 v60, v0
	v_mov_b32_e32 v61, v0
	v_mov_b32_e32 v62, v0
	v_mov_b32_e32 v63, v0
	s_mov_b64 s[52:53], 0x14e8100
	s_mov_b64 s[54:55], 0x7f88100
	s_mov_b64 s[56:57], 0x7f66100
	s_mov_b64 s[58:59], 0x150a100
	s_mov_b64 s[60:61], 0x154e100
	s_mov_b64 s[62:63], 0x152c100
	v_readlane_b32 s64, v253, 13
	v_readlane_b32 s65, v253, 14
	v_readfirstlane_b32 s25, v208
	s_nop 0
	s_lshr_b32 s25, s25, 8
	s_cmp_lg_u32 s25, 0
	s_cbranch_scc1 .Lstg723_top
; DI void wait_vm0() { asm volatile("s_waitcnt vmcnt(0)" ::: "memory"); }
; template <int MB, bool SWAP>
; DI void gemm_kloop(f32x16 (&acc)[MB][2], const h16* __restrict__ A, int lda, const h16* __restrict__ B, int ldb, int K, char* lds) {
;     ...
;   for (int kt = 0; kt < nk; ++kt) {
;     if (kt + 1 < nk) { if (MB == 2) asm volatile("s_waitcnt vmcnt(6)" ::: "memory"); else asm volatile("s_waitcnt vmcnt(5)" ::: "memory"); }
;     else wait_vm0();
;     __syncthreads();
;     const char* s = lds + cur * STAGE;
;     const int nbuf = cur == 0 ? 2 : cur - 1;
;     const bool more = kt + 2 < nk;
;     half8 af[2][MB], bf[2][2];
; #pragma unroll
;     for (int mb = 0; mb < MB; ++mb) af[0][mb] = *(const half8*)(s + a_rd + mb * 4096 + (((0 + hh) ^ sw) * 16));
; #pragma unroll
;     for (int nb = 0; nb < 2; ++nb) bf[0][nb] = *(const half8*)(s + b_rd + nb * 4096 + (((0 + hh) ^ sw) * 16));
; #pragma unroll
;     for (int ks = 0; ks < 4; ++ks) {
;       if (ks < 3) {
; #pragma unroll
;         for (int mb = 0; mb < MB; ++mb) af[(ks + 1) & 1][mb] = *(const half8*)(s + a_rd + mb * 4096 + (((2 * (ks + 1) + hh) ^ sw) * 16));
; #pragma unroll
;         for (int nb = 0; nb < 2; ++nb) bf[(ks + 1) & 1][nb] = *(const half8*)(s + b_rd + nb * 4096 + (((2 * (ks + 1) + hh) ^ sw) * 16));
;       }
;       if (more) {
;         if (2 * ks < NP) piece(2 * ks, kt + 2, nbuf);
;         if (2 * ks + 1 < NP) piece(2 * ks + 1, kt + 2, nbuf);
;       }
;       __builtin_amdgcn_sched_barrier(0);
;       __builtin_amdgcn_s_setprio(1);
; #pragma unroll
;       for (int mb = 0; mb < MB; ++mb)
; #pragma unroll
;         for (int nb = 0; nb < 2; ++nb)
;           acc[mb][nb] = SWAP ? __builtin_amdgcn_mfma_f32_32x32x16_f16(bf[ks & 1][nb], af[ks & 1][mb], acc[mb][nb], 0, 0, 0)
;                              : __builtin_amdgcn_mfma_f32_32x32x16_f16(af[ks & 1][mb], bf[ks & 1][nb], acc[mb][nb], 0, 0, 0);
;       __builtin_amdgcn_s_setprio(0);
;       __builtin_amdgcn_sched_barrier(0);
;     }
.LBB0_723:
	s_mul_i32 s24, s3, 0xc000
	s_add_i32 s25, s24, 0
	s_add_i32 s24, s24, 0xffff4000
	s_cmp_lg_u32 s3, 0
	s_cselect_b32 s24, s24, 0x18000
	v_add_u32_e32 v115, s24, v74
	v_add_u32_e32 v75, s25, v70
	v_add_u32_e32 v114, s25, v68
	v_add_u32_e32 v112, 0x2000, v115
	v_lshl_add_u64 v[108:109], v[64:65], 0, s[50:51]
	v_readfirstlane_b32 s24, v115
	v_add_u32_e32 v80, v75, v73
	v_add_u32_e32 v88, v114, v73
	v_add_u32_e32 v96, v75, v72
	v_add_u32_e32 v104, v114, v72
	v_lshl_add_u64 v[110:111], v[108:109], 0, s[54:55]
	v_lshl_add_u64 v[108:109], v[108:109], 0, s[56:57]
	s_mov_b32 m0, s24
	v_readfirstlane_b32 s24, v112
	s_waitcnt vmcnt(6)
	s_waitcnt lgkmcnt(0)
	s_barrier
	ds_read_b128 v[76:79], v80
	ds_read_b128 v[80:83], v80 offset:4096
	ds_read_b128 v[84:87], v88 offset:16384
	ds_read_b128 v[88:91], v88 offset:20480
	ds_read_b128 v[92:95], v96
	ds_read_b128 v[96:99], v96 offset:4096
	ds_read_b128 v[100:103], v104 offset:16384
	ds_read_b128 v[104:107], v104 offset:20480
	global_load_lds_dwordx4 v[108:109], off
	s_mov_b32 m0, s24
	v_lshl_add_u64 v[108:109], v[66:67], 0, s[50:51]
	global_load_lds_dwordx4 v[110:111], off
	v_lshl_add_u64 v[110:111], v[108:109], 0, s[52:53]
	s_setprio 1
	s_waitcnt lgkmcnt(0)
	v_mfma_f32_32x32x16_f16 v[48:63], v[84:87], v[76:79], v[48:63]
	v_mfma_f32_32x32x16_f16 v[32:47], v[88:91], v[76:79], v[32:47]
	v_mfma_f32_32x32x16_f16 v[16:31], v[84:87], v[80:83], v[16:31]
	v_mfma_f32_32x32x16_f16 v[0:15], v[88:91], v[80:83], v[0:15]
	s_setprio 0
	v_add_u32_e32 v117, 0x4000, v115
	v_add_u32_e32 v116, 0x6000, v115
	v_readfirstlane_b32 s24, v117
	v_add_u32_e32 v80, v75, v71
	v_add_u32_e32 v88, v114, v71
	s_mov_b32 m0, s24
	v_readfirstlane_b32 s24, v116
	ds_read_b128 v[76:79], v80
	ds_read_b128 v[80:83], v80 offset:4096
	ds_read_b128 v[84:87], v88 offset:16384
	ds_read_b128 v[88:91], v88 offset:20480
	v_lshl_add_u64 v[112:113], v[108:109], 0, s[58:59]
	global_load_lds_dwordx4 v[110:111], off
	s_mov_b32 m0, s24
	s_nop 0
	global_load_lds_dwordx4 v[112:113], off
	s_setprio 1
	v_mfma_f32_32x32x16_f16 v[48:63], v[100:103], v[92:95], v[48:63]
	v_mfma_f32_32x32x16_f16 v[32:47], v[104:107], v[92:95], v[32:47]
	v_mfma_f32_32x32x16_f16 v[16:31], v[100:103], v[96:99], v[16:31]
	v_mfma_f32_32x32x16_f16 v[0:15], v[104:107], v[96:99], v[0:15]
	s_setprio 0
	v_add_u32_e32 v75, v75, v69
	ds_read_b128 v[92:95], v75
	ds_read_b128 v[96:99], v75 offset:4096
	v_add_u32_e32 v75, v114, v69
	v_add_u32_e32 v112, 0x8000, v115
	ds_read_b128 v[100:103], v75 offset:16384
	ds_read_b128 v[104:107], v75 offset:20480
	v_add_u32_e32 v75, 0xa000, v115
	v_readfirstlane_b32 s24, v112
	v_lshl_add_u64 v[110:111], v[108:109], 0, s[60:61]
	v_lshl_add_u64 v[108:109], v[108:109], 0, s[62:63]
	s_mov_b32 m0, s24
	v_readfirstlane_b32 s24, v75
	global_load_lds_dwordx4 v[108:109], off
	s_mov_b32 m0, s24
	s_nop 0
	global_load_lds_dwordx4 v[110:111], off
	s_setprio 1
	s_waitcnt lgkmcnt(0)
	v_mfma_f32_32x32x16_f16 v[48:63], v[84:87], v[76:79], v[48:63]
	v_mfma_f32_32x32x16_f16 v[32:47], v[88:91], v[76:79], v[32:47]
	v_mfma_f32_32x32x16_f16 v[16:31], v[84:87], v[80:83], v[16:31]
	v_mfma_f32_32x32x16_f16 v[0:15], v[88:91], v[80:83], v[0:15]
	s_setprio 0
	s_setprio 1
	v_mfma_f32_32x32x16_f16 v[48:63], v[100:103], v[92:95], v[48:63]
	v_mfma_f32_32x32x16_f16 v[32:47], v[104:107], v[92:95], v[32:47]
	v_mfma_f32_32x32x16_f16 v[16:31], v[100:103], v[96:99], v[16:31]
	v_mfma_f32_32x32x16_f16 v[0:15], v[104:107], v[96:99], v[0:15]
	s_setprio 0
	s_add_i32 s24, s3, 1
	s_cmp_lg_u32 s3, 2
	s_cselect_b32 s3, s24, 0
	s_add_u32 s50, s50, 0x80
	s_addc_u32 s51, s51, 0
	s_cmpk_eq_i32 s50, 0x700
	s_cbranch_scc0 .LBB0_723
	s_branch .Lstg723_join
.Lstg723_top:
	s_mul_i32 s24, s3, 0xc000
	s_add_i32 s25, s24, 0
	s_add_i32 s24, s24, 0xffff4000
	s_cmp_lg_u32 s3, 0
	s_cselect_b32 s24, s24, 0x18000
	v_add_u32_e32 v115, s24, v74
	v_add_u32_e32 v75, s25, v70
	v_add_u32_e32 v114, s25, v68
	v_add_u32_e32 v112, 0x2000, v115
	v_lshl_add_u64 v[108:109], v[64:65], 0, s[50:51]
	v_readfirstlane_b32 s24, v115
	v_lshl_add_u64 v[110:111], v[108:109], 0, s[54:55]
	v_lshl_add_u64 v[108:109], v[108:109], 0, s[56:57]
	s_mov_b32 m0, s24
	v_readfirstlane_b32 s24, v112
	s_waitcnt vmcnt(6)
	s_waitcnt lgkmcnt(0)
	s_barrier
	s_cmp_eq_u32 s50, 0
	s_cbranch_scc1 .Lstg723_skip
	s_setprio 1
	v_mfma_f32_32x32x16_f16 v[48:63], v[84:87], v[76:79], v[48:63]
	v_mfma_f32_32x32x16_f16 v[32:47], v[88:91], v[76:79], v[32:47]
	v_mfma_f32_32x32x16_f16 v[16:31], v[84:87], v[80:83], v[16:31]
	v_mfma_f32_32x32x16_f16 v[0:15], v[88:91], v[80:83], v[0:15]
	v_mfma_f32_32x32x16_f16 v[48:63], v[100:103], v[92:95], v[48:63]
	v_mfma_f32_32x32x16_f16 v[32:47], v[104:107], v[92:95], v[32:47]
	v_mfma_f32_32x32x16_f16 v[16:31], v[100:103], v[96:99], v[16:31]
	v_mfma_f32_32x32x16_f16 v[0:15], v[104:107], v[96:99], v[0:15]
	s_setprio 0
; DI void wait_vm0() { asm volatile("s_waitcnt vmcnt(0)" ::: "memory"); }
; template <int MB, bool SWAP>
; DI void gemm_kloop(f32x16 (&acc)[MB][2], const h16* __restrict__ A, int lda, const h16* __restrict__ B, int ldb, int K, char* lds) {
;     ...
;   for (int kt = 0; kt < nk; ++kt) {
;     if (kt + 1 < nk) { if (MB == 2) asm volatile("s_waitcnt vmcnt(6)" ::: "memory"); else asm volatile("s_waitcnt vmcnt(5)" ::: "memory"); }
;     else wait_vm0();
;     __syncthreads();
;     const char* s = lds + cur * STAGE;
;     const int nbuf = cur == 0 ? 2 : cur - 1;
;     const bool more = kt + 2 < nk;
;     half8 af[2][MB], bf[2][2];
; #pragma unroll
;     for (int mb = 0; mb < MB; ++mb) af[0][mb] = *(const half8*)(s + a_rd + mb * 4096 + (((0 + hh) ^ sw) * 16));
; #pragma unroll
;     for (int nb = 0; nb < 2; ++nb) bf[0][nb] = *(const half8*)(s + b_rd + nb * 4096 + (((0 + hh) ^ sw) * 16));
; #pragma unroll
;     for (int ks = 0; ks < 4; ++ks) {
;       if (ks < 3) {
; #pragma unroll
;         for (int mb = 0; mb < MB; ++mb) af[(ks + 1) & 1][mb] = *(const half8*)(s + a_rd + mb * 4096 + (((2 * (ks + 1) + hh) ^ sw) * 16));
; #pragma unroll
;         for (int nb = 0; nb < 2; ++nb) bf[(ks + 1) & 1][nb] = *(const half8*)(s + b_rd + nb * 4096 + (((2 * (ks + 1) + hh) ^ sw) * 16));
;       }
;       if (more) {
;         if (2 * ks < NP) piece(2 * ks, kt + 2, nbuf);
;         if (2 * ks + 1 < NP) piece(2 * ks + 1, kt + 2, nbuf);
;       }
;       __builtin_amdgcn_sched_barrier(0);
;       __builtin_amdgcn_s_setprio(1);
; #pragma unroll
;       for (int mb = 0; mb < MB; ++mb)
; #pragma unroll
;         for (int nb = 0; nb < 2; ++nb)
;           acc[mb][nb] = SWAP ? __builtin_amdgcn_mfma_f32_32x32x16_f16(bf[ks & 1][nb], af[ks & 1][mb], acc[mb][nb], 0, 0, 0)
;                              : __builtin_amdgcn_mfma_f32_32x32x16_f16(af[ks & 1][mb], bf[ks & 1][nb], acc[mb][nb], 0, 0, 0);
;       __builtin_amdgcn_s_setprio(0);
;       __builtin_amdgcn_sched_barrier(0);
;     }
.Lstg723_skip:
	v_add_u32_e32 v80, v75, v73
	v_add_u32_e32 v88, v114, v73
	v_add_u32_e32 v96, v75, v72
	v_add_u32_e32 v104, v114, v72
	ds_read_b128 v[76:79], v80
	ds_read_b128 v[80:83], v80 offset:4096
	ds_read_b128 v[84:87], v88 offset:16384
	ds_read_b128 v[88:91], v88 offset:20480
	ds_read_b128 v[92:95], v96
	ds_read_b128 v[96:99], v96 offset:4096
	ds_read_b128 v[100:103], v104 offset:16384
	ds_read_b128 v[104:107], v104 offset:20480
	global_load_lds_dwordx4 v[108:109], off
	s_mov_b32 m0, s24
	v_lshl_add_u64 v[108:109], v[66:67], 0, s[50:51]
	global_load_lds_dwordx4 v[110:111], off
	v_lshl_add_u64 v[110:111], v[108:109], 0, s[52:53]
	s_setprio 1
	s_waitcnt lgkmcnt(0)
	v_mfma_f32_32x32x16_f16 v[48:63], v[84:87], v[76:79], v[48:63]
	v_mfma_f32_32x32x16_f16 v[32:47], v[88:91], v[76:79], v[32:47]
	v_mfma_f32_32x32x16_f16 v[16:31], v[84:87], v[80:83], v[16:31]
	v_mfma_f32_32x32x16_f16 v[0:15], v[88:91], v[80:83], v[0:15]
	s_setprio 0
	v_add_u32_e32 v117, 0x4000, v115
	v_add_u32_e32 v116, 0x6000, v115
	v_readfirstlane_b32 s24, v117
	v_add_u32_e32 v80, v75, v71
	v_add_u32_e32 v88, v114, v71
	s_mov_b32 m0, s24
	v_readfirstlane_b32 s24, v116
	ds_read_b128 v[76:79], v80
	ds_read_b128 v[80:83], v80 offset:4096
	ds_read_b128 v[84:87], v88 offset:16384
	ds_read_b128 v[88:91], v88 offset:20480
	v_lshl_add_u64 v[112:113], v[108:109], 0, s[58:59]
	global_load_lds_dwordx4 v[110:111], off
	s_mov_b32 m0, s24
	s_nop 0
	global_load_lds_dwordx4 v[112:113], off
	s_setprio 1
	v_mfma_f32_32x32x16_f16 v[48:63], v[100:103], v[92:95], v[48:63]
	v_mfma_f32_32x32x16_f16 v[32:47], v[104:107], v[92:95], v[32:47]
	v_mfma_f32_32x32x16_f16 v[16:31], v[100:103], v[96:99], v[16:31]
	v_mfma_f32_32x32x16_f16 v[0:15], v[104:107], v[96:99], v[0:15]
	s_setprio 0
	v_add_u32_e32 v75, v75, v69
	ds_read_b128 v[92:95], v75
	ds_read_b128 v[96:99], v75 offset:4096
	v_add_u32_e32 v75, v114, v69
	v_add_u32_e32 v112, 0x8000, v115
	ds_read_b128 v[100:103], v75 offset:16384
	ds_read_b128 v[104:107], v75 offset:20480
	v_add_u32_e32 v75, 0xa000, v115
	v_readfirstlane_b32 s24, v112
	v_lshl_add_u64 v[110:111], v[108:109], 0, s[60:61]
	v_lshl_add_u64 v[108:109], v[108:109], 0, s[62:63]
	s_mov_b32 m0, s24
	v_readfirstlane_b32 s24, v75
	global_load_lds_dwordx4 v[108:109], off
	s_mov_b32 m0, s24
	s_nop 0
	global_load_lds_dwordx4 v[110:111], off
	s_add_i32 s24, s3, 1
	s_cmp_lg_u32 s3, 2
	s_cselect_b32 s3, s24, 0
	s_add_u32 s50, s50, 0x80
	s_addc_u32 s51, s51, 0
	s_cmpk_eq_i32 s50, 0x700
	s_cbranch_scc0 .Lstg723_top
	s_waitcnt lgkmcnt(0)
	s_setprio 1
	v_mfma_f32_32x32x16_f16 v[48:63], v[84:87], v[76:79], v[48:63]
	v_mfma_f32_32x32x16_f16 v[32:47], v[88:91], v[76:79], v[32:47]
	v_mfma_f32_32x32x16_f16 v[16:31], v[84:87], v[80:83], v[16:31]
	v_mfma_f32_32x32x16_f16 v[0:15], v[88:91], v[80:83], v[0:15]
	v_mfma_f32_32x32x16_f16 v[48:63], v[100:103], v[92:95], v[48:63]
	v_mfma_f32_32x32x16_f16 v[32:47], v[104:107], v[92:95], v[32:47]
	v_mfma_f32_32x32x16_f16 v[16:31], v[100:103], v[96:99], v[16:31]
	v_mfma_f32_32x32x16_f16 v[0:15], v[104:107], v[96:99], v[0:15]
	s_setprio 0
; DI int otid() { int t = threadIdx.x; asm volatile("" : "+v"(t)); return t; }
; template <int MB, bool SWAP>
; DI void gemm_kloop(f32x16 (&acc)[MB][2], const h16* __restrict__ A, int lda, const h16* __restrict__ B, int ldb, int K, char* lds) {
;     ...
;     for (int mb = 0; mb < MB; ++mb) af[0][mb] = *(const half8*)(s + a_rd + mb * 4096 + (((0 + hh) ^ sw) * 16));
; #pragma unroll
;     for (int nb = 0; nb < 2; ++nb) bf[0][nb] = *(const half8*)(s + b_rd + nb * 4096 + (((0 + hh) ^ sw) * 16));
; #pragma unroll
;     for (int ks = 0; ks < 4; ++ks) {
;       if (ks < 3) {
; #pragma unroll
;         for (int mb = 0; mb < MB; ++mb) af[(ks + 1) & 1][mb] = *(const half8*)(s + a_rd + mb * 4096 + (((2 * (ks + 1) + hh) ^ sw) * 16));
; #pragma unroll
;         for (int nb = 0; nb < 2; ++nb) bf[(ks + 1) & 1][nb] = *(const half8*)(s + b_rd + nb * 4096 + (((2 * (ks + 1) + hh) ^ sw) * 16));
;       }
;       if (more) {
;         if (2 * ks < NP) piece(2 * ks, kt + 2, nbuf);
;         if (2 * ks + 1 < NP) piece(2 * ks + 1, kt + 2, nbuf);
;       }
;       __builtin_amdgcn_sched_barrier(0);
;       __builtin_amdgcn_s_setprio(1);
; #pragma unroll
;       for (int mb = 0; mb < MB; ++mb)
; #pragma unroll
;         for (int nb = 0; nb < 2; ++nb)
;           acc[mb][nb] = SWAP ? __builtin_amdgcn_mfma_f32_32x32x16_f16(bf[ks & 1][nb], af[ks & 1][mb], acc[mb][nb], 0, 0, 0)
;                              : __builtin_amdgcn_mfma_f32_32x32x16_f16(af[ks & 1][mb], bf[ks & 1][nb], acc[mb][nb], 0, 0, 0);
;       __builtin_amdgcn_s_setprio(0);
;       __builtin_amdgcn_sched_barrier(0);
;     }
;     cur = cur == 2 ? 0 : cur + 1;
;   }
;   __syncthreads();
; template <int MB>
; DI void out_tile(const Params& P, int layer, int row0, int nt, char* smem) {
;     ...
;   const int tid = otid(), lane = tid & 63, w = tid >> 6, wr = w >> 2, wc = w & 3, r32 = lane & 31, hh = lane >> 5;
; #pragma unroll
;   for (int mb = 0; mb < MB; ++mb) {
;     const int row = row0 + wr * 32 * MB + mb * 32 + r32;
;     const float* src; float* dst; int b;
;     if (row < T_LAT) { b = row >> 11; src = (layer == 0 ? P.x : P.out) + (size_t)row * D; dst = P.out + (size_t)row * D; }
;     else { const int rc = row - T_LAT; b = 16; src = (layer == 0 ? P.ctx : ctxw) + (size_t)rc * D; dst = ctxw + (size_t)rc * D; }
.Lstg723_join:
	s_add_i32 s3, 0, 0x18000
	v_add_u32_e32 v102, s3, v70
	v_add_u32_e32 v74, v102, v73
	v_add3_u32 v82, s3, v73, v68
	v_add_u32_e32 v90, v102, v72
	v_add3_u32 v98, s3, v72, v68
	s_waitcnt vmcnt(6)
	s_waitcnt lgkmcnt(0)
	s_barrier
	ds_read_b128 v[64:67], v74
	ds_read_b128 v[74:77], v74 offset:4096
	ds_read_b128 v[78:81], v82 offset:16384
	ds_read_b128 v[82:85], v82 offset:20480
	ds_read_b128 v[86:89], v90
	ds_read_b128 v[90:93], v90 offset:4096
	ds_read_b128 v[94:97], v98 offset:16384
	ds_read_b128 v[98:101], v98 offset:20480
	s_setprio 1
	s_waitcnt lgkmcnt(5)
	v_mfma_f32_32x32x16_f16 v[48:63], v[78:81], v[64:67], v[48:63]
	s_waitcnt lgkmcnt(4)
	v_mfma_f32_32x32x16_f16 v[32:47], v[82:85], v[64:67], v[32:47]
	v_mfma_f32_32x32x16_f16 v[16:31], v[78:81], v[74:77], v[16:31]
	v_mfma_f32_32x32x16_f16 v[0:15], v[82:85], v[74:77], v[0:15]
	s_setprio 0
	v_add_u32_e32 v74, v102, v71
	v_add3_u32 v82, s3, v71, v68
	ds_read_b128 v[64:67], v74
	ds_read_b128 v[74:77], v74 offset:4096
	ds_read_b128 v[78:81], v82 offset:16384
	ds_read_b128 v[82:85], v82 offset:20480
	s_setprio 1
	s_waitcnt lgkmcnt(5)
	v_mfma_f32_32x32x16_f16 v[48:63], v[94:97], v[86:89], v[48:63]
	s_waitcnt lgkmcnt(4)
	v_mfma_f32_32x32x16_f16 v[32:47], v[98:101], v[86:89], v[32:47]
	v_mfma_f32_32x32x16_f16 v[16:31], v[94:97], v[90:93], v[16:31]
	v_mfma_f32_32x32x16_f16 v[0:15], v[98:101], v[90:93], v[0:15]
	s_setprio 0
	v_add_u32_e32 v90, v102, v69
	v_add3_u32 v98, s3, v69, v68
	ds_read_b128 v[86:89], v90
	ds_read_b128 v[90:93], v90 offset:4096
	ds_read_b128 v[94:97], v98 offset:16384
	ds_read_b128 v[98:101], v98 offset:20480
	s_setprio 1
	s_waitcnt lgkmcnt(5)
	v_mfma_f32_32x32x16_f16 v[48:63], v[78:81], v[64:67], v[48:63]
	s_waitcnt lgkmcnt(4)
	v_mfma_f32_32x32x16_f16 v[32:47], v[82:85], v[64:67], v[32:47]
	v_mfma_f32_32x32x16_f16 v[16:31], v[78:81], v[74:77], v[16:31]
	v_mfma_f32_32x32x16_f16 v[0:15], v[82:85], v[74:77], v[0:15]
	s_setprio 0
	s_setprio 1
	s_waitcnt lgkmcnt(1)
	v_mfma_f32_32x32x16_f16 v[48:63], v[94:97], v[86:89], v[48:63]
	s_waitcnt lgkmcnt(0)
	v_mfma_f32_32x32x16_f16 v[32:47], v[98:101], v[86:89], v[32:47]
	v_mfma_f32_32x32x16_f16 v[16:31], v[94:97], v[90:93], v[16:31]
	v_mfma_f32_32x32x16_f16 v[0:15], v[98:101], v[90:93], v[0:15]
	s_setprio 0
	v_add_u32_e32 v70, 0, v70
	v_add_u32_e32 v68, 0, v68
	v_add_u32_e32 v74, v70, v73
	v_add_u32_e32 v73, v68, v73
	s_waitcnt vmcnt(0)
	s_barrier
	ds_read_b128 v[64:67], v74
	ds_read_b128 v[74:77], v74 offset:4096
	ds_read_b128 v[78:81], v73 offset:16384
	ds_read_b128 v[82:85], v73 offset:20480
	v_add_u32_e32 v73, v70, v72
	v_add_u32_e32 v72, v68, v72
	ds_read_b128 v[86:89], v73
	ds_read_b128 v[90:93], v73 offset:4096
	ds_read_b128 v[94:97], v72 offset:16384
	ds_read_b128 v[98:101], v72 offset:20480
	s_setprio 1
	s_waitcnt lgkmcnt(5)
	v_mfma_f32_32x32x16_f16 v[48:63], v[78:81], v[64:67], v[48:63]
	s_waitcnt lgkmcnt(4)
	v_mfma_f32_32x32x16_f16 v[32:47], v[82:85], v[64:67], v[32:47]
	v_mfma_f32_32x32x16_f16 v[16:31], v[78:81], v[74:77], v[16:31]
	v_mfma_f32_32x32x16_f16 v[0:15], v[82:85], v[74:77], v[0:15]
	s_setprio 0
	v_add_u32_e32 v72, v70, v71
	v_add_u32_e32 v71, v68, v71
	ds_read_b128 v[64:67], v72
	ds_read_b128 v[72:75], v72 offset:4096
	ds_read_b128 v[76:79], v71 offset:16384
	ds_read_b128 v[80:83], v71 offset:20480
	s_setprio 1
	s_waitcnt lgkmcnt(5)
	v_mfma_f32_32x32x16_f16 v[48:63], v[94:97], v[86:89], v[48:63]
	s_waitcnt lgkmcnt(4)
	v_mfma_f32_32x32x16_f16 v[32:47], v[98:101], v[86:89], v[32:47]
	v_mfma_f32_32x32x16_f16 v[16:31], v[94:97], v[90:93], v[16:31]
	v_mfma_f32_32x32x16_f16 v[0:15], v[98:101], v[90:93], v[0:15]
	s_setprio 0
	v_add_u32_e32 v70, v70, v69
	v_add_u32_e32 v92, v68, v69
	ds_read_b128 v[84:87], v70
	ds_read_b128 v[88:91], v70 offset:4096
	ds_read_b128 v[68:71], v92 offset:16384
	ds_read_b128 v[92:95], v92 offset:20480
	s_setprio 1
	s_waitcnt lgkmcnt(5)
	v_mfma_f32_32x32x16_f16 v[48:63], v[76:79], v[64:67], v[48:63]
	s_waitcnt lgkmcnt(4)
	v_mfma_f32_32x32x16_f16 v[32:47], v[80:83], v[64:67], v[32:47]
	v_mfma_f32_32x32x16_f16 v[16:31], v[76:79], v[72:75], v[16:31]
	v_mfma_f32_32x32x16_f16 v[0:15], v[80:83], v[72:75], v[0:15]
	s_setprio 0
	s_setprio 1
	s_waitcnt lgkmcnt(1)
	v_mfma_f32_32x32x16_f16 v[48:63], v[68:71], v[84:87], v[48:63]
	s_waitcnt lgkmcnt(0)
	v_mfma_f32_32x32x16_f16 v[32:47], v[92:95], v[84:87], v[32:47]
	v_mfma_f32_32x32x16_f16 v[16:31], v[68:71], v[88:91], v[16:31]
	v_mfma_f32_32x32x16_f16 v[0:15], v[92:95], v[88:91], v[0:15]
	s_setprio 0
	v_mov_b32_e32 v70, v208
	s_barrier
	s_nop 0
	v_ashrrev_i32_e32 v64, 2, v70
	v_and_b32_e32 v64, 0xffffffc0, v64
	v_and_or_b32 v65, v70, 31, s2
	v_add_u32_e32 v64, v65, v64
	s_movk_i32 s2, 0x7fff
	v_cmp_lt_i32_e32 vcc, s2, v64
	s_and_saveexec_b64 s[2:3], vcc
	s_xor_b64 s[2:3], exec, s[2:3]
	s_cbranch_execz .LBB0_726
	v_readlane_b32 s48, v253, 1
	v_add_u32_e32 v128, 0xffff8000, v64
	v_readlane_b32 s49, v253, 2
	v_lshlrev_b64 v[68:69], 12, v[128:129]
	v_readlane_b32 s62, v253, 15
	v_readlane_b32 s63, v253, 16
	v_readlane_b32 s48, v255, 30
	v_lshl_add_u64 v[66:67], s[42:43], 0, v[68:69]
	v_readlane_b32 s50, v253, 3
	v_readlane_b32 s51, v253, 4
	v_readlane_b32 s52, v253, 5
	v_readlane_b32 s53, v253, 6
	v_readlane_b32 s54, v253, 7
	v_readlane_b32 s55, v253, 8
	v_readlane_b32 s56, v253, 9
	v_readlane_b32 s57, v253, 10
	v_readlane_b32 s58, v253, 11
	v_readlane_b32 s59, v253, 12
	v_readlane_b32 s60, v253, 13
	v_readlane_b32 s61, v253, 14
	v_readlane_b32 s49, v255, 31
	v_lshl_add_u64 v[72:73], s[62:63], 0, v[68:69]
